# A-tile LDS-DMA loads with sc1 (bypass the CU L1 so the B lines shared by the co-resident block stay longer)
# speedup vs baseline: 1.0057x; 1.0026x over previous
; __device__ __forceinline__ int tidx() { int t = threadIdx.x; asm volatile("" : "+v"(t)); return t; }
; template <int NT>
; __device__ __forceinline__ void gemm_tile(f32x4 (&acc)[4][NT], const bf16_t* A, int lda, const bf16_t* B, int ldb, int K, bf16_t* sm) {
;     const int tid_ = tidx();
;     bf16_t* sA = sm; bf16_t* sB = sm + 128 * LDT;
;     const int tid = tid_, lane = tid & 63, wid = tid >> 6, wr = wid >> 1, wc = wid & 1;
;     const int fr = lane & 15, fq = lane >> 4;
;     const int lrow = tid >> 3, lkc = tid & 7;
;     const bf16_t* ga = A + (size_t)lrow * lda + lkc * 8;
;     const bf16_t* gb = B + (size_t)lrow * ldb + lkc * 8;
;     int sbrow[NT];
; #pragma unroll
;     for (int i = 0; i < NT; ++i) { const int g = lrow + 32 * i, W_ = 16 * NT, rem = g % W_; sbrow[i] = (g / W_) * W_ + (rem % NT) * 16 + rem / NT; }
;     u32x4 ra0[4], rb0[NT];
; #pragma unroll
;     for (int i = 0; i < 4; ++i) ra0[i] = *(const u32x4*)(ga + (size_t)(32 * i) * lda);
; #pragma unroll
;     for (int i = 0; i < NT; ++i) rb0[i] = *(const u32x4*)(gb + (size_t)(32 * i) * ldb);
; template <int NT>
; __device__ __forceinline__ void resid_tile(int tm, int col0, const bf16_t* A, int lda, int K, const bf16_t* W, const float* X, float* Y, float scale, bf16_t* sm) {
;     const int tid_ = tidx();
;     const int lane = tid_ & 63, wid = tid_ >> 6, wr = wid >> 1, wc = wid & 1, fr = lane & 15, fq = lane >> 4;
;     f32x4 acc[4][NT]; zero_acc<NT>(acc);
;     gemm_tile<NT>(acc, A + (size_t)tm * 128 * lda, lda, W + (size_t)col0 * K, K, K, sm);
.LBB0_35:
	v_mov_b32_e32 v118, v192
	v_mov_b32_e32 v36, v192
	s_and_b32 s18, s39, 7
	s_lshl_b32 s18, s18, 3
	s_bfe_u32 s19, s39, 0x30006
	s_or_b32 s18, s18, s19
	s_ashr_i32 s19, s39, 9
	s_lshl_b32 s19, s19, 6
	s_or_b32 s18, s18, s19
	v_ashrrev_i32_e32 v0, 31, v36
	v_ashrrev_i32_e32 v34, 3, v36
	v_lshrrev_b32_e32 v0, 26, v0
	v_add_u32_e32 v0, v34, v0
	v_lshrrev_b32_e32 v1, 6, v0
	v_mul_i32_i24_e32 v1, 64, v1
	v_sub_u32_e32 v1, v34, v1
	v_lshrrev_b16_sdwa v2, v196, sext(v1) dst_sel:DWORD dst_unused:UNUSED_PAD src0_sel:DWORD src1_sel:BYTE_0
	v_and_b32_e32 v2, 3, v2
	v_add_u16_e32 v2, v1, v2
	v_ashrrev_i16_sdwa v3, v197, sext(v2) dst_sel:DWORD dst_unused:UNUSED_PAD src0_sel:DWORD src1_sel:BYTE_0
	v_and_b32_e32 v2, 0xfc, v2
	v_sub_u16_e32 v1, v1, v2
	v_and_b32_e32 v0, 0x7ffffc0, v0
	v_lshlrev_b32_sdwa v1, v198, sext(v1) dst_sel:DWORD dst_unused:UNUSED_PAD src0_sel:DWORD src1_sel:BYTE_0
	v_bfe_i32 v2, v3, 0, 16
	v_add3_u32 v37, v0, v2, v1
	v_add_u32_e32 v0, 32, v34
	v_ashrrev_i32_e32 v1, 31, v0
	v_lshrrev_b32_e32 v1, 26, v1
	v_add_u32_e32 v1, v0, v1
	v_lshrrev_b32_e32 v2, 6, v1
	v_mul_i32_i24_e32 v2, 64, v2
	v_sub_u32_e32 v0, v0, v2
	v_lshrrev_b16_sdwa v2, v196, sext(v0) dst_sel:DWORD dst_unused:UNUSED_PAD src0_sel:DWORD src1_sel:BYTE_0
	v_and_b32_e32 v2, 3, v2
	v_add_u16_e32 v2, v0, v2
	v_ashrrev_i16_sdwa v3, v197, sext(v2) dst_sel:DWORD dst_unused:UNUSED_PAD src0_sel:DWORD src1_sel:BYTE_0
	v_and_b32_e32 v2, 0xfc, v2
	v_sub_u16_e32 v0, v0, v2
	v_and_b32_e32 v1, 0x7ffffc0, v1
	v_lshlrev_b32_sdwa v0, v198, sext(v0) dst_sel:DWORD dst_unused:UNUSED_PAD src0_sel:DWORD src1_sel:BYTE_0
	v_bfe_i32 v2, v3, 0, 16
	v_add3_u32 v38, v1, v2, v0
	v_add_u32_e32 v0, 64, v34
	v_ashrrev_i32_e32 v1, 31, v0
	v_lshrrev_b32_e32 v1, 26, v1
	v_add_u32_e32 v1, v0, v1
	v_lshrrev_b32_e32 v2, 6, v1
	v_mul_i32_i24_e32 v2, 64, v2
	v_sub_u32_e32 v0, v0, v2
	v_lshrrev_b16_sdwa v2, v196, sext(v0) dst_sel:DWORD dst_unused:UNUSED_PAD src0_sel:DWORD src1_sel:BYTE_0
	v_and_b32_e32 v2, 3, v2
	v_add_u16_e32 v2, v0, v2
	v_ashrrev_i16_sdwa v3, v197, sext(v2) dst_sel:DWORD dst_unused:UNUSED_PAD src0_sel:DWORD src1_sel:BYTE_0
	v_and_b32_e32 v2, 0xfc, v2
	v_sub_u16_e32 v0, v0, v2
	v_and_b32_e32 v1, 0x7ffffc0, v1
	v_lshlrev_b32_sdwa v0, v198, sext(v0) dst_sel:DWORD dst_unused:UNUSED_PAD src0_sel:DWORD src1_sel:BYTE_0
	v_bfe_i32 v2, v3, 0, 16
	v_add3_u32 v39, v1, v2, v0
	v_add_u32_e32 v0, 0x60, v34
	v_ashrrev_i32_e32 v1, 31, v0
	v_lshrrev_b32_e32 v1, 26, v1
	v_add_u32_e32 v1, v0, v1
	v_lshrrev_b32_e32 v2, 6, v1
	v_mul_i32_i24_e32 v2, 64, v2
	v_sub_u32_e32 v0, v0, v2
	s_ashr_i32 s19, s18, 31
	v_lshrrev_b16_sdwa v2, v196, sext(v0) dst_sel:DWORD dst_unused:UNUSED_PAD src0_sel:DWORD src1_sel:BYTE_0
	s_lshl_b32 s2, s39, 4
	s_lshl_b64 s[76:77], s[18:19], s97
	v_and_b32_e32 v2, 3, v2
	s_and_b32 s2, s2, 0x380
	s_lshl_b64 s[78:79], s[76:77], 1
	v_add_u16_e32 v2, v0, v2
	s_add_u32 s84, s12, s78
	v_ashrrev_i16_sdwa v3, v197, sext(v2) dst_sel:DWORD dst_unused:UNUSED_PAD src0_sel:DWORD src1_sel:BYTE_0
	v_and_b32_e32 v2, 0xfc, v2
	s_addc_u32 s85, s11, s79
	s_lshl_b32 s19, s2, vcc_lo
	v_sub_u16_e32 v0, v0, v2
	s_lshl_b32 s19, s19, 1
	v_and_b32_e32 v1, 0x7ffffc0, v1
	v_lshlrev_b32_sdwa v0, v198, sext(v0) dst_sel:DWORD dst_unused:UNUSED_PAD src0_sel:DWORD src1_sel:BYTE_0
	v_bfe_i32 v2, v3, 0, 16
	v_ashrrev_i32_e32 v35, 31, v34
	s_add_u32 s76, s13, s19
	v_add3_u32 v40, v1, v2, v0
	v_lshlrev_b64 v[0:1], vcc_lo, v[34:35]
	s_addc_u32 s77, s94, 0
	v_lshlrev_b64 v[100:101], 1, v[0:1]
	v_lshlrev_b32_e32 v2, 4, v36
	v_lshl_add_u64 v[0:1], s[76:77], 0, v[100:101]
	v_and_b32_e32 v12, 0x70, v2
	v_lshl_add_u64 v[18:19], s[84:85], 0, v[100:101]
	v_lshl_add_u64 v[4:5], v[0:1], 0, v[12:13]
	s_mov_b32 s75, s87
	s_mov_b32 s83, s87
	v_lshl_add_u64 v[18:19], v[18:19], 0, v[12:13]
	v_lshl_add_u64 v[0:1], v[4:5], 0, s[86:87]
	v_lshl_add_u64 v[6:7], v[4:5], 0, s[74:75]
	v_lshl_add_u64 v[14:15], v[4:5], 0, s[82:83]
	v_lshl_add_u64 v[20:21], v[18:19], 0, s[86:87]
	v_mov_b32_e32 v250, v4
	v_mov_b32_e32 v251, v5
	s_nop 0
	s_nop 0
	s_nop 0
	s_nop 0
	v_mov_b32_e32 v248, v18
	v_mov_b32_e32 v249, v19
	v_lshl_add_u64 v[20:21], v[18:19], 0, s[74:75]
	v_lshl_add_u64 v[26:27], v[18:19], 0, s[82:83]
	s_nop 0
	v_and_b32_e32 v35, 15, v36
	v_lshrrev_b32_e32 v42, 1, v36
	v_and_or_b32 v35, v42, s3, v35
	v_mul_lo_u32 v42, v35, s89
	v_mul_lo_u32 v43, v34, s89
	v_lshl_add_u64 v[34:35], v[12:13], 0, s[78:79]
	v_and_b32_e32 v41, 48, v36
	v_and_b32_e32 v36, 0x4f, v36
	v_lshl_add_u64 v[102:103], s[42:43], 0, v[34:35]
	v_lshl_add_u64 v[104:105], s[44:45], 0, v[34:35]
	v_lshl_add_u64 v[106:107], s[46:47], 0, v[34:35]
	v_lshl_add_u64 v[108:109], s[40:41], 0, v[34:35]
	v_or_b32_e32 v34, s19, v12
	v_mov_b32_e32 v35, v13
	v_mul_u32_u24_e32 v36, 0xa0, v36
	v_mul_lo_u32 v37, v37, s89
	v_mul_lo_u32 v38, v38, s89
	v_mul_lo_u32 v39, v39, s89
	v_mul_lo_u32 v40, v40, s89
	v_lshl_add_u64 v[110:111], s[48:49], 0, v[34:35]
	v_lshl_add_u64 v[112:113], s[50:51], 0, v[34:35]
	v_lshl_add_u64 v[114:115], s[52:53], 0, v[34:35]
	v_lshl_add_u64 v[116:117], s[54:55], 0, v[34:35]
	v_mov_b32_e32 v34, 0
	v_add_u32_e32 v120, v12, v43
	v_add_u32_e32 v121, v12, v37
	v_add_u32_e32 v122, v12, v38
	v_add_u32_e32 v123, v12, v39
	v_add_u32_e32 v124, v12, v40
	v_add_u32_e32 v119, v41, v42
	v_add_u32_e32 v12, v41, v36
	s_mov_b32 s19, vcc_hi
	v_mov_b32_e32 v35, v34
	v_mov_b32_e32 v36, v34
	v_mov_b32_e32 v37, v34
	v_mov_b32_e32 v38, v34
	v_mov_b32_e32 v39, v34
	v_mov_b32_e32 v40, v34
	v_mov_b32_e32 v41, v34
	v_mov_b32_e32 v42, v34
	v_mov_b32_e32 v43, v34
	v_mov_b32_e32 v44, v34
	v_mov_b32_e32 v45, v34
	v_mov_b32_e32 v46, v34
	v_mov_b32_e32 v47, v34
	v_mov_b32_e32 v48, v34
	v_mov_b32_e32 v49, v34
; __device__ __forceinline__ int tidx() { int t = threadIdx.x; asm volatile("" : "+v"(t)); return t; }
; template <int NT>
; __device__ __forceinline__ void gemm_tile(f32x4 (&acc)[4][NT], const bf16_t* A, int lda, const bf16_t* B, int ldb, int K, bf16_t* sm) {
;     const int tid_ = tidx();
;     bf16_t* sA = sm; bf16_t* sB = sm + 128 * LDT;
;     const int tid = tid_, lane = tid & 63, wid = tid >> 6, wr = wid >> 1, wc = wid & 1;
;     const int fr = lane & 15, fq = lane >> 4;
;     const int lrow = tid >> 3, lkc = tid & 7;
;     const bf16_t* ga = A + (size_t)lrow * lda + lkc * 8;
;     const bf16_t* gb = B + (size_t)lrow * ldb + lkc * 8;
;     int sbrow[NT];
; #pragma unroll
;     for (int i = 0; i < NT; ++i) { const int g = lrow + 32 * i, W_ = 16 * NT, rem = g % W_; sbrow[i] = (g / W_) * W_ + (rem % NT) * 16 + rem / NT; }
;     u32x4 ra0[4], rb0[NT];
; #pragma unroll
;     for (int i = 0; i < 4; ++i) ra0[i] = *(const u32x4*)(ga + (size_t)(32 * i) * lda);
; #pragma unroll
;     for (int i = 0; i < NT; ++i) rb0[i] = *(const u32x4*)(gb + (size_t)(32 * i) * ldb);
;     const int nk = K >> 6;
;     for (int kt = 0; kt < nk; ++kt) {
;         lds_barrier();
; #pragma unroll
;         for (int i = 0; i < 4; ++i) *(u32x4*)(sA + (lrow + 32 * i) * LDT + lkc * 8) = ra0[i];
; #pragma unroll
;         for (int i = 0; i < NT; ++i) *(u32x4*)(sB + sbrow[i] * LDT + lkc * 8) = rb0[i];
;         lds_barrier();
	v_mov_b32_e32 v50, v34
	v_mov_b32_e32 v51, v34
	v_mov_b32_e32 v52, v34
	v_mov_b32_e32 v53, v34
	v_mov_b32_e32 v54, v34
	v_mov_b32_e32 v55, v34
	v_mov_b32_e32 v56, v34
	v_mov_b32_e32 v57, v34
	v_mov_b32_e32 v58, v34
	v_mov_b32_e32 v59, v34
	v_mov_b32_e32 v60, v34
	v_mov_b32_e32 v61, v34
	v_mov_b32_e32 v62, v34
	v_mov_b32_e32 v63, v34
	v_mov_b32_e32 v64, v34
	v_mov_b32_e32 v65, v34
	v_mov_b32_e32 v66, v34
	v_mov_b32_e32 v67, v34
	v_mov_b32_e32 v68, v34
	v_mov_b32_e32 v69, v34
	v_mov_b32_e32 v70, v34
	v_mov_b32_e32 v71, v34
	v_mov_b32_e32 v72, v34
	v_mov_b32_e32 v73, v34
	v_mov_b32_e32 v74, v34
	v_mov_b32_e32 v75, v34
	v_mov_b32_e32 v76, v34
	v_mov_b32_e32 v77, v34
	v_mov_b32_e32 v78, v34
	v_mov_b32_e32 v79, v34
	v_mov_b32_e32 v80, v34
	v_mov_b32_e32 v81, v34
	v_mov_b32_e32 v82, v34
	v_mov_b32_e32 v83, v34
	v_mov_b32_e32 v84, v34
	v_mov_b32_e32 v85, v34
	v_mov_b32_e32 v86, v34
	v_mov_b32_e32 v87, v34
	v_mov_b32_e32 v88, v34
	v_mov_b32_e32 v89, v34
	v_mov_b32_e32 v90, v34
	v_mov_b32_e32 v91, v34
	v_mov_b32_e32 v92, v34
	v_mov_b32_e32 v93, v34
	v_mov_b32_e32 v94, v34
	v_mov_b32_e32 v95, v34
	v_mov_b32_e32 v96, v34
	v_mov_b32_e32 v97, v34
	v_writelane_b32 v234, s90, 0
	v_writelane_b32 v234, s91, 1
	v_writelane_b32 v234, s92, 2
	v_writelane_b32 v234, s93, 3
	v_writelane_b32 v234, s94, 4
	v_writelane_b32 v234, s95, 5
	v_bfe_u32 v160, v192, 3, 3
	v_and_b32_e32 v161, 7, v192
	v_xor_b32_e32 v161, v160, v161
	v_lshlrev_b32_e32 v161, 4, v161
	v_lshrrev_b32_e32 v162, 6, v192
	v_lshl_add_u32 v163, v162, 5, v160
	s_lshl_b32 s95, s96, 1
	v_mul_u32_u24_e32 v163, s95, v163
	v_add_u32_e32 v236, v163, v161
	s_lshl_b32 s95, s96, 4
	s_sub_u32 s95, s95, 0x400
	v_add_u32_e32 v237, s95, v236
	v_add_u32_e32 v238, s95, v237
	v_add_u32_e32 v239, s95, v238
	v_lshrrev_b32_e32 v163, 7, v192
	v_bfe_u32 v162, v192, 6, 1
	v_lshlrev_b32_e32 v163, 6, v163
	v_lshl_add_u32 v163, v160, 2, v163
	v_lshl_add_u32 v163, v162, 1, v163
	s_lshl_b32 s95, s96, 1
	v_mul_u32_u24_e32 v163, s95, v163
	v_add_u32_e32 v240, v163, v161
	s_mul_i32 s95, s96, 64
	s_sub_u32 s95, s95, 0x400
	v_add_u32_e32 v241, s95, v240
	s_mul_i32 s95, s96, 62
	s_add_u32 s95, s95, 0x400
	v_subrev_u32_e32 v242, s95, v241
	s_mul_i32 s95, s96, 64
	s_sub_u32 s95, s95, 0x400
	v_add_u32_e32 v243, s95, v242
	v_and_b32_e32 v160, 15, v192
	v_bfe_u32 v161, v192, 4, 2
	v_and_b32_e32 v162, 7, v160
	v_xor_b32_e32 v161, v161, v162
	v_lshlrev_b32_e32 v161, 4, v161
	v_lshl_add_u32 v161, v160, 7, v161
	v_lshrrev_b32_e32 v162, 7, v192
	v_lshl_add_u32 v244, v162, 13, v161
	v_bfe_u32 v162, v192, 6, 1
	v_lshl_add_u32 v246, v162, 13, v161
	v_add_u32_e32 v246, 0x4000, v246
	v_xor_b32_e32 v245, 64, v244
	v_xor_b32_e32 v247, 64, v246
	v_lshrrev_b32_e32 v160, 6, v192
	s_nop 0
	v_readfirstlane_b32 s94, v160
	v_readfirstlane_b32 s90, v248
	v_readfirstlane_b32 s91, v249
	v_readfirstlane_b32 s92, v250
	v_readfirstlane_b32 s93, v251
	s_lshl_b32 s95, s96, 4
	s_mul_i32 s95, s94, s95
	s_sub_u32 s90, s90, s95
	s_subb_u32 s91, s91, 0
	s_lshl_b32 s95, s96, 4
	s_mul_i32 s95, s94, s95
	s_sub_u32 s92, s92, s95
	s_subb_u32 s93, s93, 0
	s_lshl_b32 s94, s94, 10
	s_waitcnt lgkmcnt(0)
	s_barrier
	s_lshl_b32 s95, s94, 2
	s_add_u32 m0, s95, 0x0
	s_nop 0
	global_load_lds_dwordx4 v236, s[90:91] sc1
	global_load_lds_dwordx4 v237, s[90:91] offset:1024 sc1
	global_load_lds_dwordx4 v238, s[90:91] offset:2048 sc1
	global_load_lds_dwordx4 v239, s[90:91] offset:3072 sc1
	s_mul_i32 s95, s94, 4
	s_add_u32 m0, s95, 0x4000
	s_nop 0
	global_load_lds_dwordx4 v240, s[92:93]
	global_load_lds_dwordx4 v241, s[92:93] offset:1024
	global_load_lds_dwordx4 v242, s[92:93] offset:2048
	global_load_lds_dwordx4 v243, s[92:93] offset:3072
	s_add_u32 s90, s90, 0x80
	s_addc_u32 s91, s91, 0
	s_add_u32 s92, s92, 0x80
	s_addc_u32 s93, s93, 0
	s_waitcnt vmcnt(0)
	s_barrier
	s_lshl_b32 s95, s94, 2
	s_add_u32 m0, s95, 0x8000
	s_nop 0
	global_load_lds_dwordx4 v236, s[90:91] sc1
	global_load_lds_dwordx4 v237, s[90:91] offset:1024 sc1
	global_load_lds_dwordx4 v238, s[90:91] offset:2048 sc1
	global_load_lds_dwordx4 v239, s[90:91] offset:3072 sc1
	s_mul_i32 s95, s94, 4
	s_add_u32 m0, s95, 0xc000
	s_nop 0
	global_load_lds_dwordx4 v240, s[92:93]
	global_load_lds_dwordx4 v241, s[92:93] offset:1024
	global_load_lds_dwordx4 v242, s[92:93] offset:2048
	global_load_lds_dwordx4 v243, s[92:93] offset:3072
	s_add_u32 s90, s90, 0x80
	s_addc_u32 s91, s91, 0
	s_add_u32 s92, s92, 0x80
	s_addc_u32 s93, s93, 0
	ds_read_b128 v[126:129], v244 offset:0
	ds_read_b128 v[130:133], v244 offset:2048
	ds_read_b128 v[134:137], v244 offset:4096
	ds_read_b128 v[138:141], v244 offset:6144
	ds_read_b128 v[142:145], v246 offset:0
	ds_read_b128 v[146:149], v246 offset:2048
	ds_read_b128 v[152:155], v246 offset:4096
	ds_read_b128 v[156:159], v246 offset:6144
	s_lshr_b32 s95, s96, 7
	s_add_i32 s95, s95, -2
	s_cmp_eq_u32 s95, 0
	s_cbranch_scc1 .Lgemm_x36
; template <int NT>
; __device__ __forceinline__ void gemm_compute(f32x4 (&acc)[4][NT], const bf16_t* sA, const bf16_t* sB, int wr, int wc, int fr, int fq) {
; #pragma unroll
;     for (int ks = 0; ks < 2; ++ks) {
;         bf16x8 a[4], b[NT];
; #pragma unroll
;         for (int mt = 0; mt < 4; ++mt) a[mt] = *(const bf16x8*)(sA + (wr * 64 + mt * 16 + fr) * LDT + ks * 32 + fq * 8);
; #pragma unroll
;         for (int nt = 0; nt < NT; ++nt) b[nt] = *(const bf16x8*)(sB + (wc * 16 * NT + nt * 16 + fr) * LDT + ks * 32 + fq * 8);
;         __builtin_amdgcn_s_setprio(1);
; #pragma unroll
;         for (int mt = 0; mt < 4; ++mt)
; #pragma unroll
;             for (int nt = 0; nt < NT; ++nt)
;                 acc[mt][nt] = __builtin_amdgcn_mfma_f32_16x16x32_bf16(b[nt], a[mt], acc[mt][nt], 0, 0, 0);
;         __builtin_amdgcn_s_setprio(0);
;     }
; template <int NT>
; __device__ __forceinline__ void gemm_tile(f32x4 (&acc)[4][NT], const bf16_t* A, int lda, const bf16_t* B, int ldb, int K, bf16_t* sm) {
;     ...
;     for (int kt = 0; kt < nk; ++kt) {
;         lds_barrier();
; #pragma unroll
;         for (int i = 0; i < 4; ++i) *(u32x4*)(sA + (lrow + 32 * i) * LDT + lkc * 8) = ra0[i];
; #pragma unroll
;         for (int i = 0; i < NT; ++i) *(u32x4*)(sB + sbrow[i] * LDT + lkc * 8) = rb0[i];
;         lds_barrier();
;         if (kt + 1 < nk) {
;             ga += 64; gb += 64;
; #pragma unroll
;             for (int i = 0; i < 4; ++i) ra0[i] = *(const u32x4*)(ga + (size_t)(32 * i) * lda);
; #pragma unroll
;             for (int i = 0; i < NT; ++i) rb0[i] = *(const u32x4*)(gb + (size_t)(32 * i) * ldb);
;         }
;         __builtin_amdgcn_sched_barrier(0);
;         gemm_compute<NT>(acc, sA, sB, wr, wc, fr, fq);
.Lgemm_k36:
	v_writelane_b32 v234, s95, 6
	ds_read_b128 v[160:163], v245 offset:0
	ds_read_b128 v[164:167], v245 offset:2048
	ds_read_b128 v[168:171], v245 offset:4096
	ds_read_b128 v[172:175], v245 offset:6144
	ds_read_b128 v[176:179], v247 offset:0
	ds_read_b128 v[180:183], v247 offset:2048
	ds_read_b128 v[184:187], v247 offset:4096
	ds_read_b128 v[188:191], v247 offset:6144
	s_setprio 1
	s_waitcnt lgkmcnt(11)
	v_mfma_f32_16x16x32_bf16 v[94:97], v[142:145], v[126:129], v[94:97]
	s_waitcnt lgkmcnt(10)
	v_mfma_f32_16x16x32_bf16 v[90:93], v[146:149], v[126:129], v[90:93]
	s_waitcnt lgkmcnt(9)
	v_mfma_f32_16x16x32_bf16 v[86:89], v[152:155], v[126:129], v[86:89]
	s_waitcnt lgkmcnt(8)
	v_mfma_f32_16x16x32_bf16 v[82:85], v[156:159], v[126:129], v[82:85]
	v_mfma_f32_16x16x32_bf16 v[78:81], v[142:145], v[130:133], v[78:81]
	v_mfma_f32_16x16x32_bf16 v[74:77], v[146:149], v[130:133], v[74:77]
	v_mfma_f32_16x16x32_bf16 v[70:73], v[152:155], v[130:133], v[70:73]
	v_mfma_f32_16x16x32_bf16 v[66:69], v[156:159], v[130:133], v[66:69]
	v_mfma_f32_16x16x32_bf16 v[62:65], v[142:145], v[134:137], v[62:65]
	v_mfma_f32_16x16x32_bf16 v[58:61], v[146:149], v[134:137], v[58:61]
	v_mfma_f32_16x16x32_bf16 v[54:57], v[152:155], v[134:137], v[54:57]
	v_mfma_f32_16x16x32_bf16 v[50:53], v[156:159], v[134:137], v[50:53]
	v_mfma_f32_16x16x32_bf16 v[46:49], v[142:145], v[138:141], v[46:49]
	v_mfma_f32_16x16x32_bf16 v[42:45], v[146:149], v[138:141], v[42:45]
	v_mfma_f32_16x16x32_bf16 v[38:41], v[152:155], v[138:141], v[38:41]
	v_mfma_f32_16x16x32_bf16 v[34:37], v[156:159], v[138:141], v[34:37]
	s_setprio 0
	s_waitcnt vmcnt(0) lgkmcnt(0)
	s_barrier
	ds_read_b128 v[126:129], v244 offset:32768
	ds_read_b128 v[130:133], v244 offset:34816
	ds_read_b128 v[134:137], v244 offset:36864
	ds_read_b128 v[138:141], v244 offset:38912
	ds_read_b128 v[142:145], v246 offset:32768
	ds_read_b128 v[146:149], v246 offset:34816
	ds_read_b128 v[152:155], v246 offset:36864
	ds_read_b128 v[156:159], v246 offset:38912
	s_setprio 1
	v_mfma_f32_16x16x32_bf16 v[94:97], v[176:179], v[160:163], v[94:97]
	s_lshl_b32 s95, s94, 2
	s_add_u32 m0, s95, 0x0
	s_nop 0
	global_load_lds_dwordx4 v236, s[90:91] sc1
	v_mfma_f32_16x16x32_bf16 v[90:93], v[180:183], v[160:163], v[90:93]
	v_mfma_f32_16x16x32_bf16 v[86:89], v[184:187], v[160:163], v[86:89]
	global_load_lds_dwordx4 v237, s[90:91] offset:1024 sc1
	v_mfma_f32_16x16x32_bf16 v[82:85], v[188:191], v[160:163], v[82:85]
	v_mfma_f32_16x16x32_bf16 v[78:81], v[176:179], v[164:167], v[78:81]
	global_load_lds_dwordx4 v238, s[90:91] offset:2048 sc1
	v_mfma_f32_16x16x32_bf16 v[74:77], v[180:183], v[164:167], v[74:77]
	v_mfma_f32_16x16x32_bf16 v[70:73], v[184:187], v[164:167], v[70:73]
	global_load_lds_dwordx4 v239, s[90:91] offset:3072 sc1
	v_mfma_f32_16x16x32_bf16 v[66:69], v[188:191], v[164:167], v[66:69]
	v_mfma_f32_16x16x32_bf16 v[62:65], v[176:179], v[168:171], v[62:65]
	s_mul_i32 s95, s94, 4
	s_add_u32 m0, s95, 0x4000
	s_nop 0
	global_load_lds_dwordx4 v240, s[92:93]
	v_mfma_f32_16x16x32_bf16 v[58:61], v[180:183], v[168:171], v[58:61]
	v_mfma_f32_16x16x32_bf16 v[54:57], v[184:187], v[168:171], v[54:57]
	global_load_lds_dwordx4 v241, s[92:93] offset:1024
	v_mfma_f32_16x16x32_bf16 v[50:53], v[188:191], v[168:171], v[50:53]
	v_mfma_f32_16x16x32_bf16 v[46:49], v[176:179], v[172:175], v[46:49]
	global_load_lds_dwordx4 v242, s[92:93] offset:2048
	v_mfma_f32_16x16x32_bf16 v[42:45], v[180:183], v[172:175], v[42:45]
	v_mfma_f32_16x16x32_bf16 v[38:41], v[184:187], v[172:175], v[38:41]
	global_load_lds_dwordx4 v243, s[92:93] offset:3072
	v_mfma_f32_16x16x32_bf16 v[34:37], v[188:191], v[172:175], v[34:37]
	s_add_u32 s90, s90, 0x80
	s_addc_u32 s91, s91, 0
	s_add_u32 s92, s92, 0x80
	s_addc_u32 s93, s93, 0
	s_setprio 0
	ds_read_b128 v[160:163], v245 offset:32768
	ds_read_b128 v[164:167], v245 offset:34816
	ds_read_b128 v[168:171], v245 offset:36864
	ds_read_b128 v[172:175], v245 offset:38912
	ds_read_b128 v[176:179], v247 offset:32768
	ds_read_b128 v[180:183], v247 offset:34816
	ds_read_b128 v[184:187], v247 offset:36864
	ds_read_b128 v[188:191], v247 offset:38912
	s_setprio 1
	s_waitcnt lgkmcnt(11)
	v_mfma_f32_16x16x32_bf16 v[94:97], v[142:145], v[126:129], v[94:97]
	s_waitcnt lgkmcnt(10)
	v_mfma_f32_16x16x32_bf16 v[90:93], v[146:149], v[126:129], v[90:93]
	s_waitcnt lgkmcnt(9)
	v_mfma_f32_16x16x32_bf16 v[86:89], v[152:155], v[126:129], v[86:89]
	s_waitcnt lgkmcnt(8)
	v_mfma_f32_16x16x32_bf16 v[82:85], v[156:159], v[126:129], v[82:85]
	v_mfma_f32_16x16x32_bf16 v[78:81], v[142:145], v[130:133], v[78:81]
	v_mfma_f32_16x16x32_bf16 v[74:77], v[146:149], v[130:133], v[74:77]
	v_mfma_f32_16x16x32_bf16 v[70:73], v[152:155], v[130:133], v[70:73]
	v_mfma_f32_16x16x32_bf16 v[66:69], v[156:159], v[130:133], v[66:69]
	v_mfma_f32_16x16x32_bf16 v[62:65], v[142:145], v[134:137], v[62:65]
	v_mfma_f32_16x16x32_bf16 v[58:61], v[146:149], v[134:137], v[58:61]
	v_mfma_f32_16x16x32_bf16 v[54:57], v[152:155], v[134:137], v[54:57]
	v_mfma_f32_16x16x32_bf16 v[50:53], v[156:159], v[134:137], v[50:53]
	v_mfma_f32_16x16x32_bf16 v[46:49], v[142:145], v[138:141], v[46:49]
	v_mfma_f32_16x16x32_bf16 v[42:45], v[146:149], v[138:141], v[42:45]
	v_mfma_f32_16x16x32_bf16 v[38:41], v[152:155], v[138:141], v[38:41]
	v_mfma_f32_16x16x32_bf16 v[34:37], v[156:159], v[138:141], v[34:37]
	s_setprio 0
	s_waitcnt vmcnt(0) lgkmcnt(0)
	s_barrier
; template <int NT>
; __device__ __forceinline__ void gemm_compute(f32x4 (&acc)[4][NT], const bf16_t* sA, const bf16_t* sB, int wr, int wc, int fr, int fq) {
; #pragma unroll
;     for (int ks = 0; ks < 2; ++ks) {
;         bf16x8 a[4], b[NT];
; #pragma unroll
;         for (int mt = 0; mt < 4; ++mt) a[mt] = *(const bf16x8*)(sA + (wr * 64 + mt * 16 + fr) * LDT + ks * 32 + fq * 8);
; #pragma unroll
;         for (int nt = 0; nt < NT; ++nt) b[nt] = *(const bf16x8*)(sB + (wc * 16 * NT + nt * 16 + fr) * LDT + ks * 32 + fq * 8);
;         __builtin_amdgcn_s_setprio(1);
; #pragma unroll
;         for (int mt = 0; mt < 4; ++mt)
; #pragma unroll
;             for (int nt = 0; nt < NT; ++nt)
;                 acc[mt][nt] = __builtin_amdgcn_mfma_f32_16x16x32_bf16(b[nt], a[mt], acc[mt][nt], 0, 0, 0);
;         __builtin_amdgcn_s_setprio(0);
;     }
; template <int NT>
; __device__ __forceinline__ void gemm_tile(f32x4 (&acc)[4][NT], const bf16_t* A, int lda, const bf16_t* B, int ldb, int K, bf16_t* sm) {
;     ...
;     for (int kt = 0; kt < nk; ++kt) {
;         lds_barrier();
; #pragma unroll
;         for (int i = 0; i < 4; ++i) *(u32x4*)(sA + (lrow + 32 * i) * LDT + lkc * 8) = ra0[i];
; #pragma unroll
;         for (int i = 0; i < NT; ++i) *(u32x4*)(sB + sbrow[i] * LDT + lkc * 8) = rb0[i];
;         lds_barrier();
;         if (kt + 1 < nk) {
;             ga += 64; gb += 64;
; #pragma unroll
;             for (int i = 0; i < 4; ++i) ra0[i] = *(const u32x4*)(ga + (size_t)(32 * i) * lda);
; #pragma unroll
;             for (int i = 0; i < NT; ++i) rb0[i] = *(const u32x4*)(gb + (size_t)(32 * i) * ldb);
;         }
;         __builtin_amdgcn_sched_barrier(0);
;         gemm_compute<NT>(acc, sA, sB, wr, wc, fr, fq);
	ds_read_b128 v[126:129], v244 offset:0
	ds_read_b128 v[130:133], v244 offset:2048
	ds_read_b128 v[134:137], v244 offset:4096
	ds_read_b128 v[138:141], v244 offset:6144
	ds_read_b128 v[142:145], v246 offset:0
	ds_read_b128 v[146:149], v246 offset:2048
	ds_read_b128 v[152:155], v246 offset:4096
	ds_read_b128 v[156:159], v246 offset:6144
	s_setprio 1
	v_mfma_f32_16x16x32_bf16 v[94:97], v[176:179], v[160:163], v[94:97]
	s_lshl_b32 s95, s94, 2
	s_add_u32 m0, s95, 0x8000
	s_nop 0
	global_load_lds_dwordx4 v236, s[90:91] sc1
	v_mfma_f32_16x16x32_bf16 v[90:93], v[180:183], v[160:163], v[90:93]
	v_mfma_f32_16x16x32_bf16 v[86:89], v[184:187], v[160:163], v[86:89]
	global_load_lds_dwordx4 v237, s[90:91] offset:1024 sc1
	v_mfma_f32_16x16x32_bf16 v[82:85], v[188:191], v[160:163], v[82:85]
	v_mfma_f32_16x16x32_bf16 v[78:81], v[176:179], v[164:167], v[78:81]
	global_load_lds_dwordx4 v238, s[90:91] offset:2048 sc1
	v_mfma_f32_16x16x32_bf16 v[74:77], v[180:183], v[164:167], v[74:77]
	v_mfma_f32_16x16x32_bf16 v[70:73], v[184:187], v[164:167], v[70:73]
	global_load_lds_dwordx4 v239, s[90:91] offset:3072 sc1
	v_mfma_f32_16x16x32_bf16 v[66:69], v[188:191], v[164:167], v[66:69]
	v_mfma_f32_16x16x32_bf16 v[62:65], v[176:179], v[168:171], v[62:65]
	s_mul_i32 s95, s94, 4
	s_add_u32 m0, s95, 0xc000
	s_nop 0
	global_load_lds_dwordx4 v240, s[92:93]
	v_mfma_f32_16x16x32_bf16 v[58:61], v[180:183], v[168:171], v[58:61]
	v_mfma_f32_16x16x32_bf16 v[54:57], v[184:187], v[168:171], v[54:57]
	global_load_lds_dwordx4 v241, s[92:93] offset:1024
	v_mfma_f32_16x16x32_bf16 v[50:53], v[188:191], v[168:171], v[50:53]
	v_mfma_f32_16x16x32_bf16 v[46:49], v[176:179], v[172:175], v[46:49]
	global_load_lds_dwordx4 v242, s[92:93] offset:2048
	v_mfma_f32_16x16x32_bf16 v[42:45], v[180:183], v[172:175], v[42:45]
	v_mfma_f32_16x16x32_bf16 v[38:41], v[184:187], v[172:175], v[38:41]
	global_load_lds_dwordx4 v243, s[92:93] offset:3072
	v_mfma_f32_16x16x32_bf16 v[34:37], v[188:191], v[172:175], v[34:37]
	s_add_u32 s90, s90, 0x80
	s_addc_u32 s91, s91, 0
	s_add_u32 s92, s92, 0x80
	s_addc_u32 s93, s93, 0
	s_setprio 0
	v_readlane_b32 s95, v234, 6
	s_add_i32 s95, s95, -1
	s_cmp_lg_u32 s95, 0
	s_cbranch_scc1 .Lgemm_k36
.Lgemm_x36:
	ds_read_b128 v[160:163], v245 offset:0
	ds_read_b128 v[164:167], v245 offset:2048
	ds_read_b128 v[168:171], v245 offset:4096
	ds_read_b128 v[172:175], v245 offset:6144
	ds_read_b128 v[176:179], v247 offset:0
	ds_read_b128 v[180:183], v247 offset:2048
	ds_read_b128 v[184:187], v247 offset:4096
	ds_read_b128 v[188:191], v247 offset:6144
	s_setprio 1
	s_waitcnt lgkmcnt(11)
	v_mfma_f32_16x16x32_bf16 v[94:97], v[142:145], v[126:129], v[94:97]
	s_waitcnt lgkmcnt(10)
	v_mfma_f32_16x16x32_bf16 v[90:93], v[146:149], v[126:129], v[90:93]
	s_waitcnt lgkmcnt(9)
	v_mfma_f32_16x16x32_bf16 v[86:89], v[152:155], v[126:129], v[86:89]
	s_waitcnt lgkmcnt(8)
	v_mfma_f32_16x16x32_bf16 v[82:85], v[156:159], v[126:129], v[82:85]
	v_mfma_f32_16x16x32_bf16 v[78:81], v[142:145], v[130:133], v[78:81]
	v_mfma_f32_16x16x32_bf16 v[74:77], v[146:149], v[130:133], v[74:77]
	v_mfma_f32_16x16x32_bf16 v[70:73], v[152:155], v[130:133], v[70:73]
	v_mfma_f32_16x16x32_bf16 v[66:69], v[156:159], v[130:133], v[66:69]
	v_mfma_f32_16x16x32_bf16 v[62:65], v[142:145], v[134:137], v[62:65]
	v_mfma_f32_16x16x32_bf16 v[58:61], v[146:149], v[134:137], v[58:61]
	v_mfma_f32_16x16x32_bf16 v[54:57], v[152:155], v[134:137], v[54:57]
	v_mfma_f32_16x16x32_bf16 v[50:53], v[156:159], v[134:137], v[50:53]
	v_mfma_f32_16x16x32_bf16 v[46:49], v[142:145], v[138:141], v[46:49]
	v_mfma_f32_16x16x32_bf16 v[42:45], v[146:149], v[138:141], v[42:45]
	v_mfma_f32_16x16x32_bf16 v[38:41], v[152:155], v[138:141], v[38:41]
	v_mfma_f32_16x16x32_bf16 v[34:37], v[156:159], v[138:141], v[34:37]
	s_setprio 0
	s_waitcnt vmcnt(0) lgkmcnt(0)
	s_barrier
	ds_read_b128 v[126:129], v244 offset:32768
	ds_read_b128 v[130:133], v244 offset:34816
	ds_read_b128 v[134:137], v244 offset:36864
	ds_read_b128 v[138:141], v244 offset:38912
	ds_read_b128 v[142:145], v246 offset:32768
	ds_read_b128 v[146:149], v246 offset:34816
	ds_read_b128 v[152:155], v246 offset:36864
	ds_read_b128 v[156:159], v246 offset:38912
	s_setprio 1
	v_mfma_f32_16x16x32_bf16 v[94:97], v[176:179], v[160:163], v[94:97]
	s_lshl_b32 s95, s94, 2
	s_add_u32 m0, s95, 0x0
	s_nop 0
	global_load_lds_dwordx4 v236, s[90:91] sc1
	v_mfma_f32_16x16x32_bf16 v[90:93], v[180:183], v[160:163], v[90:93]
	v_mfma_f32_16x16x32_bf16 v[86:89], v[184:187], v[160:163], v[86:89]
	global_load_lds_dwordx4 v237, s[90:91] offset:1024 sc1
	v_mfma_f32_16x16x32_bf16 v[82:85], v[188:191], v[160:163], v[82:85]
	v_mfma_f32_16x16x32_bf16 v[78:81], v[176:179], v[164:167], v[78:81]
	global_load_lds_dwordx4 v238, s[90:91] offset:2048 sc1
	v_mfma_f32_16x16x32_bf16 v[74:77], v[180:183], v[164:167], v[74:77]
	v_mfma_f32_16x16x32_bf16 v[70:73], v[184:187], v[164:167], v[70:73]
	global_load_lds_dwordx4 v239, s[90:91] offset:3072 sc1
	v_mfma_f32_16x16x32_bf16 v[66:69], v[188:191], v[164:167], v[66:69]
	v_mfma_f32_16x16x32_bf16 v[62:65], v[176:179], v[168:171], v[62:65]
	s_mul_i32 s95, s94, 4
	s_add_u32 m0, s95, 0x4000
	s_nop 0
	global_load_lds_dwordx4 v240, s[92:93]
	v_mfma_f32_16x16x32_bf16 v[58:61], v[180:183], v[168:171], v[58:61]
	v_mfma_f32_16x16x32_bf16 v[54:57], v[184:187], v[168:171], v[54:57]
	global_load_lds_dwordx4 v241, s[92:93] offset:1024
	v_mfma_f32_16x16x32_bf16 v[50:53], v[188:191], v[168:171], v[50:53]
	v_mfma_f32_16x16x32_bf16 v[46:49], v[176:179], v[172:175], v[46:49]
	global_load_lds_dwordx4 v242, s[92:93] offset:2048
	v_mfma_f32_16x16x32_bf16 v[42:45], v[180:183], v[172:175], v[42:45]
	v_mfma_f32_16x16x32_bf16 v[38:41], v[184:187], v[172:175], v[38:41]
	global_load_lds_dwordx4 v243, s[92:93] offset:3072
	v_mfma_f32_16x16x32_bf16 v[34:37], v[188:191], v[172:175], v[34:37]
	s_add_u32 s90, s90, 0x80
	s_addc_u32 s91, s91, 0
	s_add_u32 s92, s92, 0x80
	s_addc_u32 s93, s93, 0
	s_setprio 0
	ds_read_b128 v[160:163], v245 offset:32768
	ds_read_b128 v[164:167], v245 offset:34816
	ds_read_b128 v[168:171], v245 offset:36864
	ds_read_b128 v[172:175], v245 offset:38912
	ds_read_b128 v[176:179], v247 offset:32768
	ds_read_b128 v[180:183], v247 offset:34816
	ds_read_b128 v[184:187], v247 offset:36864
	ds_read_b128 v[188:191], v247 offset:38912
	s_setprio 1
	s_waitcnt lgkmcnt(11)
; template <int NT>
; __device__ __forceinline__ void gemm_tile(f32x4 (&acc)[4][NT], const bf16_t* A, int lda, const bf16_t* B, int ldb, int K, bf16_t* sm) {
;     ...
;         if (kt + 1 < nk) {
;             ga += 64; gb += 64;
; #pragma unroll
;             for (int i = 0; i < 4; ++i) ra0[i] = *(const u32x4*)(ga + (size_t)(32 * i) * lda);
; #pragma unroll
;             for (int i = 0; i < NT; ++i) rb0[i] = *(const u32x4*)(gb + (size_t)(32 * i) * ldb);
;         }
;         __builtin_amdgcn_sched_barrier(0);
;         gemm_compute<NT>(acc, sA, sB, wr, wc, fr, fq);
	v_mfma_f32_16x16x32_bf16 v[94:97], v[142:145], v[126:129], v[94:97]
	s_waitcnt lgkmcnt(10)
	v_mfma_f32_16x16x32_bf16 v[90:93], v[146:149], v[126:129], v[90:93]
	s_waitcnt lgkmcnt(9)
	v_mfma_f32_16x16x32_bf16 v[86:89], v[152:155], v[126:129], v[86:89]
	s_waitcnt lgkmcnt(8)
	v_mfma_f32_16x16x32_bf16 v[82:85], v[156:159], v[126:129], v[82:85]
	v_mfma_f32_16x16x32_bf16 v[78:81], v[142:145], v[130:133], v[78:81]
	v_mfma_f32_16x16x32_bf16 v[74:77], v[146:149], v[130:133], v[74:77]
	v_mfma_f32_16x16x32_bf16 v[70:73], v[152:155], v[130:133], v[70:73]
	v_mfma_f32_16x16x32_bf16 v[66:69], v[156:159], v[130:133], v[66:69]
	v_mfma_f32_16x16x32_bf16 v[62:65], v[142:145], v[134:137], v[62:65]
	v_mfma_f32_16x16x32_bf16 v[58:61], v[146:149], v[134:137], v[58:61]
	v_mfma_f32_16x16x32_bf16 v[54:57], v[152:155], v[134:137], v[54:57]
	v_mfma_f32_16x16x32_bf16 v[50:53], v[156:159], v[134:137], v[50:53]
	v_mfma_f32_16x16x32_bf16 v[46:49], v[142:145], v[138:141], v[46:49]
	v_mfma_f32_16x16x32_bf16 v[42:45], v[146:149], v[138:141], v[42:45]
	v_mfma_f32_16x16x32_bf16 v[38:41], v[152:155], v[138:141], v[38:41]
	v_mfma_f32_16x16x32_bf16 v[34:37], v[156:159], v[138:141], v[34:37]
	s_setprio 0
	s_waitcnt vmcnt(0) lgkmcnt(0)
	s_barrier
	ds_read_b128 v[126:129], v244 offset:0
	ds_read_b128 v[130:133], v244 offset:2048
	ds_read_b128 v[134:137], v244 offset:4096
	ds_read_b128 v[138:141], v244 offset:6144
	ds_read_b128 v[142:145], v246 offset:0
	ds_read_b128 v[146:149], v246 offset:2048
	ds_read_b128 v[152:155], v246 offset:4096
	ds_read_b128 v[156:159], v246 offset:6144
	s_setprio 1
	v_mfma_f32_16x16x32_bf16 v[94:97], v[176:179], v[160:163], v[94:97]
	s_lshl_b32 s92, s96, 1
	s_sub_u32 s92, s92, 0x100
	s_mov_b32 s93, 0
	v_lshl_add_u64 v[102:103], v[102:103], 0, s[92:93]
	v_lshl_add_u64 v[104:105], v[104:105], 0, s[92:93]
	v_lshl_add_u64 v[106:107], v[106:107], 0, s[92:93]
	v_lshl_add_u64 v[108:109], v[108:109], 0, s[92:93]
	v_lshl_add_u64 v[110:111], v[110:111], 0, s[92:93]
	v_lshl_add_u64 v[112:113], v[112:113], 0, s[92:93]
	v_lshl_add_u64 v[114:115], v[114:115], 0, s[92:93]
	v_lshl_add_u64 v[116:117], v[116:117], 0, s[92:93]
	v_readlane_b32 s90, v234, 0
	v_readlane_b32 s91, v234, 1
	v_readlane_b32 s92, v234, 2
	v_readlane_b32 s93, v234, 3
	v_readlane_b32 s94, v234, 4
	v_readlane_b32 s95, v234, 5
	s_mov_b32 s19, 0
	s_nop 3
	v_mfma_f32_16x16x32_bf16 v[90:93], v[180:183], v[160:163], v[90:93]
	v_mfma_f32_16x16x32_bf16 v[86:89], v[184:187], v[160:163], v[86:89]
	v_lshl_add_u64 v[0:1], v[108:109], 0, v[100:101]
	v_mfma_f32_16x16x32_bf16 v[82:85], v[188:191], v[160:163], v[82:85]
	v_mfma_f32_16x16x32_bf16 v[78:81], v[176:179], v[164:167], v[78:81]
	global_load_dwordx4 v[30:33], v[0:1], off
	v_mfma_f32_16x16x32_bf16 v[74:77], v[180:183], v[164:167], v[74:77]
	v_mfma_f32_16x16x32_bf16 v[70:73], v[184:187], v[164:167], v[70:73]
	v_lshl_add_u64 v[0:1], v[106:107], 0, v[100:101]
	v_mfma_f32_16x16x32_bf16 v[66:69], v[188:191], v[164:167], v[66:69]
	v_mfma_f32_16x16x32_bf16 v[62:65], v[176:179], v[168:171], v[62:65]
	global_load_dwordx4 v[22:25], v[0:1], off
	v_mfma_f32_16x16x32_bf16 v[58:61], v[180:183], v[168:171], v[58:61]
	v_mfma_f32_16x16x32_bf16 v[54:57], v[184:187], v[168:171], v[54:57]
	v_lshl_add_u64 v[0:1], v[104:105], 0, v[100:101]
	v_mfma_f32_16x16x32_bf16 v[50:53], v[188:191], v[168:171], v[50:53]
	v_mfma_f32_16x16x32_bf16 v[46:49], v[176:179], v[172:175], v[46:49]
	global_load_dwordx4 v[18:21], v[0:1], off
	v_mfma_f32_16x16x32_bf16 v[42:45], v[180:183], v[172:175], v[42:45]
	v_mfma_f32_16x16x32_bf16 v[38:41], v[184:187], v[172:175], v[38:41]
	v_lshl_add_u64 v[0:1], v[102:103], 0, v[100:101]
	v_mfma_f32_16x16x32_bf16 v[34:37], v[188:191], v[172:175], v[34:37]
	global_load_dwordx4 v[26:29], v[0:1], off
	v_lshl_add_u64 v[0:1], v[116:117], 0, v[100:101]
	global_load_dwordx4 v[8:11], v[0:1], off
	v_lshl_add_u64 v[0:1], v[114:115], 0, v[100:101]
	v_lshl_add_u64 v[4:5], v[112:113], 0, v[100:101]
	v_lshl_add_u64 v[14:15], v[110:111], 0, v[100:101]
	global_load_dwordx4 v[0:3], v[0:1], off
	s_nop 0
	global_load_dwordx4 v[4:7], v[4:5], off
	s_nop 0
	global_load_dwordx4 v[14:17], v[14:15], off
	s_setprio 0
	ds_read_b128 v[160:163], v245 offset:0
	ds_read_b128 v[164:167], v245 offset:2048
	ds_read_b128 v[168:171], v245 offset:4096
	ds_read_b128 v[172:175], v245 offset:6144
	ds_read_b128 v[176:179], v247 offset:0
	ds_read_b128 v[180:183], v247 offset:2048
	ds_read_b128 v[184:187], v247 offset:4096
	ds_read_b128 v[188:191], v247 offset:6144
	s_setprio 1
	s_waitcnt lgkmcnt(11)
	v_mfma_f32_16x16x32_bf16 v[94:97], v[142:145], v[126:129], v[94:97]
	s_waitcnt lgkmcnt(10)
	v_mfma_f32_16x16x32_bf16 v[90:93], v[146:149], v[126:129], v[90:93]
	s_waitcnt lgkmcnt(9)
	v_mfma_f32_16x16x32_bf16 v[86:89], v[152:155], v[126:129], v[86:89]
	s_waitcnt lgkmcnt(8)
	v_mfma_f32_16x16x32_bf16 v[82:85], v[156:159], v[126:129], v[82:85]
	v_mfma_f32_16x16x32_bf16 v[78:81], v[142:145], v[130:133], v[78:81]
	v_mfma_f32_16x16x32_bf16 v[74:77], v[146:149], v[130:133], v[74:77]
	v_mfma_f32_16x16x32_bf16 v[70:73], v[152:155], v[130:133], v[70:73]
	v_mfma_f32_16x16x32_bf16 v[66:69], v[156:159], v[130:133], v[66:69]
	v_mfma_f32_16x16x32_bf16 v[62:65], v[142:145], v[134:137], v[62:65]
	v_mfma_f32_16x16x32_bf16 v[58:61], v[146:149], v[134:137], v[58:61]
	v_mfma_f32_16x16x32_bf16 v[54:57], v[152:155], v[134:137], v[54:57]
	v_mfma_f32_16x16x32_bf16 v[50:53], v[156:159], v[134:137], v[50:53]
	v_mfma_f32_16x16x32_bf16 v[46:49], v[142:145], v[138:141], v[46:49]
	v_mfma_f32_16x16x32_bf16 v[42:45], v[146:149], v[138:141], v[42:45]
	v_mfma_f32_16x16x32_bf16 v[38:41], v[152:155], v[138:141], v[38:41]
	v_mfma_f32_16x16x32_bf16 v[34:37], v[156:159], v[138:141], v[34:37]
	s_setprio 0
	s_waitcnt lgkmcnt(0)
	s_setprio 1
	v_mfma_f32_16x16x32_bf16 v[94:97], v[176:179], v[160:163], v[94:97]
	v_mfma_f32_16x16x32_bf16 v[90:93], v[180:183], v[160:163], v[90:93]
	v_mfma_f32_16x16x32_bf16 v[86:89], v[184:187], v[160:163], v[86:89]
	v_mfma_f32_16x16x32_bf16 v[82:85], v[188:191], v[160:163], v[82:85]
	v_mfma_f32_16x16x32_bf16 v[78:81], v[176:179], v[164:167], v[78:81]
	v_mfma_f32_16x16x32_bf16 v[74:77], v[180:183], v[164:167], v[74:77]
	v_mfma_f32_16x16x32_bf16 v[70:73], v[184:187], v[164:167], v[70:73]
	v_mfma_f32_16x16x32_bf16 v[66:69], v[188:191], v[164:167], v[66:69]
	v_mfma_f32_16x16x32_bf16 v[62:65], v[176:179], v[168:171], v[62:65]
	v_mfma_f32_16x16x32_bf16 v[58:61], v[180:183], v[168:171], v[58:61]
	v_mfma_f32_16x16x32_bf16 v[54:57], v[184:187], v[168:171], v[54:57]
	v_mfma_f32_16x16x32_bf16 v[50:53], v[188:191], v[168:171], v[50:53]
	v_mfma_f32_16x16x32_bf16 v[46:49], v[176:179], v[172:175], v[46:49]
	v_mfma_f32_16x16x32_bf16 v[42:45], v[180:183], v[172:175], v[42:45]
	v_mfma_f32_16x16x32_bf16 v[38:41], v[184:187], v[172:175], v[38:41]
	v_mfma_f32_16x16x32_bf16 v[34:37], v[188:191], v[172:175], v[34:37]
	s_setprio 0
	s_waitcnt lgkmcnt(0)
	s_barrier
; template <int NT>
; __device__ __forceinline__ void gemm_tile(f32x4 (&acc)[4][NT], const bf16_t* A, int lda, const bf16_t* B, int ldb, int K, bf16_t* sm) {
;     ...
;         lds_barrier();
; #pragma unroll
;         for (int i = 0; i < 4; ++i) *(u32x4*)(sA + (lrow + 32 * i) * LDT + lkc * 8) = ra0[i];
; #pragma unroll
;         for (int i = 0; i < NT; ++i) *(u32x4*)(sB + sbrow[i] * LDT + lkc * 8) = rb0[i];
;         lds_barrier();
;         if (kt + 1 < nk) {
;             ga += 64; gb += 64;
; #pragma unroll
;             for (int i = 0; i < 4; ++i) ra0[i] = *(const u32x4*)(ga + (size_t)(32 * i) * lda);
; #pragma unroll
;             for (int i = 0; i < NT; ++i) rb0[i] = *(const u32x4*)(gb + (size_t)(32 * i) * ldb);
;         }
;         __builtin_amdgcn_sched_barrier(0);
;         gemm_compute<NT>(acc, sA, sB, wr, wc, fr, fq);
; template <int NT>
; __device__ __forceinline__ void resid_tile(int tm, int col0, const bf16_t* A, int lda, int K, const bf16_t* W, const float* X, float* Y, float scale, bf16_t* sm) {
;     ...
; #pragma unroll
;     for (int mt = 0; mt < 4; ++mt) {
;         const int row = tm * 128 + wr * 64 + mt * 16 + fr;
;         const int cbase = col0 + wc * 16 * NT + fq * 4 * NT;
;         const size_t o = (size_t)row * 1024 + cbase;
;         float v[4 * NT]; gather_cols<NT>(acc, mt, v);
;         float4 xv[NT];
; #pragma unroll
;         for (int q = 0; q < NT; ++q) xv[q] = *(const float4*)(X + o + 4 * q);
; #pragma unroll
;         for (int q = 0; q < NT; ++q)
;             *(float4*)(Y + o + 4 * q) = make_float4(ALPHA * xv[q].x + scale * v[4 * q], ALPHA * xv[q].y + scale * v[4 * q + 1],
;                                                     ALPHA * xv[q].z + scale * v[4 * q + 2], ALPHA * xv[q].w + scale * v[4 * q + 3]);
;     }
	s_waitcnt vmcnt(7)
	ds_write_b128 v120, v[30:33]
	s_waitcnt vmcnt(6)
	ds_write_b128 v120, v[22:25] offset:5120
	s_waitcnt vmcnt(5)
	ds_write_b128 v120, v[18:21] offset:10240
	s_waitcnt vmcnt(4)
	ds_write_b128 v120, v[26:29] offset:15360
	s_waitcnt vmcnt(3)
	ds_write_b128 v121, v[8:11] offset:20480
	s_waitcnt vmcnt(2)
	ds_write_b128 v122, v[0:3] offset:20480
	s_waitcnt vmcnt(1)
	ds_write_b128 v123, v[4:7] offset:20480
	s_waitcnt vmcnt(0)
	ds_write_b128 v124, v[14:17] offset:20480
	s_waitcnt lgkmcnt(0)
	s_barrier
	ds_read_b128 v[0:3], v119
	ds_read_b128 v[4:7], v119 offset:2560
	ds_read_b128 v[8:11], v119 offset:5120
	ds_read_b128 v[14:17], v119 offset:7680
	ds_read_b128 v[18:21], v12 offset:20480
	ds_read_b128 v[22:25], v12 offset:23040
	ds_read_b128 v[26:29], v12 offset:25600
	ds_read_b128 v[30:33], v12 offset:28160
	s_setprio 1
	s_waitcnt lgkmcnt(3)
	v_mfma_f32_16x16x32_bf16 v[94:97], v[18:21], v[0:3], v[94:97]
	s_waitcnt lgkmcnt(2)
	v_mfma_f32_16x16x32_bf16 v[90:93], v[22:25], v[0:3], v[90:93]
	s_waitcnt lgkmcnt(1)
	v_mfma_f32_16x16x32_bf16 v[86:89], v[26:29], v[0:3], v[86:89]
	s_waitcnt lgkmcnt(0)
	v_mfma_f32_16x16x32_bf16 v[0:3], v[30:33], v[0:3], v[82:85]
	v_mfma_f32_16x16x32_bf16 v[78:81], v[18:21], v[4:7], v[78:81]
	v_mfma_f32_16x16x32_bf16 v[74:77], v[22:25], v[4:7], v[74:77]
	v_mfma_f32_16x16x32_bf16 v[70:73], v[26:29], v[4:7], v[70:73]
	v_mfma_f32_16x16x32_bf16 v[4:7], v[30:33], v[4:7], v[66:69]
	v_mfma_f32_16x16x32_bf16 v[62:65], v[18:21], v[8:11], v[62:65]
	v_mfma_f32_16x16x32_bf16 v[58:61], v[22:25], v[8:11], v[58:61]
	v_mfma_f32_16x16x32_bf16 v[54:57], v[26:29], v[8:11], v[54:57]
	v_mfma_f32_16x16x32_bf16 v[8:11], v[30:33], v[8:11], v[50:53]
	v_mfma_f32_16x16x32_bf16 v[50:53], v[18:21], v[14:17], v[46:49]
	v_mfma_f32_16x16x32_bf16 v[66:69], v[22:25], v[14:17], v[42:45]
	v_mfma_f32_16x16x32_bf16 v[82:85], v[26:29], v[14:17], v[38:41]
	v_mfma_f32_16x16x32_bf16 v[100:103], v[30:33], v[14:17], v[34:37]
	s_setprio 0
	ds_read_b128 v[14:17], v119 offset:64
	ds_read_b128 v[18:21], v119 offset:2624
	ds_read_b128 v[22:25], v119 offset:5184
	ds_read_b128 v[104:107], v119 offset:7744
	ds_read_b128 v[108:111], v12 offset:20544
	ds_read_b128 v[112:115], v12 offset:23104
	ds_read_b128 v[120:123], v12 offset:25664
	ds_read_b128 v[124:127], v12 offset:28224
	s_setprio 1
	s_waitcnt lgkmcnt(3)
	v_mfma_f32_16x16x32_bf16 v[94:97], v[108:111], v[14:17], v[94:97]
	s_waitcnt lgkmcnt(2)
	v_mfma_f32_16x16x32_bf16 v[90:93], v[112:115], v[14:17], v[90:93]
	s_waitcnt lgkmcnt(1)
	v_mfma_f32_16x16x32_bf16 v[86:89], v[120:123], v[14:17], v[86:89]
	s_waitcnt lgkmcnt(0)
	v_mfma_f32_16x16x32_bf16 v[128:131], v[124:127], v[14:17], v[0:3]
	v_mfma_f32_16x16x32_bf16 v[42:45], v[108:111], v[18:21], v[78:81]
	v_mfma_f32_16x16x32_bf16 v[46:49], v[112:115], v[18:21], v[74:77]
	v_mfma_f32_16x16x32_bf16 v[34:37], v[120:123], v[18:21], v[70:73]
	v_mfma_f32_16x16x32_bf16 v[38:41], v[124:127], v[18:21], v[4:7]
	v_mfma_f32_16x16x32_bf16 v[26:29], v[108:111], v[22:25], v[62:65]
	v_mfma_f32_16x16x32_bf16 v[30:33], v[112:115], v[22:25], v[58:61]
	v_mfma_f32_16x16x32_bf16 v[18:21], v[120:123], v[22:25], v[54:57]
	v_mfma_f32_16x16x32_bf16 v[22:25], v[124:127], v[22:25], v[8:11]
	v_mfma_f32_16x16x32_bf16 v[8:11], v[108:111], v[104:107], v[50:53]
	v_mfma_f32_16x16x32_bf16 v[14:17], v[112:115], v[104:107], v[66:69]
	v_mfma_f32_16x16x32_bf16 v[0:3], v[120:123], v[104:107], v[82:85]
	v_mfma_f32_16x16x32_bf16 v[4:7], v[124:127], v[104:107], v[100:103]
	s_setprio 0
	v_ashrrev_i32_e32 v12, 1, v118
	v_and_b32_e32 v12, 0xffffffc0, v12
	v_lshl_add_u32 v12, s18, 7, v12
	v_and_or_b32 v50, v118, 15, v12
	v_and_b32_e32 v12, 0x70, v118
	v_or_b32_e32 v12, s2, v12
	v_ashrrev_i32_e32 v51, 31, v50
	v_lshlrev_b64 v[52:53], 12, v[50:51]
	v_lshlrev_b32_e32 v12, 2, v12
	v_or_b32_e32 v52, v52, v12
	v_lshl_add_u64 v[64:65], s[56:57], 0, v[52:53]
	v_lshl_add_u64 v[68:69], s[90:91], 0, v[52:53]
	global_load_dwordx4 v[52:55], v[64:65], off offset:48
	global_load_dwordx4 v[56:59], v[64:65], off offset:32
	global_load_dwordx4 v[60:63], v[64:65], off offset:16
	s_nop 0
	global_load_dwordx4 v[64:67], v[64:65], off
	v_mov_b32_e32 v70, v94
	v_mov_b32_e32 v71, v90
	v_mov_b32_e32 v90, v95
	s_add_i32 s39, s39, s62
	s_cmp_ge_i32 s39, s1
	s_waitcnt vmcnt(3)
	v_pk_mul_f32 v[52:53], v[52:53], s[88:89] op_sel_hi:[1,0]
	s_waitcnt vmcnt(2)
	v_pk_mul_f32 v[56:57], v[56:57], s[88:89] op_sel_hi:[1,0]
	s_waitcnt vmcnt(1)
	v_pk_mul_f32 v[60:61], v[60:61], s[88:89] op_sel_hi:[1,0]
	s_waitcnt vmcnt(0)
	v_pk_mul_f32 v[64:65], v[64:65], s[88:89] op_sel_hi:[1,0]
	v_pk_mul_f32 v[66:67], v[66:67], s[88:89] op_sel_hi:[1,0]
	v_pk_fma_f32 v[64:65], v[98:99], v[70:71], v[64:65]
	v_mov_b32_e32 v70, v86
	v_mov_b32_e32 v71, v128
	v_pk_fma_f32 v[66:67], v[98:99], v[70:71], v[66:67]
	v_mov_b32_e32 v70, v96
	v_mov_b32_e32 v71, v92
	v_mov_b32_e32 v92, v97
	v_pk_mul_f32 v[62:63], v[62:63], s[88:89] op_sel_hi:[1,0]
	v_mov_b32_e32 v128, v87
	v_pk_fma_f32 v[56:57], v[98:99], v[70:71], v[56:57]
	v_pk_mul_f32 v[58:59], v[58:59], s[88:89] op_sel_hi:[1,0]
	v_mov_b32_e32 v70, v88
	v_mov_b32_e32 v71, v130
	v_pk_fma_f32 v[52:53], v[98:99], v[92:93], v[52:53]
	v_pk_mul_f32 v[54:55], v[54:55], s[88:89] op_sel_hi:[1,0]
	v_mov_b32_e32 v130, v89
	v_pk_fma_f32 v[60:61], v[98:99], v[90:91], v[60:61]
	v_pk_fma_f32 v[62:63], v[98:99], v[128:129], v[62:63]
	v_pk_fma_f32 v[58:59], v[98:99], v[70:71], v[58:59]
	v_pk_fma_f32 v[54:55], v[98:99], v[130:131], v[54:55]
	global_store_dwordx4 v[68:69], v[64:67], off
	global_store_dwordx4 v[68:69], v[60:63], off offset:16
	global_store_dwordx4 v[68:69], v[56:59], off offset:32
	global_store_dwordx4 v[68:69], v[52:55], off offset:48
	v_mov_b32_e32 v70, v42
	v_mov_b32_e32 v71, v46
	v_or_b32_e32 v52, 16, v50
	v_ashrrev_i32_e32 v53, 31, v52
	v_lshlrev_b64 v[52:53], 12, v[52:53]
	v_or_b32_e32 v52, v52, v12
	v_lshl_add_u64 v[64:65], s[56:57], 0, v[52:53]
	v_lshl_add_u64 v[68:69], s[90:91], 0, v[52:53]
	global_load_dwordx4 v[52:55], v[64:65], off offset:48
	global_load_dwordx4 v[56:59], v[64:65], off offset:32
	global_load_dwordx4 v[60:63], v[64:65], off offset:16
	s_nop 0
	global_load_dwordx4 v[64:67], v[64:65], off
	v_mov_b32_e32 v46, v43
	s_waitcnt vmcnt(1)
; template <int NT>
; __device__ __forceinline__ void resid_tile(int tm, int col0, const bf16_t* A, int lda, int K, const bf16_t* W, const float* X, float* Y, float scale, bf16_t* sm) {
;     ...
;     for (int mt = 0; mt < 4; ++mt) {
;         const int row = tm * 128 + wr * 64 + mt * 16 + fr;
;         const int cbase = col0 + wc * 16 * NT + fq * 4 * NT;
;         const size_t o = (size_t)row * 1024 + cbase;
;         float v[4 * NT]; gather_cols<NT>(acc, mt, v);
;         float4 xv[NT];
; #pragma unroll
;         for (int q = 0; q < NT; ++q) xv[q] = *(const float4*)(X + o + 4 * q);
; #pragma unroll
;         for (int q = 0; q < NT; ++q)
;             *(float4*)(Y + o + 4 * q) = make_float4(ALPHA * xv[q].x + scale * v[4 * q], ALPHA * xv[q].y + scale * v[4 * q + 1],
;                                                     ALPHA * xv[q].z + scale * v[4 * q + 2], ALPHA * xv[q].w + scale * v[4 * q + 3]);
;     }
	v_pk_mul_f32 v[42:43], v[62:63], s[88:89] op_sel_hi:[1,0]
	s_waitcnt vmcnt(0)
	v_pk_mul_f32 v[64:65], v[64:65], s[88:89] op_sel_hi:[1,0]
	v_pk_mul_f32 v[66:67], v[66:67], s[88:89] op_sel_hi:[1,0]
	v_pk_fma_f32 v[64:65], v[98:99], v[70:71], v[64:65]
	v_mov_b32_e32 v71, v38
	v_mov_b32_e32 v38, v35
	v_mov_b32_e32 v70, v34
	v_pk_fma_f32 v[62:63], v[98:99], v[38:39], v[42:43]
	v_pk_mul_f32 v[34:35], v[56:57], s[88:89] op_sel_hi:[1,0]
	v_mov_b32_e32 v38, v44
	v_mov_b32_e32 v39, v48
	v_pk_fma_f32 v[56:57], v[98:99], v[38:39], v[34:35]
	v_pk_mul_f32 v[34:35], v[58:59], s[88:89] op_sel_hi:[1,0]
	v_mov_b32_e32 v38, v36
	v_mov_b32_e32 v39, v40
	v_pk_fma_f32 v[58:59], v[98:99], v[38:39], v[34:35]
	v_pk_mul_f32 v[34:35], v[52:53], s[88:89] op_sel_hi:[1,0]
	v_mov_b32_e32 v48, v45
	v_pk_fma_f32 v[66:67], v[98:99], v[70:71], v[66:67]
	v_pk_mul_f32 v[60:61], v[60:61], s[88:89] op_sel_hi:[1,0]
	v_pk_fma_f32 v[34:35], v[98:99], v[48:49], v[34:35]
	v_pk_mul_f32 v[38:39], v[54:55], s[88:89] op_sel_hi:[1,0]
	v_mov_b32_e32 v40, v37
	v_pk_fma_f32 v[60:61], v[98:99], v[46:47], v[60:61]
	v_pk_fma_f32 v[36:37], v[98:99], v[40:41], v[38:39]
	global_store_dwordx4 v[68:69], v[64:67], off
	global_store_dwordx4 v[68:69], v[60:63], off offset:16
	global_store_dwordx4 v[68:69], v[56:59], off offset:32
	global_store_dwordx4 v[68:69], v[34:37], off offset:48
	v_mov_b32_e32 v54, v26
	v_mov_b32_e32 v55, v30
	v_or_b32_e32 v34, 32, v50
	v_ashrrev_i32_e32 v35, 31, v34
	v_lshlrev_b64 v[34:35], 12, v[34:35]
	v_or_b32_e32 v34, v34, v12
	v_lshl_add_u64 v[46:47], s[56:57], 0, v[34:35]
	v_lshl_add_u64 v[52:53], s[90:91], 0, v[34:35]
	global_load_dwordx4 v[34:37], v[46:47], off offset:48
	global_load_dwordx4 v[38:41], v[46:47], off offset:32
	global_load_dwordx4 v[42:45], v[46:47], off offset:16
	s_nop 0
	global_load_dwordx4 v[46:49], v[46:47], off
	v_mov_b32_e32 v30, v27
	s_waitcnt vmcnt(1)
	v_pk_mul_f32 v[26:27], v[44:45], s[88:89] op_sel_hi:[1,0]
	s_waitcnt vmcnt(0)
	v_pk_mul_f32 v[46:47], v[46:47], s[88:89] op_sel_hi:[1,0]
	v_pk_mul_f32 v[48:49], v[48:49], s[88:89] op_sel_hi:[1,0]
	v_pk_fma_f32 v[46:47], v[98:99], v[54:55], v[46:47]
	v_mov_b32_e32 v55, v22
	v_mov_b32_e32 v22, v19
	v_mov_b32_e32 v54, v18
	v_pk_fma_f32 v[44:45], v[98:99], v[22:23], v[26:27]
	v_pk_mul_f32 v[18:19], v[38:39], s[88:89] op_sel_hi:[1,0]
	v_mov_b32_e32 v22, v28
	v_mov_b32_e32 v23, v32
	v_pk_fma_f32 v[38:39], v[98:99], v[22:23], v[18:19]
	v_pk_mul_f32 v[18:19], v[40:41], s[88:89] op_sel_hi:[1,0]
	v_mov_b32_e32 v22, v20
	v_mov_b32_e32 v23, v24
	v_pk_fma_f32 v[40:41], v[98:99], v[22:23], v[18:19]
	v_pk_mul_f32 v[18:19], v[34:35], s[88:89] op_sel_hi:[1,0]
	v_mov_b32_e32 v32, v29
	v_pk_fma_f32 v[48:49], v[98:99], v[54:55], v[48:49]
	v_pk_mul_f32 v[42:43], v[42:43], s[88:89] op_sel_hi:[1,0]
	v_pk_fma_f32 v[18:19], v[98:99], v[32:33], v[18:19]
	v_pk_mul_f32 v[22:23], v[36:37], s[88:89] op_sel_hi:[1,0]
	v_mov_b32_e32 v24, v21
	v_pk_fma_f32 v[42:43], v[98:99], v[30:31], v[42:43]
	v_pk_fma_f32 v[20:21], v[98:99], v[24:25], v[22:23]
	global_store_dwordx4 v[52:53], v[46:49], off
	global_store_dwordx4 v[52:53], v[42:45], off offset:16
	global_store_dwordx4 v[52:53], v[38:41], off offset:32
	global_store_dwordx4 v[52:53], v[18:21], off offset:48
	v_mov_b32_e32 v36, v8
	v_mov_b32_e32 v37, v14
	v_or_b32_e32 v18, 48, v50
	v_ashrrev_i32_e32 v19, 31, v18
	v_lshlrev_b64 v[18:19], 12, v[18:19]
	v_or_b32_e32 v18, v18, v12
	v_lshl_add_u64 v[30:31], s[56:57], 0, v[18:19]
	v_lshl_add_u64 v[34:35], s[90:91], 0, v[18:19]
	global_load_dwordx4 v[18:21], v[30:31], off offset:48
	global_load_dwordx4 v[22:25], v[30:31], off offset:32
	global_load_dwordx4 v[26:29], v[30:31], off offset:16
	s_nop 0
	global_load_dwordx4 v[30:33], v[30:31], off
	v_mov_b32_e32 v14, v9
	s_waitcnt vmcnt(1)
	v_pk_mul_f32 v[8:9], v[28:29], s[88:89] op_sel_hi:[1,0]
	s_waitcnt vmcnt(0)
	v_pk_mul_f32 v[30:31], v[30:31], s[88:89] op_sel_hi:[1,0]
	v_pk_mul_f32 v[32:33], v[32:33], s[88:89] op_sel_hi:[1,0]
	v_pk_fma_f32 v[30:31], v[98:99], v[36:37], v[30:31]
	v_mov_b32_e32 v37, v4
	v_mov_b32_e32 v4, v1
	v_mov_b32_e32 v36, v0
	v_pk_fma_f32 v[28:29], v[98:99], v[4:5], v[8:9]
	v_pk_mul_f32 v[0:1], v[22:23], s[88:89] op_sel_hi:[1,0]
	v_mov_b32_e32 v4, v10
	v_mov_b32_e32 v5, v16
	v_pk_fma_f32 v[22:23], v[98:99], v[4:5], v[0:1]
	v_pk_mul_f32 v[0:1], v[24:25], s[88:89] op_sel_hi:[1,0]
	v_mov_b32_e32 v4, v2
	v_mov_b32_e32 v5, v6
	v_pk_fma_f32 v[32:33], v[98:99], v[36:37], v[32:33]
	v_pk_mul_f32 v[26:27], v[26:27], s[88:89] op_sel_hi:[1,0]
	v_pk_fma_f32 v[24:25], v[98:99], v[4:5], v[0:1]
	v_pk_mul_f32 v[0:1], v[18:19], s[88:89] op_sel_hi:[1,0]
	v_mov_b32_e32 v16, v11
	v_pk_mul_f32 v[4:5], v[20:21], s[88:89] op_sel_hi:[1,0]
	v_mov_b32_e32 v6, v3
	v_pk_fma_f32 v[26:27], v[98:99], v[14:15], v[26:27]
	v_pk_fma_f32 v[0:1], v[98:99], v[16:17], v[0:1]
	v_pk_fma_f32 v[2:3], v[98:99], v[6:7], v[4:5]
	global_store_dwordx4 v[34:35], v[30:33], off
	global_store_dwordx4 v[34:35], v[26:29], off offset:16
	global_store_dwordx4 v[34:35], v[22:25], off offset:32
	global_store_dwordx4 v[34:35], v[0:3], off offset:48
	s_cbranch_scc0 .LBB0_35

; __device__ __forceinline__ int tidx() { int t = threadIdx.x; asm volatile("" : "+v"(t)); return t; }
; __device__ __forceinline__ void gate_tile(int t, const bf16_t* xb, const bf16_t* Wg, bf16_t* G, bf16_t* sm) {
;     const int tid_ = tidx();
;     const int lane = tid_ & 63, wid = tid_ >> 6, wr = wid >> 1, wc = wid & 1, fr = lane & 15, fq = lane >> 4;
;     const int tm = t >> 5, tn = t & 31;
;     f32x4 acc[4][4]; zero_acc<4>(acc);
;     gemm_tile<4>(acc, xb + (size_t)tm * 128 * 1024, 1024, Wg + (size_t)tn * 128 * 1024, 1024, 1024, sm);
; __device__ __forceinline__ void phase_scan(KP p, int l, unsigned char* smem) {
;     ...
;         const int t = s_q;
;         const int NGT = 136 * 32, NAT = 1152, NMV = 256;
;         if (t >= NGT + NAT + NMV) break;
;         if (t < NMV) misc_vblock(p, l, t, NMV);
;         else if (t < NMV + NAT) attn_block_task(p, l, t - NMV);
;         else gate_tile(t - NMV - NAT, (const bf16_t*)(p->ws + OFF_XB), (const bf16_t*)(p->ws + OFF_WG), (bf16_t*)(p->ws + OFF_G), (bf16_t*)smem);
.Lq_xcd:
	s_cmpk_lt_u32 s74, 0x220
	s_cbranch_scc0 .LBB0_169
	s_lshr_b32 s14, s2, 2
	s_add_i32 s14, s14, -1
	s_mul_i32 s15, s74, 0x1e2
	s_lshr_b32 s15, s15, 16
	s_mul_i32 s18, s15, 0x88
	s_sub_i32 s18, s74, s18
	s_lshr_b32 s19, s18, 3
	s_and_b32 s18, s18, 7
	s_mul_i32 s14, s14, 17
	s_add_i32 s14, s14, s19
	s_lshl_b32 s15, s15, 3
	s_add_i32 s15, s15, s18
	s_lshl_b32 s14, s14, 5
	s_add_i32 s74, s14, s15
	s_addk_i32 s74, 0x580
	v_mov_b32_e32 v12, v192
	v_mov_b32_e32 v40, v192
	s_add_i32 s2, s74, 0xfffffa80
	v_ashrrev_i32_e32 v0, 31, v40
	s_waitcnt vmcnt(6)
	v_ashrrev_i32_e32 v30, 3, v40
	v_lshrrev_b32_e32 v0, 26, v0
	v_add_u32_e32 v0, v30, v0
	v_lshrrev_b32_e32 v1, 6, v0
	v_mul_i32_i24_e32 v1, 64, v1
	v_sub_u32_e32 v1, v30, v1
	v_lshrrev_b16_sdwa v2, v196, sext(v1) dst_sel:DWORD dst_unused:UNUSED_PAD src0_sel:DWORD src1_sel:BYTE_0
	v_and_b32_e32 v2, 3, v2
	v_add_u16_e32 v2, v1, v2
	v_ashrrev_i16_sdwa v3, v197, sext(v2) dst_sel:DWORD dst_unused:UNUSED_PAD src0_sel:DWORD src1_sel:BYTE_0
	v_and_b32_e32 v2, 0xfc, v2
	v_sub_u16_e32 v1, v1, v2
	v_and_b32_e32 v0, 0x7ffffc0, v0
	v_lshlrev_b32_sdwa v1, v198, sext(v1) dst_sel:DWORD dst_unused:UNUSED_PAD src0_sel:DWORD src1_sel:BYTE_0
	v_bfe_i32 v2, v3, 0, 16
	v_add3_u32 v41, v0, v2, v1
	v_add_u32_e32 v0, 32, v30
	v_ashrrev_i32_e32 v1, 31, v0
	v_lshrrev_b32_e32 v1, 26, v1
	v_add_u32_e32 v1, v0, v1
	v_lshrrev_b32_e32 v2, 6, v1
	v_mul_i32_i24_e32 v2, 64, v2
	v_sub_u32_e32 v0, v0, v2
	v_lshrrev_b16_sdwa v2, v196, sext(v0) dst_sel:DWORD dst_unused:UNUSED_PAD src0_sel:DWORD src1_sel:BYTE_0
	v_and_b32_e32 v2, 3, v2
	v_add_u16_e32 v2, v0, v2
	v_ashrrev_i16_sdwa v3, v197, sext(v2) dst_sel:DWORD dst_unused:UNUSED_PAD src0_sel:DWORD src1_sel:BYTE_0
	v_and_b32_e32 v2, 0xfc, v2
	v_sub_u16_e32 v0, v0, v2
	v_and_b32_e32 v1, 0x7ffffc0, v1
	v_lshlrev_b32_sdwa v0, v198, sext(v0) dst_sel:DWORD dst_unused:UNUSED_PAD src0_sel:DWORD src1_sel:BYTE_0
	v_bfe_i32 v2, v3, 0, 16
	v_add3_u32 v42, v1, v2, v0
	v_add_u32_e32 v0, 64, v30
	v_ashrrev_i32_e32 v1, 31, v0
	v_lshrrev_b32_e32 v1, 26, v1
	v_add_u32_e32 v1, v0, v1
	v_lshrrev_b32_e32 v2, 6, v1
	v_mul_i32_i24_e32 v2, 64, v2
	v_sub_u32_e32 v0, v0, v2
	v_lshrrev_b16_sdwa v2, v196, sext(v0) dst_sel:DWORD dst_unused:UNUSED_PAD src0_sel:DWORD src1_sel:BYTE_0
	v_and_b32_e32 v2, 3, v2
	v_add_u16_e32 v2, v0, v2
	v_ashrrev_i16_sdwa v3, v197, sext(v2) dst_sel:DWORD dst_unused:UNUSED_PAD src0_sel:DWORD src1_sel:BYTE_0
	v_and_b32_e32 v2, 0xfc, v2
	v_sub_u16_e32 v0, v0, v2
	v_and_b32_e32 v1, 0x7ffffc0, v1
	v_lshlrev_b32_sdwa v0, v198, sext(v0) dst_sel:DWORD dst_unused:UNUSED_PAD src0_sel:DWORD src1_sel:BYTE_0
	v_bfe_i32 v2, v3, 0, 16
	v_add3_u32 v43, v1, v2, v0
	v_add_u32_e32 v0, 0x60, v30
	v_ashrrev_i32_e32 v1, 31, v0
	v_lshrrev_b32_e32 v1, 26, v1
	v_add_u32_e32 v1, v0, v1
	v_lshrrev_b32_e32 v2, 6, v1
	v_mul_i32_i24_e32 v2, 64, v2
	v_sub_u32_e32 v0, v0, v2
	s_lshr_b32 s13, s2, 5
	v_lshrrev_b16_sdwa v2, v196, sext(v0) dst_sel:DWORD dst_unused:UNUSED_PAD src0_sel:DWORD src1_sel:BYTE_0
	s_lshl_b32 s86, s13, 17
	v_and_b32_e32 v2, 3, v2
	s_and_b32 s12, s74, 31
	s_lshl_b64 s[14:15], s[86:87], 1
	v_add_u16_e32 v2, v0, v2
	s_add_u32 s18, s80, s14
	v_ashrrev_i16_sdwa v3, v197, sext(v2) dst_sel:DWORD dst_unused:UNUSED_PAD src0_sel:DWORD src1_sel:BYTE_0
	v_and_b32_e32 v2, 0xfc, v2
	s_addc_u32 s19, s81, s15
	s_lshl_b32 s2, s12, 18
	v_sub_u16_e32 v0, v0, v2
	s_add_u32 s22, s11, s2
	v_and_b32_e32 v1, 0x7ffffc0, v1
	v_lshlrev_b32_sdwa v0, v198, sext(v0) dst_sel:DWORD dst_unused:UNUSED_PAD src0_sel:DWORD src1_sel:BYTE_0
	v_bfe_i32 v2, v3, 0, 16
	v_ashrrev_i32_e32 v31, 31, v30
	s_addc_u32 s23, s39, 0
	v_add3_u32 v44, v1, v2, v0
	v_lshlrev_b64 v[32:33], 11, v[30:31]
	v_lshlrev_b32_e32 v2, 4, v40
	v_lshl_add_u64 v[0:1], s[22:23], 0, v[32:33]
	v_and_b32_e32 v38, 0x70, v2
	v_mov_b32_e32 v39, v13
	v_lshl_add_u64 v[8:9], v[0:1], 0, v[38:39]
	v_add_co_u32_e32 v0, vcc, s7, v8
	v_mul_lo_u32 v46, v30, s89
	s_nop 0
	v_addc_co_u32_e32 v1, vcc, 0, v9, vcc
	v_add_co_u32_e32 v10, vcc, s37, v8
	v_mov_b32_e32 v250, v8
	v_mov_b32_e32 v251, v9
	s_nop 0
	v_addc_co_u32_e32 v11, vcc, 0, v9, vcc
	v_add_co_u32_e32 v14, vcc, s73, v8
	v_and_b32_e32 v30, 7, v40
	s_nop 0
	v_addc_co_u32_e32 v15, vcc, 0, v9, vcc
	s_nop 0
	v_lshl_add_u64 v[14:15], s[18:19], 0, v[32:33]
	v_lshl_add_u64 v[26:27], v[14:15], 0, v[38:39]
	v_add_co_u32_e32 v14, vcc, s7, v26
	s_add_u32 s14, s58, s14
	s_nop 0
	v_addc_co_u32_e32 v15, vcc, 0, v27, vcc
	v_add_co_u32_e32 v28, vcc, s37, v26
	v_mov_b32_e32 v248, v26
	v_mov_b32_e32 v249, v27
	s_nop 0
	v_addc_co_u32_e32 v29, vcc, 0, v27, vcc
	v_add_co_u32_e32 v34, vcc, s73, v26
	v_and_b32_e32 v31, 15, v40
	s_nop 0
	v_addc_co_u32_e32 v35, vcc, 0, v27, vcc
	s_nop 0
	v_lshrrev_b32_e32 v39, 1, v40
	v_lshl_or_b32 v32, v30, 4, v32
	s_addc_u32 s15, s59, s15
	v_and_or_b32 v31, v39, s3, v31
	v_and_b32_e32 v39, 0x4f, v40
	v_lshl_add_u64 v[98:99], s[14:15], 0, v[32:33]
	s_add_u32 s14, s58, s2
	v_and_b32_e32 v45, 48, v40
	v_mul_lo_u32 v31, v31, s89
	v_mul_u32_u24_e32 v39, 0xa0, v39
	v_mul_lo_u32 v41, v41, s89
	v_mul_lo_u32 v42, v42, s89
	v_mul_lo_u32 v43, v43, s89
	v_mul_lo_u32 v44, v44, s89
	s_addc_u32 s15, s59, 0
	v_mov_b32_e32 v30, 0
	v_lshl_add_u64 v[100:101], s[14:15], 0, v[32:33]
	s_mov_b64 s[14:15], 0
	v_add_u32_e32 v104, v38, v46
	v_add_u32_e32 v105, v38, v41
	v_add_u32_e32 v106, v38, v42
	v_add_u32_e32 v107, v38, v43
	v_add_u32_e32 v108, v38, v44
	v_add_u32_e32 v103, v45, v31
	v_add_u32_e32 v102, v45, v39
	v_mov_b32_e32 v31, v30
	v_mov_b32_e32 v32, v30
	v_mov_b32_e32 v33, v30
	v_mov_b32_e32 v38, v30
	v_mov_b32_e32 v39, v30
	v_mov_b32_e32 v40, v30
	v_mov_b32_e32 v41, v30
	v_mov_b32_e32 v42, v30
	v_mov_b32_e32 v43, v30
; __device__ __forceinline__ int tidx() { int t = threadIdx.x; asm volatile("" : "+v"(t)); return t; }
; template <int NT>
; __device__ __forceinline__ void gemm_tile(f32x4 (&acc)[4][NT], const bf16_t* A, int lda, const bf16_t* B, int ldb, int K, bf16_t* sm) {
;     const int tid_ = tidx();
;     bf16_t* sA = sm; bf16_t* sB = sm + 128 * LDT;
;     const int tid = tid_, lane = tid & 63, wid = tid >> 6, wr = wid >> 1, wc = wid & 1;
;     const int fr = lane & 15, fq = lane >> 4;
;     const int lrow = tid >> 3, lkc = tid & 7;
;     const bf16_t* ga = A + (size_t)lrow * lda + lkc * 8;
;     const bf16_t* gb = B + (size_t)lrow * ldb + lkc * 8;
;     int sbrow[NT];
; #pragma unroll
;     for (int i = 0; i < NT; ++i) { const int g = lrow + 32 * i, W_ = 16 * NT, rem = g % W_; sbrow[i] = (g / W_) * W_ + (rem % NT) * 16 + rem / NT; }
;     u32x4 ra0[4], rb0[NT];
; #pragma unroll
;     for (int i = 0; i < 4; ++i) ra0[i] = *(const u32x4*)(ga + (size_t)(32 * i) * lda);
; #pragma unroll
;     for (int i = 0; i < NT; ++i) rb0[i] = *(const u32x4*)(gb + (size_t)(32 * i) * ldb);
;     const int nk = K >> 6;
;     for (int kt = 0; kt < nk; ++kt) {
;         lds_barrier();
; #pragma unroll
;         for (int i = 0; i < 4; ++i) *(u32x4*)(sA + (lrow + 32 * i) * LDT + lkc * 8) = ra0[i];
; #pragma unroll
;         for (int i = 0; i < NT; ++i) *(u32x4*)(sB + sbrow[i] * LDT + lkc * 8) = rb0[i];
;         lds_barrier();
	v_mov_b32_e32 v44, v30
	v_mov_b32_e32 v45, v30
	v_mov_b32_e32 v46, v30
	v_mov_b32_e32 v47, v30
	v_mov_b32_e32 v48, v30
	v_mov_b32_e32 v49, v30
	v_mov_b32_e32 v50, v30
	v_mov_b32_e32 v51, v30
	v_mov_b32_e32 v52, v30
	v_mov_b32_e32 v53, v30
	v_mov_b32_e32 v54, v30
	v_mov_b32_e32 v55, v30
	v_mov_b32_e32 v56, v30
	v_mov_b32_e32 v57, v30
	v_mov_b32_e32 v58, v30
	v_mov_b32_e32 v59, v30
	v_mov_b32_e32 v60, v30
	v_mov_b32_e32 v61, v30
	v_mov_b32_e32 v62, v30
	v_mov_b32_e32 v63, v30
	v_mov_b32_e32 v64, v30
	v_mov_b32_e32 v65, v30
	v_mov_b32_e32 v66, v30
	v_mov_b32_e32 v67, v30
	v_mov_b32_e32 v68, v30
	v_mov_b32_e32 v69, v30
	v_mov_b32_e32 v70, v30
	v_mov_b32_e32 v71, v30
	v_mov_b32_e32 v72, v30
	v_mov_b32_e32 v73, v30
	v_mov_b32_e32 v74, v30
	v_mov_b32_e32 v75, v30
	v_mov_b32_e32 v76, v30
	v_mov_b32_e32 v77, v30
	v_mov_b32_e32 v78, v30
	v_mov_b32_e32 v79, v30
	v_mov_b32_e32 v80, v30
	v_mov_b32_e32 v81, v30
	v_mov_b32_e32 v82, v30
	v_mov_b32_e32 v83, v30
	v_mov_b32_e32 v84, v30
	v_mov_b32_e32 v85, v30
	v_mov_b32_e32 v86, v30
	v_mov_b32_e32 v87, v30
	v_mov_b32_e32 v88, v30
	v_mov_b32_e32 v89, v30
	v_mov_b32_e32 v90, v30
	v_mov_b32_e32 v91, v30
	v_mov_b32_e32 v92, v30
	v_mov_b32_e32 v93, v30
	v_mov_b32_e32 v94, v30
	v_mov_b32_e32 v95, v30
	v_mov_b32_e32 v96, v30
	v_mov_b32_e32 v97, v30
	v_writelane_b32 v234, s90, 0
	v_writelane_b32 v234, s91, 1
	v_writelane_b32 v234, s92, 2
	v_writelane_b32 v234, s93, 3
	v_writelane_b32 v234, s94, 4
	v_writelane_b32 v234, s95, 5
	v_bfe_u32 v160, v192, 3, 3
	v_and_b32_e32 v161, 7, v192
	v_xor_b32_e32 v161, v160, v161
	v_lshlrev_b32_e32 v161, 4, v161
	v_lshrrev_b32_e32 v162, 6, v192
	v_lshl_add_u32 v163, v162, 5, v160
	v_mul_u32_u24_e32 v163, 0x800, v163
	v_add_u32_e32 v236, v163, v161
	v_add_u32_e32 v237, 0x3c00, v236
	v_add_u32_e32 v238, 0x3c00, v237
	v_add_u32_e32 v239, 0x3c00, v238
	v_lshrrev_b32_e32 v163, 7, v192
	v_bfe_u32 v162, v192, 6, 1
	v_lshlrev_b32_e32 v163, 6, v163
	v_lshl_add_u32 v163, v160, 2, v163
	v_lshl_add_u32 v163, v162, 1, v163
	v_mul_u32_u24_e32 v163, 0x800, v163
	v_add_u32_e32 v240, v163, v161
	v_add_u32_e32 v241, 0xfc00, v240
	v_subrev_u32_e32 v242, 0xfc00, v241
	v_add_u32_e32 v243, 0xfc00, v242
	v_and_b32_e32 v160, 15, v192
	v_bfe_u32 v161, v192, 4, 2
	v_and_b32_e32 v162, 7, v160
	v_xor_b32_e32 v161, v161, v162
	v_lshlrev_b32_e32 v161, 4, v161
	v_lshl_add_u32 v161, v160, 7, v161
	v_lshrrev_b32_e32 v162, 7, v192
	v_lshl_add_u32 v244, v162, 13, v161
	v_bfe_u32 v162, v192, 6, 1
	v_lshl_add_u32 v246, v162, 13, v161
	v_add_u32_e32 v246, 0x4000, v246
	v_xor_b32_e32 v245, 64, v244
	v_xor_b32_e32 v247, 64, v246
	v_lshrrev_b32_e32 v160, 6, v192
	s_nop 0
	v_readfirstlane_b32 s94, v160
	v_readfirstlane_b32 s90, v248
	v_readfirstlane_b32 s91, v249
	v_readfirstlane_b32 s92, v250
	v_readfirstlane_b32 s93, v251
	s_mul_i32 s95, s94, 0x4000
	s_sub_u32 s90, s90, s95
	s_subb_u32 s91, s91, 0
	s_mul_i32 s95, s94, 0x4000
	s_sub_u32 s92, s92, s95
	s_subb_u32 s93, s93, 0
	s_lshl_b32 s94, s94, 10
	s_waitcnt lgkmcnt(0)
	s_barrier
	s_lshl_b32 s95, s94, 2
	s_add_u32 m0, s95, 0x0
	s_nop 0
	global_load_lds_dwordx4 v236, s[90:91] sc1
	global_load_lds_dwordx4 v237, s[90:91] offset:1024 sc1
	global_load_lds_dwordx4 v238, s[90:91] offset:2048 sc1
	global_load_lds_dwordx4 v239, s[90:91] offset:3072 sc1
	s_mul_i32 s95, s94, 4
	s_add_u32 m0, s95, 0x4000
	s_nop 0
	global_load_lds_dwordx4 v240, s[92:93]
	global_load_lds_dwordx4 v241, s[92:93] offset:1024
	global_load_lds_dwordx4 v242, s[92:93] offset:2048
	global_load_lds_dwordx4 v243, s[92:93] offset:3072
	s_add_u32 s90, s90, 0x80
	s_addc_u32 s91, s91, 0
	s_add_u32 s92, s92, 0x80
	s_addc_u32 s93, s93, 0
	s_waitcnt vmcnt(0)
	s_barrier
	s_lshl_b32 s95, s94, 2
	s_add_u32 m0, s95, 0x8000
	s_nop 0
	global_load_lds_dwordx4 v236, s[90:91] sc1
	global_load_lds_dwordx4 v237, s[90:91] offset:1024 sc1
	global_load_lds_dwordx4 v238, s[90:91] offset:2048 sc1
	global_load_lds_dwordx4 v239, s[90:91] offset:3072 sc1
	s_mul_i32 s95, s94, 4
	s_add_u32 m0, s95, 0xc000
	s_nop 0
	global_load_lds_dwordx4 v240, s[92:93]
	global_load_lds_dwordx4 v241, s[92:93] offset:1024
	global_load_lds_dwordx4 v242, s[92:93] offset:2048
	global_load_lds_dwordx4 v243, s[92:93] offset:3072
	s_add_u32 s90, s90, 0x80
	s_addc_u32 s91, s91, 0
	s_add_u32 s92, s92, 0x80
	s_addc_u32 s93, s93, 0
	ds_read_b128 v[110:113], v244 offset:0
	ds_read_b128 v[114:117], v244 offset:2048
	ds_read_b128 v[118:121], v244 offset:4096
	ds_read_b128 v[122:125], v244 offset:6144
	ds_read_b128 v[126:129], v246 offset:0
	ds_read_b128 v[130:133], v246 offset:2048
	ds_read_b128 v[134:137], v246 offset:4096
	ds_read_b128 v[138:141], v246 offset:6144
	s_movk_i32 s95, 0x6
	s_cmp_eq_u32 s95, 0
	s_cbranch_scc1 .Lgemm_x178
; template <int NT>
; __device__ __forceinline__ void gemm_compute(f32x4 (&acc)[4][NT], const bf16_t* sA, const bf16_t* sB, int wr, int wc, int fr, int fq) {
; #pragma unroll
;     for (int ks = 0; ks < 2; ++ks) {
;         bf16x8 a[4], b[NT];
; #pragma unroll
;         for (int mt = 0; mt < 4; ++mt) a[mt] = *(const bf16x8*)(sA + (wr * 64 + mt * 16 + fr) * LDT + ks * 32 + fq * 8);
; #pragma unroll
;         for (int nt = 0; nt < NT; ++nt) b[nt] = *(const bf16x8*)(sB + (wc * 16 * NT + nt * 16 + fr) * LDT + ks * 32 + fq * 8);
;         __builtin_amdgcn_s_setprio(1);
; #pragma unroll
;         for (int mt = 0; mt < 4; ++mt)
; #pragma unroll
;             for (int nt = 0; nt < NT; ++nt)
;                 acc[mt][nt] = __builtin_amdgcn_mfma_f32_16x16x32_bf16(b[nt], a[mt], acc[mt][nt], 0, 0, 0);
;         __builtin_amdgcn_s_setprio(0);
;     }
; template <int NT>
; __device__ __forceinline__ void gemm_tile(f32x4 (&acc)[4][NT], const bf16_t* A, int lda, const bf16_t* B, int ldb, int K, bf16_t* sm) {
;     ...
;     for (int kt = 0; kt < nk; ++kt) {
;         lds_barrier();
; #pragma unroll
;         for (int i = 0; i < 4; ++i) *(u32x4*)(sA + (lrow + 32 * i) * LDT + lkc * 8) = ra0[i];
; #pragma unroll
;         for (int i = 0; i < NT; ++i) *(u32x4*)(sB + sbrow[i] * LDT + lkc * 8) = rb0[i];
;         lds_barrier();
;         if (kt + 1 < nk) {
;             ga += 64; gb += 64;
; #pragma unroll
;             for (int i = 0; i < 4; ++i) ra0[i] = *(const u32x4*)(ga + (size_t)(32 * i) * lda);
; #pragma unroll
;             for (int i = 0; i < NT; ++i) rb0[i] = *(const u32x4*)(gb + (size_t)(32 * i) * ldb);
;         }
;         __builtin_amdgcn_sched_barrier(0);
;         gemm_compute<NT>(acc, sA, sB, wr, wc, fr, fq);
.Lgemm_k178:
	v_writelane_b32 v234, s95, 6
	ds_read_b128 v[160:163], v245 offset:0
	ds_read_b128 v[164:167], v245 offset:2048
	ds_read_b128 v[168:171], v245 offset:4096
	ds_read_b128 v[172:175], v245 offset:6144
	ds_read_b128 v[176:179], v247 offset:0
	ds_read_b128 v[180:183], v247 offset:2048
	ds_read_b128 v[184:187], v247 offset:4096
	ds_read_b128 v[188:191], v247 offset:6144
	s_setprio 1
	s_waitcnt lgkmcnt(11)
	v_mfma_f32_16x16x32_bf16 v[94:97], v[126:129], v[110:113], v[94:97]
	s_waitcnt lgkmcnt(10)
	v_mfma_f32_16x16x32_bf16 v[90:93], v[130:133], v[110:113], v[90:93]
	s_waitcnt lgkmcnt(9)
	v_mfma_f32_16x16x32_bf16 v[86:89], v[134:137], v[110:113], v[86:89]
	s_waitcnt lgkmcnt(8)
	v_mfma_f32_16x16x32_bf16 v[82:85], v[138:141], v[110:113], v[82:85]
	v_mfma_f32_16x16x32_bf16 v[78:81], v[126:129], v[114:117], v[78:81]
	v_mfma_f32_16x16x32_bf16 v[74:77], v[130:133], v[114:117], v[74:77]
	v_mfma_f32_16x16x32_bf16 v[70:73], v[134:137], v[114:117], v[70:73]
	v_mfma_f32_16x16x32_bf16 v[66:69], v[138:141], v[114:117], v[66:69]
	v_mfma_f32_16x16x32_bf16 v[62:65], v[126:129], v[118:121], v[62:65]
	v_mfma_f32_16x16x32_bf16 v[58:61], v[130:133], v[118:121], v[58:61]
	v_mfma_f32_16x16x32_bf16 v[54:57], v[134:137], v[118:121], v[54:57]
	v_mfma_f32_16x16x32_bf16 v[50:53], v[138:141], v[118:121], v[50:53]
	v_mfma_f32_16x16x32_bf16 v[46:49], v[126:129], v[122:125], v[46:49]
	v_mfma_f32_16x16x32_bf16 v[42:45], v[130:133], v[122:125], v[42:45]
	v_mfma_f32_16x16x32_bf16 v[38:41], v[134:137], v[122:125], v[38:41]
	v_mfma_f32_16x16x32_bf16 v[30:33], v[138:141], v[122:125], v[30:33]
	s_setprio 0
	s_waitcnt vmcnt(0) lgkmcnt(0)
	s_barrier
	ds_read_b128 v[110:113], v244 offset:32768
	ds_read_b128 v[114:117], v244 offset:34816
	ds_read_b128 v[118:121], v244 offset:36864
	ds_read_b128 v[122:125], v244 offset:38912
	ds_read_b128 v[126:129], v246 offset:32768
	ds_read_b128 v[130:133], v246 offset:34816
	ds_read_b128 v[134:137], v246 offset:36864
	ds_read_b128 v[138:141], v246 offset:38912
	s_setprio 1
	v_mfma_f32_16x16x32_bf16 v[94:97], v[176:179], v[160:163], v[94:97]
	s_lshl_b32 s95, s94, 2
	s_add_u32 m0, s95, 0x0
	s_nop 0
	global_load_lds_dwordx4 v236, s[90:91] sc1
	v_mfma_f32_16x16x32_bf16 v[90:93], v[180:183], v[160:163], v[90:93]
	v_mfma_f32_16x16x32_bf16 v[86:89], v[184:187], v[160:163], v[86:89]
	global_load_lds_dwordx4 v237, s[90:91] offset:1024 sc1
	v_mfma_f32_16x16x32_bf16 v[82:85], v[188:191], v[160:163], v[82:85]
	v_mfma_f32_16x16x32_bf16 v[78:81], v[176:179], v[164:167], v[78:81]
	global_load_lds_dwordx4 v238, s[90:91] offset:2048 sc1
	v_mfma_f32_16x16x32_bf16 v[74:77], v[180:183], v[164:167], v[74:77]
	v_mfma_f32_16x16x32_bf16 v[70:73], v[184:187], v[164:167], v[70:73]
	global_load_lds_dwordx4 v239, s[90:91] offset:3072 sc1
	v_mfma_f32_16x16x32_bf16 v[66:69], v[188:191], v[164:167], v[66:69]
	v_mfma_f32_16x16x32_bf16 v[62:65], v[176:179], v[168:171], v[62:65]
	s_mul_i32 s95, s94, 4
	s_add_u32 m0, s95, 0x4000
	s_nop 0
	global_load_lds_dwordx4 v240, s[92:93]
	v_mfma_f32_16x16x32_bf16 v[58:61], v[180:183], v[168:171], v[58:61]
	v_mfma_f32_16x16x32_bf16 v[54:57], v[184:187], v[168:171], v[54:57]
	global_load_lds_dwordx4 v241, s[92:93] offset:1024
	v_mfma_f32_16x16x32_bf16 v[50:53], v[188:191], v[168:171], v[50:53]
	v_mfma_f32_16x16x32_bf16 v[46:49], v[176:179], v[172:175], v[46:49]
	global_load_lds_dwordx4 v242, s[92:93] offset:2048
	v_mfma_f32_16x16x32_bf16 v[42:45], v[180:183], v[172:175], v[42:45]
	v_mfma_f32_16x16x32_bf16 v[38:41], v[184:187], v[172:175], v[38:41]
	global_load_lds_dwordx4 v243, s[92:93] offset:3072
	v_mfma_f32_16x16x32_bf16 v[30:33], v[188:191], v[172:175], v[30:33]
	s_add_u32 s90, s90, 0x80
	s_addc_u32 s91, s91, 0
	s_add_u32 s92, s92, 0x80
	s_addc_u32 s93, s93, 0
	s_setprio 0
	ds_read_b128 v[160:163], v245 offset:32768
	ds_read_b128 v[164:167], v245 offset:34816
	ds_read_b128 v[168:171], v245 offset:36864
	ds_read_b128 v[172:175], v245 offset:38912
	ds_read_b128 v[176:179], v247 offset:32768
	ds_read_b128 v[180:183], v247 offset:34816
	ds_read_b128 v[184:187], v247 offset:36864
	ds_read_b128 v[188:191], v247 offset:38912
	s_setprio 1
	s_waitcnt lgkmcnt(11)
	v_mfma_f32_16x16x32_bf16 v[94:97], v[126:129], v[110:113], v[94:97]
	s_waitcnt lgkmcnt(10)
	v_mfma_f32_16x16x32_bf16 v[90:93], v[130:133], v[110:113], v[90:93]
	s_waitcnt lgkmcnt(9)
	v_mfma_f32_16x16x32_bf16 v[86:89], v[134:137], v[110:113], v[86:89]
	s_waitcnt lgkmcnt(8)
	v_mfma_f32_16x16x32_bf16 v[82:85], v[138:141], v[110:113], v[82:85]
	v_mfma_f32_16x16x32_bf16 v[78:81], v[126:129], v[114:117], v[78:81]
	v_mfma_f32_16x16x32_bf16 v[74:77], v[130:133], v[114:117], v[74:77]
	v_mfma_f32_16x16x32_bf16 v[70:73], v[134:137], v[114:117], v[70:73]
	v_mfma_f32_16x16x32_bf16 v[66:69], v[138:141], v[114:117], v[66:69]
	v_mfma_f32_16x16x32_bf16 v[62:65], v[126:129], v[118:121], v[62:65]
	v_mfma_f32_16x16x32_bf16 v[58:61], v[130:133], v[118:121], v[58:61]
	v_mfma_f32_16x16x32_bf16 v[54:57], v[134:137], v[118:121], v[54:57]
	v_mfma_f32_16x16x32_bf16 v[50:53], v[138:141], v[118:121], v[50:53]
	v_mfma_f32_16x16x32_bf16 v[46:49], v[126:129], v[122:125], v[46:49]
	v_mfma_f32_16x16x32_bf16 v[42:45], v[130:133], v[122:125], v[42:45]
	v_mfma_f32_16x16x32_bf16 v[38:41], v[134:137], v[122:125], v[38:41]
	v_mfma_f32_16x16x32_bf16 v[30:33], v[138:141], v[122:125], v[30:33]
	s_setprio 0
	s_waitcnt vmcnt(0) lgkmcnt(0)
	s_barrier
; template <int NT>
; __device__ __forceinline__ void gemm_compute(f32x4 (&acc)[4][NT], const bf16_t* sA, const bf16_t* sB, int wr, int wc, int fr, int fq) {
; #pragma unroll
;     for (int ks = 0; ks < 2; ++ks) {
;         bf16x8 a[4], b[NT];
; #pragma unroll
;         for (int mt = 0; mt < 4; ++mt) a[mt] = *(const bf16x8*)(sA + (wr * 64 + mt * 16 + fr) * LDT + ks * 32 + fq * 8);
; #pragma unroll
;         for (int nt = 0; nt < NT; ++nt) b[nt] = *(const bf16x8*)(sB + (wc * 16 * NT + nt * 16 + fr) * LDT + ks * 32 + fq * 8);
;         __builtin_amdgcn_s_setprio(1);
; #pragma unroll
;         for (int mt = 0; mt < 4; ++mt)
; #pragma unroll
;             for (int nt = 0; nt < NT; ++nt)
;                 acc[mt][nt] = __builtin_amdgcn_mfma_f32_16x16x32_bf16(b[nt], a[mt], acc[mt][nt], 0, 0, 0);
;         __builtin_amdgcn_s_setprio(0);
;     }
; template <int NT>
; __device__ __forceinline__ void gemm_tile(f32x4 (&acc)[4][NT], const bf16_t* A, int lda, const bf16_t* B, int ldb, int K, bf16_t* sm) {
;     ...
;     for (int kt = 0; kt < nk; ++kt) {
;         lds_barrier();
; #pragma unroll
;         for (int i = 0; i < 4; ++i) *(u32x4*)(sA + (lrow + 32 * i) * LDT + lkc * 8) = ra0[i];
; #pragma unroll
;         for (int i = 0; i < NT; ++i) *(u32x4*)(sB + sbrow[i] * LDT + lkc * 8) = rb0[i];
;         lds_barrier();
;         if (kt + 1 < nk) {
;             ga += 64; gb += 64;
; #pragma unroll
;             for (int i = 0; i < 4; ++i) ra0[i] = *(const u32x4*)(ga + (size_t)(32 * i) * lda);
; #pragma unroll
;             for (int i = 0; i < NT; ++i) rb0[i] = *(const u32x4*)(gb + (size_t)(32 * i) * ldb);
;         }
;         __builtin_amdgcn_sched_barrier(0);
;         gemm_compute<NT>(acc, sA, sB, wr, wc, fr, fq);
	ds_read_b128 v[110:113], v244 offset:0
	ds_read_b128 v[114:117], v244 offset:2048
	ds_read_b128 v[118:121], v244 offset:4096
	ds_read_b128 v[122:125], v244 offset:6144
	ds_read_b128 v[126:129], v246 offset:0
	ds_read_b128 v[130:133], v246 offset:2048
	ds_read_b128 v[134:137], v246 offset:4096
	ds_read_b128 v[138:141], v246 offset:6144
	s_setprio 1
	v_mfma_f32_16x16x32_bf16 v[94:97], v[176:179], v[160:163], v[94:97]
	s_lshl_b32 s95, s94, 2
	s_add_u32 m0, s95, 0x8000
	s_nop 0
	global_load_lds_dwordx4 v236, s[90:91] sc1
	v_mfma_f32_16x16x32_bf16 v[90:93], v[180:183], v[160:163], v[90:93]
	v_mfma_f32_16x16x32_bf16 v[86:89], v[184:187], v[160:163], v[86:89]
	global_load_lds_dwordx4 v237, s[90:91] offset:1024 sc1
	v_mfma_f32_16x16x32_bf16 v[82:85], v[188:191], v[160:163], v[82:85]
	v_mfma_f32_16x16x32_bf16 v[78:81], v[176:179], v[164:167], v[78:81]
	global_load_lds_dwordx4 v238, s[90:91] offset:2048 sc1
	v_mfma_f32_16x16x32_bf16 v[74:77], v[180:183], v[164:167], v[74:77]
	v_mfma_f32_16x16x32_bf16 v[70:73], v[184:187], v[164:167], v[70:73]
	global_load_lds_dwordx4 v239, s[90:91] offset:3072 sc1
	v_mfma_f32_16x16x32_bf16 v[66:69], v[188:191], v[164:167], v[66:69]
	v_mfma_f32_16x16x32_bf16 v[62:65], v[176:179], v[168:171], v[62:65]
	s_mul_i32 s95, s94, 4
	s_add_u32 m0, s95, 0xc000
	s_nop 0
	global_load_lds_dwordx4 v240, s[92:93]
	v_mfma_f32_16x16x32_bf16 v[58:61], v[180:183], v[168:171], v[58:61]
	v_mfma_f32_16x16x32_bf16 v[54:57], v[184:187], v[168:171], v[54:57]
	global_load_lds_dwordx4 v241, s[92:93] offset:1024
	v_mfma_f32_16x16x32_bf16 v[50:53], v[188:191], v[168:171], v[50:53]
	v_mfma_f32_16x16x32_bf16 v[46:49], v[176:179], v[172:175], v[46:49]
	global_load_lds_dwordx4 v242, s[92:93] offset:2048
	v_mfma_f32_16x16x32_bf16 v[42:45], v[180:183], v[172:175], v[42:45]
	v_mfma_f32_16x16x32_bf16 v[38:41], v[184:187], v[172:175], v[38:41]
	global_load_lds_dwordx4 v243, s[92:93] offset:3072
	v_mfma_f32_16x16x32_bf16 v[30:33], v[188:191], v[172:175], v[30:33]
	s_add_u32 s90, s90, 0x80
	s_addc_u32 s91, s91, 0
	s_add_u32 s92, s92, 0x80
	s_addc_u32 s93, s93, 0
	s_setprio 0
	v_readlane_b32 s95, v234, 6
	s_add_i32 s95, s95, -1
	s_cmp_lg_u32 s95, 0
	s_cbranch_scc1 .Lgemm_k178
.Lgemm_x178:
	ds_read_b128 v[160:163], v245 offset:0
	ds_read_b128 v[164:167], v245 offset:2048
	ds_read_b128 v[168:171], v245 offset:4096
	ds_read_b128 v[172:175], v245 offset:6144
	ds_read_b128 v[176:179], v247 offset:0
	ds_read_b128 v[180:183], v247 offset:2048
	ds_read_b128 v[184:187], v247 offset:4096
	ds_read_b128 v[188:191], v247 offset:6144
	s_setprio 1
	s_waitcnt lgkmcnt(11)
	v_mfma_f32_16x16x32_bf16 v[94:97], v[126:129], v[110:113], v[94:97]
	s_waitcnt lgkmcnt(10)
	v_mfma_f32_16x16x32_bf16 v[90:93], v[130:133], v[110:113], v[90:93]
	s_waitcnt lgkmcnt(9)
	v_mfma_f32_16x16x32_bf16 v[86:89], v[134:137], v[110:113], v[86:89]
	s_waitcnt lgkmcnt(8)
	v_mfma_f32_16x16x32_bf16 v[82:85], v[138:141], v[110:113], v[82:85]
	v_mfma_f32_16x16x32_bf16 v[78:81], v[126:129], v[114:117], v[78:81]
	v_mfma_f32_16x16x32_bf16 v[74:77], v[130:133], v[114:117], v[74:77]
	v_mfma_f32_16x16x32_bf16 v[70:73], v[134:137], v[114:117], v[70:73]
	v_mfma_f32_16x16x32_bf16 v[66:69], v[138:141], v[114:117], v[66:69]
	v_mfma_f32_16x16x32_bf16 v[62:65], v[126:129], v[118:121], v[62:65]
	v_mfma_f32_16x16x32_bf16 v[58:61], v[130:133], v[118:121], v[58:61]
	v_mfma_f32_16x16x32_bf16 v[54:57], v[134:137], v[118:121], v[54:57]
	v_mfma_f32_16x16x32_bf16 v[50:53], v[138:141], v[118:121], v[50:53]
	v_mfma_f32_16x16x32_bf16 v[46:49], v[126:129], v[122:125], v[46:49]
	v_mfma_f32_16x16x32_bf16 v[42:45], v[130:133], v[122:125], v[42:45]
	v_mfma_f32_16x16x32_bf16 v[38:41], v[134:137], v[122:125], v[38:41]
	v_mfma_f32_16x16x32_bf16 v[30:33], v[138:141], v[122:125], v[30:33]
	s_setprio 0
	s_waitcnt vmcnt(0) lgkmcnt(0)
	s_barrier
	ds_read_b128 v[110:113], v244 offset:32768
	ds_read_b128 v[114:117], v244 offset:34816
	ds_read_b128 v[118:121], v244 offset:36864
	ds_read_b128 v[122:125], v244 offset:38912
	ds_read_b128 v[126:129], v246 offset:32768
	ds_read_b128 v[130:133], v246 offset:34816
	ds_read_b128 v[134:137], v246 offset:36864
	ds_read_b128 v[138:141], v246 offset:38912
	s_setprio 1
	v_mfma_f32_16x16x32_bf16 v[94:97], v[176:179], v[160:163], v[94:97]
	s_lshl_b32 s95, s94, 2
	s_add_u32 m0, s95, 0x0
	s_nop 0
	global_load_lds_dwordx4 v236, s[90:91] sc1
	v_mfma_f32_16x16x32_bf16 v[90:93], v[180:183], v[160:163], v[90:93]
	v_mfma_f32_16x16x32_bf16 v[86:89], v[184:187], v[160:163], v[86:89]
	global_load_lds_dwordx4 v237, s[90:91] offset:1024 sc1
	v_mfma_f32_16x16x32_bf16 v[82:85], v[188:191], v[160:163], v[82:85]
	v_mfma_f32_16x16x32_bf16 v[78:81], v[176:179], v[164:167], v[78:81]
	global_load_lds_dwordx4 v238, s[90:91] offset:2048 sc1
	v_mfma_f32_16x16x32_bf16 v[74:77], v[180:183], v[164:167], v[74:77]
	v_mfma_f32_16x16x32_bf16 v[70:73], v[184:187], v[164:167], v[70:73]
	global_load_lds_dwordx4 v239, s[90:91] offset:3072 sc1
	v_mfma_f32_16x16x32_bf16 v[66:69], v[188:191], v[164:167], v[66:69]
	v_mfma_f32_16x16x32_bf16 v[62:65], v[176:179], v[168:171], v[62:65]
	s_mul_i32 s95, s94, 4
	s_add_u32 m0, s95, 0x4000
	s_nop 0
	global_load_lds_dwordx4 v240, s[92:93]
	v_mfma_f32_16x16x32_bf16 v[58:61], v[180:183], v[168:171], v[58:61]
	v_mfma_f32_16x16x32_bf16 v[54:57], v[184:187], v[168:171], v[54:57]
	global_load_lds_dwordx4 v241, s[92:93] offset:1024
	v_mfma_f32_16x16x32_bf16 v[50:53], v[188:191], v[168:171], v[50:53]
	v_mfma_f32_16x16x32_bf16 v[46:49], v[176:179], v[172:175], v[46:49]
	global_load_lds_dwordx4 v242, s[92:93] offset:2048
	v_mfma_f32_16x16x32_bf16 v[42:45], v[180:183], v[172:175], v[42:45]
	v_mfma_f32_16x16x32_bf16 v[38:41], v[184:187], v[172:175], v[38:41]
	global_load_lds_dwordx4 v243, s[92:93] offset:3072
	v_mfma_f32_16x16x32_bf16 v[30:33], v[188:191], v[172:175], v[30:33]
	s_add_u32 s90, s90, 0x80
	s_addc_u32 s91, s91, 0
	s_add_u32 s92, s92, 0x80
	s_addc_u32 s93, s93, 0
	s_setprio 0
	ds_read_b128 v[160:163], v245 offset:32768
	ds_read_b128 v[164:167], v245 offset:34816
	ds_read_b128 v[168:171], v245 offset:36864
	ds_read_b128 v[172:175], v245 offset:38912
	ds_read_b128 v[176:179], v247 offset:32768
	ds_read_b128 v[180:183], v247 offset:34816
	ds_read_b128 v[184:187], v247 offset:36864
	ds_read_b128 v[188:191], v247 offset:38912
	s_setprio 1
	s_waitcnt lgkmcnt(11)
; template <int NT>
; __device__ __forceinline__ void gemm_tile(f32x4 (&acc)[4][NT], const bf16_t* A, int lda, const bf16_t* B, int ldb, int K, bf16_t* sm) {
;     ...
;         if (kt + 1 < nk) {
;             ga += 64; gb += 64;
; #pragma unroll
;             for (int i = 0; i < 4; ++i) ra0[i] = *(const u32x4*)(ga + (size_t)(32 * i) * lda);
; #pragma unroll
;             for (int i = 0; i < NT; ++i) rb0[i] = *(const u32x4*)(gb + (size_t)(32 * i) * ldb);
;         }
;         __builtin_amdgcn_sched_barrier(0);
;         gemm_compute<NT>(acc, sA, sB, wr, wc, fr, fq);
	v_mfma_f32_16x16x32_bf16 v[94:97], v[126:129], v[110:113], v[94:97]
	s_waitcnt lgkmcnt(10)
	v_mfma_f32_16x16x32_bf16 v[90:93], v[130:133], v[110:113], v[90:93]
	s_waitcnt lgkmcnt(9)
	v_mfma_f32_16x16x32_bf16 v[86:89], v[134:137], v[110:113], v[86:89]
	s_waitcnt lgkmcnt(8)
	v_mfma_f32_16x16x32_bf16 v[82:85], v[138:141], v[110:113], v[82:85]
	v_mfma_f32_16x16x32_bf16 v[78:81], v[126:129], v[114:117], v[78:81]
	v_mfma_f32_16x16x32_bf16 v[74:77], v[130:133], v[114:117], v[74:77]
	v_mfma_f32_16x16x32_bf16 v[70:73], v[134:137], v[114:117], v[70:73]
	v_mfma_f32_16x16x32_bf16 v[66:69], v[138:141], v[114:117], v[66:69]
	v_mfma_f32_16x16x32_bf16 v[62:65], v[126:129], v[118:121], v[62:65]
	v_mfma_f32_16x16x32_bf16 v[58:61], v[130:133], v[118:121], v[58:61]
	v_mfma_f32_16x16x32_bf16 v[54:57], v[134:137], v[118:121], v[54:57]
	v_mfma_f32_16x16x32_bf16 v[50:53], v[138:141], v[118:121], v[50:53]
	v_mfma_f32_16x16x32_bf16 v[46:49], v[126:129], v[122:125], v[46:49]
	v_mfma_f32_16x16x32_bf16 v[42:45], v[130:133], v[122:125], v[42:45]
	v_mfma_f32_16x16x32_bf16 v[38:41], v[134:137], v[122:125], v[38:41]
	v_mfma_f32_16x16x32_bf16 v[30:33], v[138:141], v[122:125], v[30:33]
	s_setprio 0
	s_waitcnt vmcnt(0) lgkmcnt(0)
	s_barrier
	ds_read_b128 v[110:113], v244 offset:0
	ds_read_b128 v[114:117], v244 offset:2048
	ds_read_b128 v[118:121], v244 offset:4096
	ds_read_b128 v[122:125], v244 offset:6144
	ds_read_b128 v[126:129], v246 offset:0
	ds_read_b128 v[130:133], v246 offset:2048
	ds_read_b128 v[134:137], v246 offset:4096
	ds_read_b128 v[138:141], v246 offset:6144
	s_setprio 1
	v_mfma_f32_16x16x32_bf16 v[94:97], v[176:179], v[160:163], v[94:97]
	v_readlane_b32 s90, v234, 0
	v_readlane_b32 s91, v234, 1
	v_readlane_b32 s92, v234, 2
	v_readlane_b32 s93, v234, 3
	v_readlane_b32 s94, v234, 4
	v_readlane_b32 s95, v234, 5
	s_mov_b32 s14, 0x700
	s_mov_b32 s15, 0
	s_nop 3
	v_mfma_f32_16x16x32_bf16 v[90:93], v[180:183], v[160:163], v[90:93]
	v_mfma_f32_16x16x32_bf16 v[86:89], v[184:187], v[160:163], v[86:89]
	v_lshl_add_u64 v[0:1], v[98:99], 0, s[14:15]
	v_mfma_f32_16x16x32_bf16 v[82:85], v[188:191], v[160:163], v[82:85]
	v_mfma_f32_16x16x32_bf16 v[78:81], v[176:179], v[164:167], v[78:81]
	v_add_co_u32_e32 v2, vcc, s0, v0
	v_mfma_f32_16x16x32_bf16 v[74:77], v[180:183], v[164:167], v[74:77]
	v_mfma_f32_16x16x32_bf16 v[70:73], v[184:187], v[164:167], v[70:73]
	s_nop 0
	v_mfma_f32_16x16x32_bf16 v[66:69], v[188:191], v[164:167], v[66:69]
	v_mfma_f32_16x16x32_bf16 v[62:65], v[176:179], v[168:171], v[62:65]
	s_nop 0
	v_mfma_f32_16x16x32_bf16 v[58:61], v[180:183], v[168:171], v[58:61]
	v_mfma_f32_16x16x32_bf16 v[54:57], v[184:187], v[168:171], v[54:57]
	v_addc_co_u32_e32 v3, vcc, 0, v1, vcc
	v_mfma_f32_16x16x32_bf16 v[50:53], v[188:191], v[168:171], v[50:53]
	v_mfma_f32_16x16x32_bf16 v[46:49], v[176:179], v[172:175], v[46:49]
	v_add_co_u32_e32 v4, vcc, s64, v0
	v_mfma_f32_16x16x32_bf16 v[42:45], v[180:183], v[172:175], v[42:45]
	v_mfma_f32_16x16x32_bf16 v[38:41], v[184:187], v[172:175], v[38:41]
	v_lshl_add_u64 v[8:9], v[100:101], 0, s[14:15]
	v_mfma_f32_16x16x32_bf16 v[30:33], v[188:191], v[172:175], v[30:33]
	s_nop 0
	v_addc_co_u32_e32 v5, vcc, 0, v1, vcc
	global_load_dwordx4 v[18:21], v[2:3], off offset:128
	global_load_dwordx4 v[14:17], v[4:5], off offset:128
	v_add_co_u32_e32 v2, vcc, s65, v0
	s_mov_b32 s2, 0x2140000
	s_nop 0
	v_addc_co_u32_e32 v3, vcc, 0, v1, vcc
	v_add_co_u32_e32 v0, vcc, s33, v0
	s_nop 1
	v_addc_co_u32_e32 v1, vcc, 0, v1, vcc
	global_load_dwordx4 v[26:29], v[2:3], off offset:128
	global_load_dwordx4 v[34:37], v[0:1], off offset:128
	v_add_co_u32_e32 v0, vcc, s2, v8
	s_mov_b32 s2, 0x2150000
	s_nop 0
	v_addc_co_u32_e32 v1, vcc, 0, v9, vcc
	v_add_co_u32_e32 v2, vcc, s2, v8
	s_mov_b32 s2, 0x2160000
	s_nop 0
	v_addc_co_u32_e32 v3, vcc, 0, v9, vcc
	v_add_co_u32_e32 v10, vcc, s2, v8
	s_mov_b32 s2, 0x2170000
	s_nop 0
	v_addc_co_u32_e32 v11, vcc, 0, v9, vcc
	v_add_co_u32_e32 v22, vcc, s2, v8
	global_load_dwordx4 v[4:7], v[0:1], off offset:128
	s_nop 0
	global_load_dwordx4 v[0:3], v[2:3], off offset:128
	v_addc_co_u32_e32 v23, vcc, 0, v9, vcc
	global_load_dwordx4 v[8:11], v[10:11], off offset:128
	s_nop 0
	global_load_dwordx4 v[22:25], v[22:23], off offset:128
	s_setprio 0
	ds_read_b128 v[160:163], v245 offset:0
	ds_read_b128 v[164:167], v245 offset:2048
	ds_read_b128 v[168:171], v245 offset:4096
	ds_read_b128 v[172:175], v245 offset:6144
	ds_read_b128 v[176:179], v247 offset:0
	ds_read_b128 v[180:183], v247 offset:2048
	ds_read_b128 v[184:187], v247 offset:4096
	ds_read_b128 v[188:191], v247 offset:6144
	s_setprio 1
	s_waitcnt lgkmcnt(11)
	v_mfma_f32_16x16x32_bf16 v[94:97], v[126:129], v[110:113], v[94:97]
	s_waitcnt lgkmcnt(10)
	v_mfma_f32_16x16x32_bf16 v[90:93], v[130:133], v[110:113], v[90:93]
	s_waitcnt lgkmcnt(9)
	v_mfma_f32_16x16x32_bf16 v[86:89], v[134:137], v[110:113], v[86:89]
	s_waitcnt lgkmcnt(8)
	v_mfma_f32_16x16x32_bf16 v[82:85], v[138:141], v[110:113], v[82:85]
	v_mfma_f32_16x16x32_bf16 v[78:81], v[126:129], v[114:117], v[78:81]
	v_mfma_f32_16x16x32_bf16 v[74:77], v[130:133], v[114:117], v[74:77]
	v_mfma_f32_16x16x32_bf16 v[70:73], v[134:137], v[114:117], v[70:73]
	v_mfma_f32_16x16x32_bf16 v[66:69], v[138:141], v[114:117], v[66:69]
	v_mfma_f32_16x16x32_bf16 v[62:65], v[126:129], v[118:121], v[62:65]
	v_mfma_f32_16x16x32_bf16 v[58:61], v[130:133], v[118:121], v[58:61]
	v_mfma_f32_16x16x32_bf16 v[54:57], v[134:137], v[118:121], v[54:57]
	v_mfma_f32_16x16x32_bf16 v[50:53], v[138:141], v[118:121], v[50:53]
	v_mfma_f32_16x16x32_bf16 v[46:49], v[126:129], v[122:125], v[46:49]
	v_mfma_f32_16x16x32_bf16 v[42:45], v[130:133], v[122:125], v[42:45]
	v_mfma_f32_16x16x32_bf16 v[38:41], v[134:137], v[122:125], v[38:41]
	v_mfma_f32_16x16x32_bf16 v[30:33], v[138:141], v[122:125], v[30:33]
	s_setprio 0
	s_waitcnt lgkmcnt(0)
	s_setprio 1
	v_mfma_f32_16x16x32_bf16 v[94:97], v[176:179], v[160:163], v[94:97]
	v_mfma_f32_16x16x32_bf16 v[90:93], v[180:183], v[160:163], v[90:93]
	v_mfma_f32_16x16x32_bf16 v[86:89], v[184:187], v[160:163], v[86:89]
	v_mfma_f32_16x16x32_bf16 v[82:85], v[188:191], v[160:163], v[82:85]
	v_mfma_f32_16x16x32_bf16 v[78:81], v[176:179], v[164:167], v[78:81]
	v_mfma_f32_16x16x32_bf16 v[74:77], v[180:183], v[164:167], v[74:77]
	v_mfma_f32_16x16x32_bf16 v[70:73], v[184:187], v[164:167], v[70:73]
	v_mfma_f32_16x16x32_bf16 v[66:69], v[188:191], v[164:167], v[66:69]
	v_mfma_f32_16x16x32_bf16 v[62:65], v[176:179], v[168:171], v[62:65]
	v_mfma_f32_16x16x32_bf16 v[58:61], v[180:183], v[168:171], v[58:61]
	v_mfma_f32_16x16x32_bf16 v[54:57], v[184:187], v[168:171], v[54:57]
	v_mfma_f32_16x16x32_bf16 v[50:53], v[188:191], v[168:171], v[50:53]
	v_mfma_f32_16x16x32_bf16 v[46:49], v[176:179], v[172:175], v[46:49]
	v_mfma_f32_16x16x32_bf16 v[42:45], v[180:183], v[172:175], v[42:45]
	v_mfma_f32_16x16x32_bf16 v[38:41], v[184:187], v[172:175], v[38:41]
	v_mfma_f32_16x16x32_bf16 v[30:33], v[188:191], v[172:175], v[30:33]
	s_setprio 0
	s_waitcnt lgkmcnt(0)
	s_barrier
; __device__ __forceinline__ float sigmoid_(float x) { return __builtin_amdgcn_rcpf(1.f + __expf(-x)); }
; template <int NT>
; __device__ __forceinline__ void gemm_tile(f32x4 (&acc)[4][NT], const bf16_t* A, int lda, const bf16_t* B, int ldb, int K, bf16_t* sm) {
;     ...
;         lds_barrier();
; #pragma unroll
;         for (int i = 0; i < 4; ++i) *(u32x4*)(sA + (lrow + 32 * i) * LDT + lkc * 8) = ra0[i];
; #pragma unroll
;         for (int i = 0; i < NT; ++i) *(u32x4*)(sB + sbrow[i] * LDT + lkc * 8) = rb0[i];
;         lds_barrier();
;         if (kt + 1 < nk) {
;             ga += 64; gb += 64;
; #pragma unroll
;             for (int i = 0; i < 4; ++i) ra0[i] = *(const u32x4*)(ga + (size_t)(32 * i) * lda);
; #pragma unroll
;             for (int i = 0; i < NT; ++i) rb0[i] = *(const u32x4*)(gb + (size_t)(32 * i) * ldb);
;         }
;         __builtin_amdgcn_sched_barrier(0);
;         gemm_compute<NT>(acc, sA, sB, wr, wc, fr, fq);
; __device__ __forceinline__ void gate_tile(int t, const bf16_t* xb, const bf16_t* Wg, bf16_t* G, bf16_t* sm) {
;     ...
; #pragma unroll
;     for (int mt = 0; mt < 4; ++mt) {
;         const int row = tm * 128 + wr * 64 + mt * 16 + fr;
;         const int cbase = tn * 128 + wc * 64 + fq * 16;
;         float v[16]; gather_cols<4>(acc, mt, v);
;         u32x4 o0, o1;
; #pragma unroll
;         for (int q = 0; q < 4; ++q) {
;             o0[q] = pack2(sigmoid_(v[2 * q]), sigmoid_(v[2 * q + 1]));
;             o1[q] = pack2(sigmoid_(v[8 + 2 * q]), sigmoid_(v[8 + 2 * q + 1]));
;         }
;         *(u32x4*)(G + (size_t)row * 4096 + cbase) = o0;
;         *(u32x4*)(G + (size_t)row * 4096 + cbase + 8) = o1;
;     }
	s_waitcnt vmcnt(7)
	ds_write_b128 v104, v[18:21]
	s_waitcnt vmcnt(6)
	ds_write_b128 v104, v[14:17] offset:5120
	s_waitcnt vmcnt(5)
	ds_write_b128 v104, v[26:29] offset:10240
	s_waitcnt vmcnt(4)
	ds_write_b128 v104, v[34:37] offset:15360
	s_waitcnt vmcnt(3)
	ds_write_b128 v105, v[4:7] offset:20480
	s_waitcnt vmcnt(2)
	ds_write_b128 v106, v[0:3] offset:20480
	s_waitcnt vmcnt(1)
	ds_write_b128 v107, v[8:11] offset:20480
	s_waitcnt vmcnt(0)
	ds_write_b128 v108, v[22:25] offset:20480
	s_waitcnt lgkmcnt(0)
	s_barrier
	ds_read_b128 v[0:3], v103
	ds_read_b128 v[4:7], v103 offset:2560
	ds_read_b128 v[8:11], v103 offset:5120
	ds_read_b128 v[14:17], v103 offset:7680
	ds_read_b128 v[18:21], v102 offset:20480
	ds_read_b128 v[22:25], v102 offset:23040
	ds_read_b128 v[26:29], v102 offset:25600
	ds_read_b128 v[34:37], v102 offset:28160
	s_setprio 1
	s_waitcnt lgkmcnt(3)
	v_mfma_f32_16x16x32_bf16 v[94:97], v[18:21], v[0:3], v[94:97]
	s_waitcnt lgkmcnt(2)
	v_mfma_f32_16x16x32_bf16 v[90:93], v[22:25], v[0:3], v[90:93]
	s_waitcnt lgkmcnt(1)
	v_mfma_f32_16x16x32_bf16 v[86:89], v[26:29], v[0:3], v[86:89]
	s_waitcnt lgkmcnt(0)
	v_mfma_f32_16x16x32_bf16 v[0:3], v[34:37], v[0:3], v[82:85]
	v_mfma_f32_16x16x32_bf16 v[78:81], v[18:21], v[4:7], v[78:81]
	v_mfma_f32_16x16x32_bf16 v[74:77], v[22:25], v[4:7], v[74:77]
	v_mfma_f32_16x16x32_bf16 v[70:73], v[26:29], v[4:7], v[70:73]
	v_mfma_f32_16x16x32_bf16 v[4:7], v[34:37], v[4:7], v[66:69]
	v_mfma_f32_16x16x32_bf16 v[62:65], v[18:21], v[8:11], v[62:65]
	v_mfma_f32_16x16x32_bf16 v[58:61], v[22:25], v[8:11], v[58:61]
	v_mfma_f32_16x16x32_bf16 v[54:57], v[26:29], v[8:11], v[54:57]
	v_mfma_f32_16x16x32_bf16 v[8:11], v[34:37], v[8:11], v[50:53]
	v_mfma_f32_16x16x32_bf16 v[46:49], v[18:21], v[14:17], v[46:49]
	v_mfma_f32_16x16x32_bf16 v[42:45], v[22:25], v[14:17], v[42:45]
	v_mfma_f32_16x16x32_bf16 v[38:41], v[26:29], v[14:17], v[38:41]
	v_mfma_f32_16x16x32_bf16 v[34:37], v[34:37], v[14:17], v[30:33]
	s_setprio 0
	ds_read_b128 v[14:17], v103 offset:64
	ds_read_b128 v[18:21], v103 offset:2624
	ds_read_b128 v[50:53], v103 offset:5184
	ds_read_b128 v[66:69], v103 offset:7744
	ds_read_b128 v[82:85], v102 offset:20544
	ds_read_b128 v[98:101], v102 offset:23104
	ds_read_b128 v[104:107], v102 offset:25664
	ds_read_b128 v[108:111], v102 offset:28224
	s_setprio 1
	s_waitcnt lgkmcnt(3)
	v_mfma_f32_16x16x32_bf16 v[94:97], v[82:85], v[14:17], v[94:97]
	s_waitcnt lgkmcnt(2)
	v_mfma_f32_16x16x32_bf16 v[90:93], v[98:101], v[14:17], v[90:93]
	s_waitcnt lgkmcnt(1)
	v_mfma_f32_16x16x32_bf16 v[86:89], v[104:107], v[14:17], v[86:89]
	s_waitcnt lgkmcnt(0)
	v_mfma_f32_16x16x32_bf16 v[112:115], v[108:111], v[14:17], v[0:3]
	v_mfma_f32_16x16x32_bf16 v[78:81], v[82:85], v[18:21], v[78:81]
	v_mfma_f32_16x16x32_bf16 v[74:77], v[98:101], v[18:21], v[74:77]
	v_mfma_f32_16x16x32_bf16 v[70:73], v[104:107], v[18:21], v[70:73]
	v_mfma_f32_16x16x32_bf16 v[116:119], v[108:111], v[18:21], v[4:7]
	v_mfma_f32_16x16x32_bf16 v[30:33], v[82:85], v[50:53], v[62:65]
	v_mfma_f32_16x16x32_bf16 v[26:29], v[98:101], v[50:53], v[58:61]
	v_mfma_f32_16x16x32_bf16 v[22:25], v[104:107], v[50:53], v[54:57]
	v_mfma_f32_16x16x32_bf16 v[18:21], v[108:111], v[50:53], v[8:11]
	v_mfma_f32_16x16x32_bf16 v[14:17], v[82:85], v[66:69], v[46:49]
	v_mfma_f32_16x16x32_bf16 v[8:11], v[98:101], v[66:69], v[42:45]
	v_mfma_f32_16x16x32_bf16 v[4:7], v[104:107], v[66:69], v[38:41]
	v_mfma_f32_16x16x32_bf16 v[0:3], v[108:111], v[66:69], v[34:37]
	s_setprio 0
	s_nop 1
	v_ashrrev_i32_e32 v34, 1, v12
	v_and_b32_e32 v34, 0xffffffc0, v34
	v_lshl_add_u32 v34, s13, 7, v34
	v_and_or_b32 v34, v12, 15, v34
	v_and_b32_e32 v12, 0x70, v12
	v_lshlrev_b32_e32 v12, 1, v12
	v_lshl_or_b32 v36, s12, 8, v12
	v_mul_f32_e32 v12, 0xbfb8aa3b, v94
	v_mul_f32_e32 v35, 0xbfb8aa3b, v90
	v_exp_f32_e32 v12, v12
	v_exp_f32_e32 v35, v35
	v_mul_f32_e32 v38, 0xbfb8aa3b, v96
	v_exp_f32_e32 v39, v38
	v_add_f32_e32 v12, 1.0, v12
	v_add_f32_e32 v35, 1.0, v35
	v_mul_f32_e32 v38, 0xbfb8aa3b, v92
	v_rcp_f32_e32 v12, v12
	v_rcp_f32_e32 v35, v35
	v_exp_f32_e32 v40, v38
	v_mul_f32_e32 v45, 0xbfb8aa3b, v113
	v_exp_f32_e32 v45, v45
	v_cvt_pk_bf16_f32 v38, v12, v35
	v_add_f32_e32 v12, 1.0, v39
	v_add_f32_e32 v35, 1.0, v40
	v_mul_f32_e32 v39, 0xbfb8aa3b, v86
	v_rcp_f32_e32 v12, v12
	v_rcp_f32_e32 v35, v35
	v_exp_f32_e32 v39, v39
	v_mul_f32_e32 v40, 0xbfb8aa3b, v112
	v_exp_f32_e32 v40, v40
	v_cvt_pk_bf16_f32 v42, v12, v35
	v_add_f32_e32 v12, 1.0, v39
	v_mul_f32_e32 v39, 0xbfb8aa3b, v88
	v_add_f32_e32 v35, 1.0, v40
	v_exp_f32_e32 v40, v39
	v_mul_f32_e32 v39, 0xbfb8aa3b, v114
	v_rcp_f32_e32 v12, v12
	v_rcp_f32_e32 v35, v35
	v_exp_f32_e32 v41, v39
	v_mul_f32_e32 v47, 0xbfb8aa3b, v115
	v_exp_f32_e32 v47, v47
	v_cvt_pk_bf16_f32 v39, v12, v35
	v_add_f32_e32 v12, 1.0, v40
	v_add_f32_e32 v35, 1.0, v41
	v_mul_f32_e32 v40, 0xbfb8aa3b, v95
	v_rcp_f32_e32 v12, v12
	v_rcp_f32_e32 v35, v35
	v_exp_f32_e32 v40, v40
	v_mul_f32_e32 v41, 0xbfb8aa3b, v91
	v_exp_f32_e32 v41, v41
	v_cvt_pk_bf16_f32 v43, v12, v35
	v_add_f32_e32 v12, 1.0, v40
	v_mul_f32_e32 v40, 0xbfb8aa3b, v97
	v_add_f32_e32 v35, 1.0, v41
	v_exp_f32_e32 v40, v40
	v_mul_f32_e32 v41, 0xbfb8aa3b, v93
	v_exp_f32_e32 v41, v41
	v_rcp_f32_e32 v12, v12
	v_add_f32_e32 v40, 1.0, v40
	v_rcp_f32_e32 v44, v40
	v_add_f32_e32 v40, 1.0, v41
	v_mul_f32_e32 v41, 0xbfb8aa3b, v87
	v_exp_f32_e32 v41, v41
	v_rcp_f32_e32 v46, v40
	v_rcp_f32_e32 v35, v35
	v_readlane_b32 s12, v230, 34
	v_add_f32_e32 v40, 1.0, v41
	v_rcp_f32_e32 v41, v40
	v_add_f32_e32 v40, 1.0, v45
	v_mul_f32_e32 v45, 0xbfb8aa3b, v89
	v_exp_f32_e32 v45, v45
	v_rcp_f32_e32 v48, v40
	v_cvt_pk_bf16_f32 v44, v44, v46
	v_mov_b32_e32 v37, v13
	v_add_f32_e32 v40, 1.0, v45
; __device__ __forceinline__ float sigmoid_(float x) { return __builtin_amdgcn_rcpf(1.f + __expf(-x)); }
; __device__ __forceinline__ void gate_tile(int t, const bf16_t* xb, const bf16_t* Wg, bf16_t* G, bf16_t* sm) {
;     ...
; #pragma unroll
;     for (int mt = 0; mt < 4; ++mt) {
;         const int row = tm * 128 + wr * 64 + mt * 16 + fr;
;         const int cbase = tn * 128 + wc * 64 + fq * 16;
;         float v[16]; gather_cols<4>(acc, mt, v);
;         u32x4 o0, o1;
; #pragma unroll
;         for (int q = 0; q < 4; ++q) {
;             o0[q] = pack2(sigmoid_(v[2 * q]), sigmoid_(v[2 * q + 1]));
;             o1[q] = pack2(sigmoid_(v[8 + 2 * q]), sigmoid_(v[8 + 2 * q + 1]));
;         }
;         *(u32x4*)(G + (size_t)row * 4096 + cbase) = o0;
;         *(u32x4*)(G + (size_t)row * 4096 + cbase + 8) = o1;
;     }
	v_rcp_f32_e32 v45, v40
	v_add_f32_e32 v40, 1.0, v47
	v_rcp_f32_e32 v47, v40
	v_cvt_pk_bf16_f32 v40, v12, v35
	v_ashrrev_i32_e32 v35, 31, v34
	v_mul_f32_e32 v12, 0xbfb8aa3b, v78
	v_cvt_pk_bf16_f32 v45, v45, v47
	v_lshlrev_b64 v[46:47], 13, v[34:35]
	v_mul_f32_e32 v35, 0xbfb8aa3b, v74
	v_readlane_b32 s13, v230, 35
	v_exp_f32_e32 v12, v12
	v_exp_f32_e32 v35, v35
	v_lshl_add_u64 v[36:37], s[12:13], 0, v[36:37]
	v_cvt_pk_bf16_f32 v41, v41, v48
	v_lshl_add_u64 v[46:47], v[36:37], 0, v[46:47]
	global_store_dwordx4 v[46:47], v[38:41], off
	v_add_f32_e32 v12, 1.0, v12
	v_add_f32_e32 v35, 1.0, v35
	v_mul_f32_e32 v38, 0xbfb8aa3b, v80
	v_exp_f32_e32 v39, v38
	v_mul_f32_e32 v38, 0xbfb8aa3b, v76
	v_rcp_f32_e32 v12, v12
	v_rcp_f32_e32 v35, v35
	v_exp_f32_e32 v40, v38
	global_store_dwordx4 v[46:47], v[42:45], off offset:16
	v_mul_f32_e32 v47, 0xbfb8aa3b, v119
	v_cvt_pk_bf16_f32 v38, v12, v35
	v_add_f32_e32 v12, 1.0, v39
	v_add_f32_e32 v35, 1.0, v40
	v_mul_f32_e32 v39, 0xbfb8aa3b, v70
	v_rcp_f32_e32 v12, v12
	v_rcp_f32_e32 v35, v35
	v_exp_f32_e32 v39, v39
	v_mul_f32_e32 v40, 0xbfb8aa3b, v116
	v_exp_f32_e32 v40, v40
	v_cvt_pk_bf16_f32 v42, v12, v35
	v_add_f32_e32 v12, 1.0, v39
	v_mul_f32_e32 v39, 0xbfb8aa3b, v72
	v_add_f32_e32 v35, 1.0, v40
	v_exp_f32_e32 v40, v39
	v_mul_f32_e32 v39, 0xbfb8aa3b, v118
	v_rcp_f32_e32 v12, v12
	v_rcp_f32_e32 v35, v35
	v_exp_f32_e32 v41, v39
	v_mul_f32_e32 v45, 0xbfb8aa3b, v117
	v_exp_f32_e32 v45, v45
	v_cvt_pk_bf16_f32 v39, v12, v35
	v_add_f32_e32 v12, 1.0, v40
	v_add_f32_e32 v35, 1.0, v41
	v_mul_f32_e32 v40, 0xbfb8aa3b, v79
	v_rcp_f32_e32 v12, v12
	v_rcp_f32_e32 v35, v35
	v_exp_f32_e32 v40, v40
	v_mul_f32_e32 v41, 0xbfb8aa3b, v75
	v_exp_f32_e32 v41, v41
	v_cvt_pk_bf16_f32 v43, v12, v35
	v_add_f32_e32 v12, 1.0, v40
	v_mul_f32_e32 v40, 0xbfb8aa3b, v81
	v_add_f32_e32 v35, 1.0, v41
	v_exp_f32_e32 v40, v40
	v_mul_f32_e32 v41, 0xbfb8aa3b, v77
	v_exp_f32_e32 v41, v41
	v_exp_f32_e32 v47, v47
	v_add_f32_e32 v40, 1.0, v40
	v_rcp_f32_e32 v44, v40
	v_add_f32_e32 v40, 1.0, v41
	v_mul_f32_e32 v41, 0xbfb8aa3b, v71
	v_exp_f32_e32 v41, v41
	v_rcp_f32_e32 v46, v40
	v_rcp_f32_e32 v12, v12
	v_rcp_f32_e32 v35, v35
	v_add_f32_e32 v40, 1.0, v41
	v_rcp_f32_e32 v41, v40
	v_add_f32_e32 v40, 1.0, v45
	v_mul_f32_e32 v45, 0xbfb8aa3b, v73
	v_exp_f32_e32 v45, v45
	v_rcp_f32_e32 v48, v40
	v_mul_f32_e32 v26, 0xbfb8aa3b, v26
	v_exp_f32_e32 v26, v26
	v_add_f32_e32 v40, 1.0, v45
	v_rcp_f32_e32 v45, v40
	v_add_f32_e32 v40, 1.0, v47
	v_rcp_f32_e32 v47, v40
	v_cvt_pk_bf16_f32 v40, v12, v35
	v_mul_f32_e32 v12, 0xbfb8aa3b, v30
	v_exp_f32_e32 v12, v12
	v_add_f32_e32 v26, 1.0, v26
	v_mul_f32_e32 v30, 0xbfb8aa3b, v32
	v_mul_f32_e32 v28, 0xbfb8aa3b, v28
	v_add_f32_e32 v12, 1.0, v12
	v_cvt_pk_bf16_f32 v44, v44, v46
	v_or_b32_e32 v46, 16, v34
	v_rcp_f32_e32 v12, v12
	v_rcp_f32_e32 v26, v26
	v_exp_f32_e32 v30, v30
	v_exp_f32_e32 v28, v28
	v_cvt_pk_bf16_f32 v45, v45, v47
	v_ashrrev_i32_e32 v47, 31, v46
	v_lshlrev_b64 v[46:47], 13, v[46:47]
	v_cvt_pk_bf16_f32 v41, v41, v48
	v_lshl_add_u64 v[46:47], v[36:37], 0, v[46:47]
	global_store_dwordx4 v[46:47], v[38:41], off
	v_mul_f32_e32 v22, 0xbfb8aa3b, v22
	v_mul_f32_e32 v18, 0xbfb8aa3b, v18
	v_cvt_pk_bf16_f32 v38, v12, v26
	v_add_f32_e32 v12, 1.0, v30
	v_add_f32_e32 v26, 1.0, v28
	v_rcp_f32_e32 v12, v12
	v_rcp_f32_e32 v26, v26
	v_exp_f32_e32 v22, v22
	v_exp_f32_e32 v18, v18
	v_mul_f32_e32 v20, 0xbfb8aa3b, v20
	v_cvt_pk_bf16_f32 v26, v12, v26
	v_add_f32_e32 v12, 1.0, v22
	v_add_f32_e32 v18, 1.0, v18
	v_mul_f32_e32 v22, 0xbfb8aa3b, v24
	v_rcp_f32_e32 v12, v12
	v_rcp_f32_e32 v18, v18
	v_exp_f32_e32 v22, v22
	v_exp_f32_e32 v20, v20
	v_mul_f32_e32 v23, 0xbfb8aa3b, v23
	v_cvt_pk_bf16_f32 v39, v12, v18
; __device__ __forceinline__ float sigmoid_(float x) { return __builtin_amdgcn_rcpf(1.f + __expf(-x)); }
; __device__ __forceinline__ void gate_tile(int t, const bf16_t* xb, const bf16_t* Wg, bf16_t* G, bf16_t* sm) {
;     ...
; #pragma unroll
;     for (int mt = 0; mt < 4; ++mt) {
;         const int row = tm * 128 + wr * 64 + mt * 16 + fr;
;         const int cbase = tn * 128 + wc * 64 + fq * 16;
;         float v[16]; gather_cols<4>(acc, mt, v);
;         u32x4 o0, o1;
; #pragma unroll
;         for (int q = 0; q < 4; ++q) {
;             o0[q] = pack2(sigmoid_(v[2 * q]), sigmoid_(v[2 * q + 1]));
;             o1[q] = pack2(sigmoid_(v[8 + 2 * q]), sigmoid_(v[8 + 2 * q + 1]));
;         }
;         *(u32x4*)(G + (size_t)row * 4096 + cbase) = o0;
;         *(u32x4*)(G + (size_t)row * 4096 + cbase + 8) = o1;
;     }
	v_add_f32_e32 v12, 1.0, v22
	v_add_f32_e32 v18, 1.0, v20
	v_mul_f32_e32 v20, 0xbfb8aa3b, v31
	v_mul_f32_e32 v22, 0xbfb8aa3b, v27
	v_rcp_f32_e32 v12, v12
	v_rcp_f32_e32 v18, v18
	v_exp_f32_e32 v20, v20
	v_exp_f32_e32 v22, v22
	v_mul_f32_e32 v19, 0xbfb8aa3b, v19
	v_exp_f32_e32 v23, v23
	v_exp_f32_e32 v19, v19
	v_cvt_pk_bf16_f32 v27, v12, v18
	v_add_f32_e32 v12, 1.0, v20
	v_add_f32_e32 v18, 1.0, v22
	v_mul_f32_e32 v20, 0xbfb8aa3b, v33
	v_mul_f32_e32 v22, 0xbfb8aa3b, v29
	v_mul_f32_e32 v24, 0xbfb8aa3b, v25
	v_mul_f32_e32 v21, 0xbfb8aa3b, v21
	v_exp_f32_e32 v20, v20
	v_exp_f32_e32 v22, v22
	v_exp_f32_e32 v24, v24
	v_exp_f32_e32 v21, v21
	v_mul_f32_e32 v4, 0xbfb8aa3b, v4
	v_mul_f32_e32 v0, 0xbfb8aa3b, v0
	v_exp_f32_e32 v4, v4
	v_exp_f32_e32 v0, v0
	v_rcp_f32_e32 v12, v12
	v_rcp_f32_e32 v18, v18
	v_add_f32_e32 v23, 1.0, v23
	v_add_f32_e32 v19, 1.0, v19
	v_rcp_f32_e32 v23, v23
	v_rcp_f32_e32 v19, v19
	v_add_f32_e32 v20, 1.0, v20
	v_add_f32_e32 v22, 1.0, v22
	v_add_f32_e32 v24, 1.0, v24
	v_add_f32_e32 v21, 1.0, v21
	v_rcp_f32_e32 v20, v20
	v_rcp_f32_e32 v22, v22
	v_rcp_f32_e32 v24, v24
	v_rcp_f32_e32 v21, v21
	v_add_f32_e32 v4, 1.0, v4
	v_add_f32_e32 v0, 1.0, v0
	v_mul_f32_e32 v6, 0xbfb8aa3b, v6
	v_mul_f32_e32 v2, 0xbfb8aa3b, v2
	v_cvt_pk_bf16_f32 v40, v12, v18
	v_or_b32_e32 v18, 32, v34
	v_rcp_f32_e32 v4, v4
	v_rcp_f32_e32 v0, v0
	v_exp_f32_e32 v6, v6
	v_exp_f32_e32 v2, v2
	v_cvt_pk_bf16_f32 v41, v23, v19
	v_ashrrev_i32_e32 v19, 31, v18
	v_lshlrev_b64 v[18:19], 13, v[18:19]
	v_cvt_pk_bf16_f32 v28, v20, v22
	v_cvt_pk_bf16_f32 v29, v24, v21
	v_lshl_add_u64 v[18:19], v[36:37], 0, v[18:19]
	global_store_dwordx4 v[18:19], v[38:41], off
	v_mul_f32_e32 v12, 0xbfb8aa3b, v14
	v_mul_f32_e32 v8, 0xbfb8aa3b, v8
	global_store_dwordx4 v[18:19], v[26:29], off offset:16
	v_cvt_pk_bf16_f32 v19, v4, v0
	v_add_f32_e32 v0, 1.0, v6
	v_add_f32_e32 v2, 1.0, v2
	v_mul_f32_e32 v4, 0xbfb8aa3b, v15
	v_mul_f32_e32 v6, 0xbfb8aa3b, v9
	v_exp_f32_e32 v12, v12
	v_exp_f32_e32 v8, v8
	v_rcp_f32_e32 v0, v0
	v_rcp_f32_e32 v2, v2
	v_exp_f32_e32 v4, v4
	v_exp_f32_e32 v6, v6
	v_mul_f32_e32 v5, 0xbfb8aa3b, v5
	v_mul_f32_e32 v1, 0xbfb8aa3b, v1
	v_exp_f32_e32 v5, v5
	v_exp_f32_e32 v1, v1
	v_add_f32_e32 v12, 1.0, v12
	v_add_f32_e32 v8, 1.0, v8
	v_mul_f32_e32 v14, 0xbfb8aa3b, v16
	v_mul_f32_e32 v10, 0xbfb8aa3b, v10
	v_cvt_pk_bf16_f32 v9, v0, v2
	v_add_f32_e32 v0, 1.0, v4
	v_add_f32_e32 v2, 1.0, v6
	v_mul_f32_e32 v4, 0xbfb8aa3b, v17
	v_mul_f32_e32 v6, 0xbfb8aa3b, v11
	v_mul_f32_e32 v7, 0xbfb8aa3b, v7
	v_mul_f32_e32 v3, 0xbfb8aa3b, v3
	v_rcp_f32_e32 v12, v12
	v_rcp_f32_e32 v8, v8
	v_exp_f32_e32 v14, v14
	v_exp_f32_e32 v10, v10
	v_exp_f32_e32 v4, v4
	v_exp_f32_e32 v6, v6
	v_exp_f32_e32 v7, v7
	v_exp_f32_e32 v3, v3
	v_rcp_f32_e32 v0, v0
	v_rcp_f32_e32 v2, v2
	v_add_f32_e32 v5, 1.0, v5
	v_add_f32_e32 v1, 1.0, v1
	v_rcp_f32_e32 v5, v5
	v_rcp_f32_e32 v1, v1
	v_cvt_pk_bf16_f32 v18, v12, v8
	v_add_f32_e32 v8, 1.0, v14
	v_add_f32_e32 v10, 1.0, v10
	v_add_f32_e32 v4, 1.0, v4
	v_add_f32_e32 v6, 1.0, v6
	v_add_f32_e32 v7, 1.0, v7
	v_add_f32_e32 v3, 1.0, v3
	v_rcp_f32_e32 v8, v8
	v_rcp_f32_e32 v10, v10
	v_rcp_f32_e32 v4, v4
	v_rcp_f32_e32 v6, v6
	v_rcp_f32_e32 v7, v7
	v_rcp_f32_e32 v3, v3
	v_cvt_pk_bf16_f32 v20, v0, v2
	v_or_b32_e32 v0, 48, v34
	v_cvt_pk_bf16_f32 v21, v5, v1
	v_ashrrev_i32_e32 v1, 31, v0
	v_lshlrev_b64 v[0:1], 13, v[0:1]
	v_lshl_add_u64 v[0:1], v[36:37], 0, v[0:1]
	global_store_dwordx4 v[46:47], v[42:45], off offset:16
	v_cvt_pk_bf16_f32 v8, v8, v10
	v_cvt_pk_bf16_f32 v10, v4, v6
	v_cvt_pk_bf16_f32 v11, v7, v3
	global_store_dwordx4 v[0:1], v[18:21], off
	global_store_dwordx4 v[0:1], v[8:11], off offset:16
	s_mov_b64 s[12:13], 0

; __device__ __forceinline__ int tidx() { int t = threadIdx.x; asm volatile("" : "+v"(t)); return t; }
; template <int NT>
; __device__ __forceinline__ void gemm_tile(f32x4 (&acc)[4][NT], const bf16_t* A, int lda, const bf16_t* B, int ldb, int K, bf16_t* sm) {
;     const int tid_ = tidx();
;     bf16_t* sA = sm; bf16_t* sB = sm + 128 * LDT;
;     const int tid = tid_, lane = tid & 63, wid = tid >> 6, wr = wid >> 1, wc = wid & 1;
;     const int fr = lane & 15, fq = lane >> 4;
;     const int lrow = tid >> 3, lkc = tid & 7;
;     const bf16_t* ga = A + (size_t)lrow * lda + lkc * 8;
;     const bf16_t* gb = B + (size_t)lrow * ldb + lkc * 8;
;     int sbrow[NT];
; #pragma unroll
;     for (int i = 0; i < NT; ++i) { const int g = lrow + 32 * i, W_ = 16 * NT, rem = g % W_; sbrow[i] = (g / W_) * W_ + (rem % NT) * 16 + rem / NT; }
;     u32x4 ra0[4], rb0[NT];
; #pragma unroll
;     for (int i = 0; i < 4; ++i) ra0[i] = *(const u32x4*)(ga + (size_t)(32 * i) * lda);
; #pragma unroll
;     for (int i = 0; i < NT; ++i) rb0[i] = *(const u32x4*)(gb + (size_t)(32 * i) * ldb);
; __device__ __forceinline__ void phase_proj(const bf16_t* xb, const bf16_t* W, bf16_t* P, bf16_t* sm) {
;     const int tid_ = tidx();
;     const int lane = tid_ & 63, wid = tid_ >> 6, wr = wid >> 1, wc = wid & 1, fr = lane & 15, fq = lane >> 4;
;     for (int t = blockIdx.x; t < 136 * 37; t += gridDim.x) {
;         const int tm = t / 37, tn = t % 37;
;         f32x4 acc[4][4]; zero_acc<4>(acc);
;         gemm_tile<4>(acc, xb + (size_t)tm * 128 * 1024, 1024, W + (size_t)tn * 128 * 1024, 1024, 1024, sm);
.Lproj_map_done:
	s_mov_b32 s15, 0
	v_ashrrev_i32_e32 v0, 31, v38
	s_waitcnt vmcnt(6)
	v_ashrrev_i32_e32 v30, 3, v38
	v_lshrrev_b32_e32 v0, 26, v0
	v_add_u32_e32 v0, v30, v0
	v_lshrrev_b32_e32 v1, 6, v0
	v_mul_i32_i24_e32 v1, 64, v1
	v_sub_u32_e32 v1, v30, v1
	v_lshrrev_b16_sdwa v2, v196, sext(v1) dst_sel:DWORD dst_unused:UNUSED_PAD src0_sel:DWORD src1_sel:BYTE_0
	v_and_b32_e32 v2, 3, v2
	v_add_u16_e32 v2, v1, v2
	v_ashrrev_i16_sdwa v3, v197, sext(v2) dst_sel:DWORD dst_unused:UNUSED_PAD src0_sel:DWORD src1_sel:BYTE_0
	v_and_b32_e32 v2, 0xfc, v2
	v_sub_u16_e32 v1, v1, v2
	v_and_b32_e32 v0, 0x7ffffc0, v0
	v_lshlrev_b32_sdwa v1, v198, sext(v1) dst_sel:DWORD dst_unused:UNUSED_PAD src0_sel:DWORD src1_sel:BYTE_0
	v_bfe_i32 v2, v3, 0, 16
	v_add3_u32 v39, v0, v2, v1
	v_add_u32_e32 v0, 32, v30
	v_ashrrev_i32_e32 v1, 31, v0
	v_lshrrev_b32_e32 v1, 26, v1
	v_add_u32_e32 v1, v0, v1
	v_lshrrev_b32_e32 v2, 6, v1
	v_mul_i32_i24_e32 v2, 64, v2
	v_sub_u32_e32 v0, v0, v2
	v_lshrrev_b16_sdwa v2, v196, sext(v0) dst_sel:DWORD dst_unused:UNUSED_PAD src0_sel:DWORD src1_sel:BYTE_0
	v_and_b32_e32 v2, 3, v2
	v_add_u16_e32 v2, v0, v2
	v_ashrrev_i16_sdwa v3, v197, sext(v2) dst_sel:DWORD dst_unused:UNUSED_PAD src0_sel:DWORD src1_sel:BYTE_0
	v_and_b32_e32 v2, 0xfc, v2
	v_sub_u16_e32 v0, v0, v2
	v_and_b32_e32 v1, 0x7ffffc0, v1
	v_lshlrev_b32_sdwa v0, v198, sext(v0) dst_sel:DWORD dst_unused:UNUSED_PAD src0_sel:DWORD src1_sel:BYTE_0
	v_bfe_i32 v2, v3, 0, 16
	v_add3_u32 v40, v1, v2, v0
	v_add_u32_e32 v0, 64, v30
	v_ashrrev_i32_e32 v1, 31, v0
	v_lshrrev_b32_e32 v1, 26, v1
	v_add_u32_e32 v1, v0, v1
	v_lshrrev_b32_e32 v2, 6, v1
	v_mul_i32_i24_e32 v2, 64, v2
	v_sub_u32_e32 v0, v0, v2
	v_lshrrev_b16_sdwa v2, v196, sext(v0) dst_sel:DWORD dst_unused:UNUSED_PAD src0_sel:DWORD src1_sel:BYTE_0
	v_and_b32_e32 v2, 3, v2
	v_add_u16_e32 v2, v0, v2
	v_ashrrev_i16_sdwa v3, v197, sext(v2) dst_sel:DWORD dst_unused:UNUSED_PAD src0_sel:DWORD src1_sel:BYTE_0
	v_and_b32_e32 v2, 0xfc, v2
	v_sub_u16_e32 v0, v0, v2
	v_and_b32_e32 v1, 0x7ffffc0, v1
	v_lshlrev_b32_sdwa v0, v198, sext(v0) dst_sel:DWORD dst_unused:UNUSED_PAD src0_sel:DWORD src1_sel:BYTE_0
	v_bfe_i32 v2, v3, 0, 16
	s_waitcnt lgkmcnt(0)
	v_add3_u32 v41, v1, v2, v0
	v_add_u32_e32 v0, 0x60, v30
	v_ashrrev_i32_e32 v1, 31, v0
	v_lshrrev_b32_e32 v1, 26, v1
	v_add_u32_e32 v1, v0, v1
	v_lshrrev_b32_e32 v2, 6, v1
	v_mul_i32_i24_e32 v2, 64, v2
	v_sub_u32_e32 v0, v0, v2
	v_lshrrev_b16_sdwa v2, v196, sext(v0) dst_sel:DWORD dst_unused:UNUSED_PAD src0_sel:DWORD src1_sel:BYTE_0
	s_lshl_b64 s[22:23], s[14:15], 18
	v_and_b32_e32 v2, 3, v2
	s_add_u32 s40, s80, s22
	v_add_u16_e32 v2, v0, v2
	s_addc_u32 s41, s81, s23
	s_ashr_i32 s19, s18, 31
	v_ashrrev_i16_sdwa v3, v197, sext(v2) dst_sel:DWORD dst_unused:UNUSED_PAD src0_sel:DWORD src1_sel:BYTE_0
	v_and_b32_e32 v2, 0xfc, v2
	s_lshl_b64 s[24:25], s[18:19], 18
	v_sub_u16_e32 v0, v0, v2
	s_add_u32 s42, s11, s24
	v_and_b32_e32 v1, 0x7ffffc0, v1
	v_lshlrev_b32_sdwa v0, v198, sext(v0) dst_sel:DWORD dst_unused:UNUSED_PAD src0_sel:DWORD src1_sel:BYTE_0
	v_bfe_i32 v2, v3, 0, 16
	v_ashrrev_i32_e32 v31, 31, v30
	s_addc_u32 s43, s12, s25
	v_add3_u32 v42, v1, v2, v0
	v_lshlrev_b64 v[32:33], 11, v[30:31]
	v_lshlrev_b32_e32 v2, 4, v38
	v_lshl_add_u64 v[0:1], s[42:43], 0, v[32:33]
	v_and_b32_e32 v12, 0x70, v2
	v_lshl_add_u64 v[8:9], v[0:1], 0, v[12:13]
	v_add_co_u32_e32 v0, vcc, s7, v8
	v_and_b32_e32 v31, 15, v38
	s_nop 0
	v_addc_co_u32_e32 v1, vcc, 0, v9, vcc
	v_add_co_u32_e32 v10, vcc, s37, v8
	v_mov_b32_e32 v250, v8
	v_mov_b32_e32 v251, v9
	s_nop 0
	v_addc_co_u32_e32 v11, vcc, 0, v9, vcc
	v_add_co_u32_e32 v14, vcc, s73, v8
	v_lshrrev_b32_e32 v44, 1, v38
	s_nop 0
	v_addc_co_u32_e32 v15, vcc, 0, v9, vcc
	s_nop 0
	v_lshl_add_u64 v[14:15], s[40:41], 0, v[32:33]
	v_lshl_add_u64 v[26:27], v[14:15], 0, v[12:13]
	v_add_co_u32_e32 v14, vcc, s7, v26
	v_and_or_b32 v31, v44, s3, v31
	s_nop 0
	v_addc_co_u32_e32 v15, vcc, 0, v27, vcc
	v_add_co_u32_e32 v28, vcc, s37, v26
	v_mov_b32_e32 v248, v26
	v_mov_b32_e32 v249, v27
	s_nop 0
	v_addc_co_u32_e32 v29, vcc, 0, v27, vcc
	v_add_co_u32_e32 v34, vcc, s73, v26
	v_mul_lo_u32 v44, v31, s89
	s_nop 0
	v_addc_co_u32_e32 v35, vcc, 0, v27, vcc
	s_nop 0
	v_mul_lo_u32 v45, v30, s89
	v_lshl_add_u64 v[30:31], s[22:23], 0, v[32:33]
	v_or_b32_e32 v30, v30, v12
	v_lshl_add_u64 v[98:99], s[58:59], 0, v[30:31]
	v_lshl_add_u64 v[30:31], s[24:25], 0, v[32:33]
	v_and_b32_e32 v43, 48, v38
	v_and_b32_e32 v38, 0x4f, v38
	v_or_b32_e32 v30, v30, v12
	v_mul_u32_u24_e32 v38, 0xa0, v38
	v_mul_lo_u32 v39, v39, s89
	v_mul_lo_u32 v40, v40, s89
	v_mul_lo_u32 v41, v41, s89
	v_mul_lo_u32 v42, v42, s89
	v_lshl_add_u64 v[100:101], s[58:59], 0, v[30:31]
	v_mov_b32_e32 v30, 0
	s_mov_b64 s[22:23], 0
	v_add_u32_e32 v105, v12, v45
	v_add_u32_e32 v106, v12, v39
	v_add_u32_e32 v107, v12, v40
	v_add_u32_e32 v108, v12, v41
	v_add_u32_e32 v109, v12, v42
	v_add_u32_e32 v104, v43, v44
	v_add_u32_e32 v12, v43, v38
; __device__ __forceinline__ int tidx() { int t = threadIdx.x; asm volatile("" : "+v"(t)); return t; }
; template <int NT>
; __device__ __forceinline__ void gemm_tile(f32x4 (&acc)[4][NT], const bf16_t* A, int lda, const bf16_t* B, int ldb, int K, bf16_t* sm) {
;     const int tid_ = tidx();
;     bf16_t* sA = sm; bf16_t* sB = sm + 128 * LDT;
;     const int tid = tid_, lane = tid & 63, wid = tid >> 6, wr = wid >> 1, wc = wid & 1;
;     const int fr = lane & 15, fq = lane >> 4;
;     const int lrow = tid >> 3, lkc = tid & 7;
;     const bf16_t* ga = A + (size_t)lrow * lda + lkc * 8;
;     const bf16_t* gb = B + (size_t)lrow * ldb + lkc * 8;
;     int sbrow[NT];
; #pragma unroll
;     for (int i = 0; i < NT; ++i) { const int g = lrow + 32 * i, W_ = 16 * NT, rem = g % W_; sbrow[i] = (g / W_) * W_ + (rem % NT) * 16 + rem / NT; }
;     u32x4 ra0[4], rb0[NT];
; #pragma unroll
;     for (int i = 0; i < 4; ++i) ra0[i] = *(const u32x4*)(ga + (size_t)(32 * i) * lda);
; #pragma unroll
;     for (int i = 0; i < NT; ++i) rb0[i] = *(const u32x4*)(gb + (size_t)(32 * i) * ldb);
;     const int nk = K >> 6;
;     for (int kt = 0; kt < nk; ++kt) {
;         lds_barrier();
; #pragma unroll
;         for (int i = 0; i < 4; ++i) *(u32x4*)(sA + (lrow + 32 * i) * LDT + lkc * 8) = ra0[i];
; #pragma unroll
;         for (int i = 0; i < NT; ++i) *(u32x4*)(sB + sbrow[i] * LDT + lkc * 8) = rb0[i];
;         lds_barrier();
	v_mov_b32_e32 v31, v30
	v_mov_b32_e32 v32, v30
	v_mov_b32_e32 v33, v30
	v_mov_b32_e32 v38, v30
	v_mov_b32_e32 v39, v30
	v_mov_b32_e32 v40, v30
	v_mov_b32_e32 v41, v30
	v_mov_b32_e32 v42, v30
	v_mov_b32_e32 v43, v30
	v_mov_b32_e32 v44, v30
	v_mov_b32_e32 v45, v30
	v_mov_b32_e32 v46, v30
	v_mov_b32_e32 v47, v30
	v_mov_b32_e32 v48, v30
	v_mov_b32_e32 v49, v30
	v_mov_b32_e32 v50, v30
	v_mov_b32_e32 v51, v30
	v_mov_b32_e32 v52, v30
	v_mov_b32_e32 v53, v30
	v_mov_b32_e32 v54, v30
	v_mov_b32_e32 v55, v30
	v_mov_b32_e32 v56, v30
	v_mov_b32_e32 v57, v30
	v_mov_b32_e32 v58, v30
	v_mov_b32_e32 v59, v30
	v_mov_b32_e32 v60, v30
	v_mov_b32_e32 v61, v30
	v_mov_b32_e32 v62, v30
	v_mov_b32_e32 v63, v30
	v_mov_b32_e32 v64, v30
	v_mov_b32_e32 v65, v30
	v_mov_b32_e32 v66, v30
	v_mov_b32_e32 v67, v30
	v_mov_b32_e32 v68, v30
	v_mov_b32_e32 v69, v30
	v_mov_b32_e32 v70, v30
	v_mov_b32_e32 v71, v30
	v_mov_b32_e32 v72, v30
	v_mov_b32_e32 v73, v30
	v_mov_b32_e32 v74, v30
	v_mov_b32_e32 v75, v30
	v_mov_b32_e32 v76, v30
	v_mov_b32_e32 v77, v30
	v_mov_b32_e32 v78, v30
	v_mov_b32_e32 v79, v30
	v_mov_b32_e32 v80, v30
	v_mov_b32_e32 v81, v30
	v_mov_b32_e32 v82, v30
	v_mov_b32_e32 v83, v30
	v_mov_b32_e32 v84, v30
	v_mov_b32_e32 v85, v30
	v_mov_b32_e32 v86, v30
	v_mov_b32_e32 v87, v30
	v_mov_b32_e32 v88, v30
	v_mov_b32_e32 v89, v30
	v_mov_b32_e32 v90, v30
	v_mov_b32_e32 v91, v30
	v_mov_b32_e32 v92, v30
	v_mov_b32_e32 v93, v30
	v_mov_b32_e32 v94, v30
	v_mov_b32_e32 v95, v30
	v_mov_b32_e32 v96, v30
	v_mov_b32_e32 v97, v30
	v_writelane_b32 v234, s90, 0
	v_writelane_b32 v234, s91, 1
	v_writelane_b32 v234, s92, 2
	v_writelane_b32 v234, s93, 3
	v_writelane_b32 v234, s94, 4
	v_writelane_b32 v234, s95, 5
	v_bfe_u32 v160, v192, 3, 3
	v_and_b32_e32 v161, 7, v192
	v_xor_b32_e32 v161, v160, v161
	v_lshlrev_b32_e32 v161, 4, v161
	v_lshrrev_b32_e32 v162, 6, v192
	v_lshl_add_u32 v163, v162, 5, v160
	v_mul_u32_u24_e32 v163, 0x800, v163
	v_add_u32_e32 v236, v163, v161
	v_add_u32_e32 v237, 0x3c00, v236
	v_add_u32_e32 v238, 0x3c00, v237
	v_add_u32_e32 v239, 0x3c00, v238
	v_lshrrev_b32_e32 v163, 7, v192
	v_bfe_u32 v162, v192, 6, 1
	v_lshlrev_b32_e32 v163, 6, v163
	v_lshl_add_u32 v163, v160, 2, v163
	v_lshl_add_u32 v163, v162, 1, v163
	v_mul_u32_u24_e32 v163, 0x800, v163
	v_add_u32_e32 v240, v163, v161
	v_add_u32_e32 v241, 0xfc00, v240
	v_subrev_u32_e32 v242, 0xfc00, v241
	v_add_u32_e32 v243, 0xfc00, v242
	v_and_b32_e32 v160, 15, v192
	v_bfe_u32 v161, v192, 4, 2
	v_and_b32_e32 v162, 7, v160
	v_xor_b32_e32 v161, v161, v162
	v_lshlrev_b32_e32 v161, 4, v161
	v_lshl_add_u32 v161, v160, 7, v161
	v_lshrrev_b32_e32 v162, 7, v192
	v_lshl_add_u32 v244, v162, 13, v161
	v_bfe_u32 v162, v192, 6, 1
	v_lshl_add_u32 v246, v162, 13, v161
	v_add_u32_e32 v246, 0x4000, v246
	v_xor_b32_e32 v245, 64, v244
	v_xor_b32_e32 v247, 64, v246
	v_lshrrev_b32_e32 v160, 6, v192
	s_nop 0
	v_readfirstlane_b32 s94, v160
	v_readfirstlane_b32 s90, v248
	v_readfirstlane_b32 s91, v249
	v_readfirstlane_b32 s92, v250
	v_readfirstlane_b32 s93, v251
	s_mul_i32 s95, s94, 0x4000
	s_sub_u32 s90, s90, s95
	s_subb_u32 s91, s91, 0
	s_mul_i32 s95, s94, 0x4000
	s_sub_u32 s92, s92, s95
	s_subb_u32 s93, s93, 0
	s_lshl_b32 s94, s94, 10
	s_waitcnt lgkmcnt(0)
	s_barrier
	s_lshl_b32 s95, s94, 2
	s_add_u32 m0, s95, 0x0
	s_nop 0
	global_load_lds_dwordx4 v236, s[90:91] sc1
	global_load_lds_dwordx4 v237, s[90:91] offset:1024 sc1
	global_load_lds_dwordx4 v238, s[90:91] offset:2048 sc1
	global_load_lds_dwordx4 v239, s[90:91] offset:3072 sc1
	s_mul_i32 s95, s94, 4
	s_add_u32 m0, s95, 0x4000
	s_nop 0
	global_load_lds_dwordx4 v240, s[92:93]
	global_load_lds_dwordx4 v241, s[92:93] offset:1024
	global_load_lds_dwordx4 v242, s[92:93] offset:2048
	global_load_lds_dwordx4 v243, s[92:93] offset:3072
	s_add_u32 s90, s90, 0x80
	s_addc_u32 s91, s91, 0
	s_add_u32 s92, s92, 0x80
	s_addc_u32 s93, s93, 0
	s_waitcnt vmcnt(0)
	s_barrier
	s_lshl_b32 s95, s94, 2
	s_add_u32 m0, s95, 0x8000
	s_nop 0
	global_load_lds_dwordx4 v236, s[90:91] sc1
	global_load_lds_dwordx4 v237, s[90:91] offset:1024 sc1
	global_load_lds_dwordx4 v238, s[90:91] offset:2048 sc1
	global_load_lds_dwordx4 v239, s[90:91] offset:3072 sc1
	s_mul_i32 s95, s94, 4
	s_add_u32 m0, s95, 0xc000
	s_nop 0
	global_load_lds_dwordx4 v240, s[92:93]
	global_load_lds_dwordx4 v241, s[92:93] offset:1024
	global_load_lds_dwordx4 v242, s[92:93] offset:2048
	global_load_lds_dwordx4 v243, s[92:93] offset:3072
	s_add_u32 s90, s90, 0x80
	s_addc_u32 s91, s91, 0
	s_add_u32 s92, s92, 0x80
	s_addc_u32 s93, s93, 0
	ds_read_b128 v[110:113], v244 offset:0
	ds_read_b128 v[114:117], v244 offset:2048
	ds_read_b128 v[118:121], v244 offset:4096
	ds_read_b128 v[122:125], v244 offset:6144
	ds_read_b128 v[126:129], v246 offset:0
	ds_read_b128 v[130:133], v246 offset:2048
	ds_read_b128 v[134:137], v246 offset:4096
	ds_read_b128 v[138:141], v246 offset:6144
	s_movk_i32 s95, 0x6
	s_cmp_eq_u32 s95, 0
	s_cbranch_scc1 .Lgemm_x465

; template <int NT>
; __device__ __forceinline__ void gemm_compute(f32x4 (&acc)[4][NT], const bf16_t* sA, const bf16_t* sB, int wr, int wc, int fr, int fq) {
; #pragma unroll
;     for (int ks = 0; ks < 2; ++ks) {
;         bf16x8 a[4], b[NT];
; #pragma unroll
;         for (int mt = 0; mt < 4; ++mt) a[mt] = *(const bf16x8*)(sA + (wr * 64 + mt * 16 + fr) * LDT + ks * 32 + fq * 8);
; #pragma unroll
;         for (int nt = 0; nt < NT; ++nt) b[nt] = *(const bf16x8*)(sB + (wc * 16 * NT + nt * 16 + fr) * LDT + ks * 32 + fq * 8);
;         __builtin_amdgcn_s_setprio(1);
; #pragma unroll
;         for (int mt = 0; mt < 4; ++mt)
; #pragma unroll
;             for (int nt = 0; nt < NT; ++nt)
;                 acc[mt][nt] = __builtin_amdgcn_mfma_f32_16x16x32_bf16(b[nt], a[mt], acc[mt][nt], 0, 0, 0);
;         __builtin_amdgcn_s_setprio(0);
;     }
; template <int NT>
; __device__ __forceinline__ void gemm_tile(f32x4 (&acc)[4][NT], const bf16_t* A, int lda, const bf16_t* B, int ldb, int K, bf16_t* sm) {
;     ...
;     for (int kt = 0; kt < nk; ++kt) {
;         lds_barrier();
; #pragma unroll
;         for (int i = 0; i < 4; ++i) *(u32x4*)(sA + (lrow + 32 * i) * LDT + lkc * 8) = ra0[i];
; #pragma unroll
;         for (int i = 0; i < NT; ++i) *(u32x4*)(sB + sbrow[i] * LDT + lkc * 8) = rb0[i];
;         lds_barrier();
;         if (kt + 1 < nk) {
;             ga += 64; gb += 64;
; #pragma unroll
;             for (int i = 0; i < 4; ++i) ra0[i] = *(const u32x4*)(ga + (size_t)(32 * i) * lda);
; #pragma unroll
;             for (int i = 0; i < NT; ++i) rb0[i] = *(const u32x4*)(gb + (size_t)(32 * i) * ldb);
;         }
;         __builtin_amdgcn_sched_barrier(0);
;         gemm_compute<NT>(acc, sA, sB, wr, wc, fr, fq);
.Lgemm_x465:
	ds_read_b128 v[160:163], v245 offset:0
	ds_read_b128 v[164:167], v245 offset:2048
	ds_read_b128 v[168:171], v245 offset:4096
	ds_read_b128 v[172:175], v245 offset:6144
	ds_read_b128 v[176:179], v247 offset:0
	ds_read_b128 v[180:183], v247 offset:2048
	ds_read_b128 v[184:187], v247 offset:4096
	ds_read_b128 v[188:191], v247 offset:6144
	s_setprio 1
	s_waitcnt lgkmcnt(11)
	v_mfma_f32_16x16x32_bf16 v[94:97], v[126:129], v[110:113], v[94:97]
	s_waitcnt lgkmcnt(10)
	v_mfma_f32_16x16x32_bf16 v[90:93], v[130:133], v[110:113], v[90:93]
	s_waitcnt lgkmcnt(9)
	v_mfma_f32_16x16x32_bf16 v[86:89], v[134:137], v[110:113], v[86:89]
	s_waitcnt lgkmcnt(8)
	v_mfma_f32_16x16x32_bf16 v[82:85], v[138:141], v[110:113], v[82:85]
	v_mfma_f32_16x16x32_bf16 v[78:81], v[126:129], v[114:117], v[78:81]
	v_mfma_f32_16x16x32_bf16 v[74:77], v[130:133], v[114:117], v[74:77]
	v_mfma_f32_16x16x32_bf16 v[70:73], v[134:137], v[114:117], v[70:73]
	v_mfma_f32_16x16x32_bf16 v[66:69], v[138:141], v[114:117], v[66:69]
	v_mfma_f32_16x16x32_bf16 v[62:65], v[126:129], v[118:121], v[62:65]
	v_mfma_f32_16x16x32_bf16 v[58:61], v[130:133], v[118:121], v[58:61]
	v_mfma_f32_16x16x32_bf16 v[54:57], v[134:137], v[118:121], v[54:57]
	v_mfma_f32_16x16x32_bf16 v[50:53], v[138:141], v[118:121], v[50:53]
	v_mfma_f32_16x16x32_bf16 v[46:49], v[126:129], v[122:125], v[46:49]
	v_mfma_f32_16x16x32_bf16 v[42:45], v[130:133], v[122:125], v[42:45]
	v_mfma_f32_16x16x32_bf16 v[38:41], v[134:137], v[122:125], v[38:41]
	v_mfma_f32_16x16x32_bf16 v[30:33], v[138:141], v[122:125], v[30:33]
	s_setprio 0
	s_waitcnt vmcnt(0) lgkmcnt(0)
	s_barrier
	ds_read_b128 v[110:113], v244 offset:32768
	ds_read_b128 v[114:117], v244 offset:34816
	ds_read_b128 v[118:121], v244 offset:36864
	ds_read_b128 v[122:125], v244 offset:38912
	ds_read_b128 v[126:129], v246 offset:32768
	ds_read_b128 v[130:133], v246 offset:34816
	ds_read_b128 v[134:137], v246 offset:36864
	ds_read_b128 v[138:141], v246 offset:38912
	s_setprio 1
	v_mfma_f32_16x16x32_bf16 v[94:97], v[176:179], v[160:163], v[94:97]
	s_lshl_b32 s95, s94, 2
	s_add_u32 m0, s95, 0x0
	s_nop 0
	global_load_lds_dwordx4 v236, s[90:91] sc1
	v_mfma_f32_16x16x32_bf16 v[90:93], v[180:183], v[160:163], v[90:93]
	v_mfma_f32_16x16x32_bf16 v[86:89], v[184:187], v[160:163], v[86:89]
	global_load_lds_dwordx4 v237, s[90:91] offset:1024 sc1
	v_mfma_f32_16x16x32_bf16 v[82:85], v[188:191], v[160:163], v[82:85]
	v_mfma_f32_16x16x32_bf16 v[78:81], v[176:179], v[164:167], v[78:81]
	global_load_lds_dwordx4 v238, s[90:91] offset:2048 sc1
	v_mfma_f32_16x16x32_bf16 v[74:77], v[180:183], v[164:167], v[74:77]
	v_mfma_f32_16x16x32_bf16 v[70:73], v[184:187], v[164:167], v[70:73]
	global_load_lds_dwordx4 v239, s[90:91] offset:3072 sc1
	v_mfma_f32_16x16x32_bf16 v[66:69], v[188:191], v[164:167], v[66:69]
	v_mfma_f32_16x16x32_bf16 v[62:65], v[176:179], v[168:171], v[62:65]
	s_mul_i32 s95, s94, 4
	s_add_u32 m0, s95, 0x4000
	s_nop 0
	global_load_lds_dwordx4 v240, s[92:93]
	v_mfma_f32_16x16x32_bf16 v[58:61], v[180:183], v[168:171], v[58:61]
	v_mfma_f32_16x16x32_bf16 v[54:57], v[184:187], v[168:171], v[54:57]
	global_load_lds_dwordx4 v241, s[92:93] offset:1024
	v_mfma_f32_16x16x32_bf16 v[50:53], v[188:191], v[168:171], v[50:53]
	v_mfma_f32_16x16x32_bf16 v[46:49], v[176:179], v[172:175], v[46:49]
	global_load_lds_dwordx4 v242, s[92:93] offset:2048
	v_mfma_f32_16x16x32_bf16 v[42:45], v[180:183], v[172:175], v[42:45]
	v_mfma_f32_16x16x32_bf16 v[38:41], v[184:187], v[172:175], v[38:41]
	global_load_lds_dwordx4 v243, s[92:93] offset:3072
	v_mfma_f32_16x16x32_bf16 v[30:33], v[188:191], v[172:175], v[30:33]
	s_add_u32 s90, s90, 0x80
	s_addc_u32 s91, s91, 0
	s_add_u32 s92, s92, 0x80
	s_addc_u32 s93, s93, 0
	s_setprio 0
	ds_read_b128 v[160:163], v245 offset:32768
	ds_read_b128 v[164:167], v245 offset:34816
	ds_read_b128 v[168:171], v245 offset:36864
	ds_read_b128 v[172:175], v245 offset:38912
	ds_read_b128 v[176:179], v247 offset:32768
	ds_read_b128 v[180:183], v247 offset:34816
	ds_read_b128 v[184:187], v247 offset:36864
	ds_read_b128 v[188:191], v247 offset:38912
	s_setprio 1
	s_waitcnt lgkmcnt(11)
	v_mfma_f32_16x16x32_bf16 v[94:97], v[126:129], v[110:113], v[94:97]
	s_waitcnt lgkmcnt(10)
	v_mfma_f32_16x16x32_bf16 v[90:93], v[130:133], v[110:113], v[90:93]
	s_waitcnt lgkmcnt(9)
	v_mfma_f32_16x16x32_bf16 v[86:89], v[134:137], v[110:113], v[86:89]
	s_waitcnt lgkmcnt(8)
	v_mfma_f32_16x16x32_bf16 v[82:85], v[138:141], v[110:113], v[82:85]
	v_mfma_f32_16x16x32_bf16 v[78:81], v[126:129], v[114:117], v[78:81]
	v_mfma_f32_16x16x32_bf16 v[74:77], v[130:133], v[114:117], v[74:77]
	v_mfma_f32_16x16x32_bf16 v[70:73], v[134:137], v[114:117], v[70:73]
	v_mfma_f32_16x16x32_bf16 v[66:69], v[138:141], v[114:117], v[66:69]
	v_mfma_f32_16x16x32_bf16 v[62:65], v[126:129], v[118:121], v[62:65]
	v_mfma_f32_16x16x32_bf16 v[58:61], v[130:133], v[118:121], v[58:61]
	v_mfma_f32_16x16x32_bf16 v[54:57], v[134:137], v[118:121], v[54:57]
	v_mfma_f32_16x16x32_bf16 v[50:53], v[138:141], v[118:121], v[50:53]
	v_mfma_f32_16x16x32_bf16 v[46:49], v[126:129], v[122:125], v[46:49]
	v_mfma_f32_16x16x32_bf16 v[42:45], v[130:133], v[122:125], v[42:45]
	v_mfma_f32_16x16x32_bf16 v[38:41], v[134:137], v[122:125], v[38:41]
	v_mfma_f32_16x16x32_bf16 v[30:33], v[138:141], v[122:125], v[30:33]
	s_setprio 0
	s_waitcnt vmcnt(0) lgkmcnt(0)
	s_barrier
; template <int NT>
; __device__ __forceinline__ void gemm_tile(f32x4 (&acc)[4][NT], const bf16_t* A, int lda, const bf16_t* B, int ldb, int K, bf16_t* sm) {
;     ...
;         if (kt + 1 < nk) {
;             ga += 64; gb += 64;
; #pragma unroll
;             for (int i = 0; i < 4; ++i) ra0[i] = *(const u32x4*)(ga + (size_t)(32 * i) * lda);
; #pragma unroll
;             for (int i = 0; i < NT; ++i) rb0[i] = *(const u32x4*)(gb + (size_t)(32 * i) * ldb);
;         }
;         __builtin_amdgcn_sched_barrier(0);
;         gemm_compute<NT>(acc, sA, sB, wr, wc, fr, fq);
	ds_read_b128 v[110:113], v244 offset:0
	ds_read_b128 v[114:117], v244 offset:2048
	ds_read_b128 v[118:121], v244 offset:4096
	ds_read_b128 v[122:125], v244 offset:6144
	ds_read_b128 v[126:129], v246 offset:0
	ds_read_b128 v[130:133], v246 offset:2048
	ds_read_b128 v[134:137], v246 offset:4096
	ds_read_b128 v[138:141], v246 offset:6144
	s_setprio 1
	v_mfma_f32_16x16x32_bf16 v[94:97], v[176:179], v[160:163], v[94:97]
	v_readlane_b32 s90, v234, 0
	v_readlane_b32 s91, v234, 1
	v_readlane_b32 s92, v234, 2
	v_readlane_b32 s93, v234, 3
	v_readlane_b32 s94, v234, 4
	v_readlane_b32 s95, v234, 5
	s_mov_b32 s22, 0x700
	s_mov_b32 s23, 0
	s_nop 3
	v_mfma_f32_16x16x32_bf16 v[90:93], v[180:183], v[160:163], v[90:93]
	v_mfma_f32_16x16x32_bf16 v[86:89], v[184:187], v[160:163], v[86:89]
	v_lshl_add_u64 v[0:1], v[98:99], 0, s[22:23]
	v_mfma_f32_16x16x32_bf16 v[82:85], v[188:191], v[160:163], v[82:85]
	v_mfma_f32_16x16x32_bf16 v[78:81], v[176:179], v[164:167], v[78:81]
	v_add_co_u32_e32 v2, vcc, s0, v0
	v_mfma_f32_16x16x32_bf16 v[74:77], v[180:183], v[164:167], v[74:77]
	v_mfma_f32_16x16x32_bf16 v[70:73], v[184:187], v[164:167], v[70:73]
	s_nop 0
	v_mfma_f32_16x16x32_bf16 v[66:69], v[188:191], v[164:167], v[66:69]
	v_mfma_f32_16x16x32_bf16 v[62:65], v[176:179], v[168:171], v[62:65]
	s_nop 0
	v_mfma_f32_16x16x32_bf16 v[58:61], v[180:183], v[168:171], v[58:61]
	v_mfma_f32_16x16x32_bf16 v[54:57], v[184:187], v[168:171], v[54:57]
	v_addc_co_u32_e32 v3, vcc, 0, v1, vcc
	v_mfma_f32_16x16x32_bf16 v[50:53], v[188:191], v[168:171], v[50:53]
	v_mfma_f32_16x16x32_bf16 v[46:49], v[176:179], v[172:175], v[46:49]
	v_add_co_u32_e32 v4, vcc, s64, v0
	v_mfma_f32_16x16x32_bf16 v[42:45], v[180:183], v[172:175], v[42:45]
	v_mfma_f32_16x16x32_bf16 v[38:41], v[184:187], v[172:175], v[38:41]
	v_lshl_add_u64 v[8:9], v[100:101], 0, s[22:23]
	v_mfma_f32_16x16x32_bf16 v[30:33], v[188:191], v[172:175], v[30:33]
	s_nop 0
	v_addc_co_u32_e32 v5, vcc, 0, v1, vcc
	global_load_dwordx4 v[18:21], v[2:3], off offset:128
	global_load_dwordx4 v[14:17], v[4:5], off offset:128
	v_add_co_u32_e32 v2, vcc, s65, v0
	s_mov_b32 s2, 0x1800000
	s_nop 0
	v_addc_co_u32_e32 v3, vcc, 0, v1, vcc
	v_add_co_u32_e32 v0, vcc, s33, v0
	s_nop 1
	v_addc_co_u32_e32 v1, vcc, 0, v1, vcc
	global_load_dwordx4 v[26:29], v[2:3], off offset:128
	global_load_dwordx4 v[34:37], v[0:1], off offset:128
	v_add_co_u32_e32 v0, vcc, s2, v8
	s_mov_b32 s2, 0x1810000
	s_nop 0
	v_addc_co_u32_e32 v1, vcc, 0, v9, vcc
	v_add_co_u32_e32 v2, vcc, s2, v8
	s_mov_b32 s2, 0x1820000
	s_nop 0
	v_addc_co_u32_e32 v3, vcc, 0, v9, vcc
	v_add_co_u32_e32 v10, vcc, s2, v8
	s_mov_b32 s2, 0x1830000
	s_nop 0
	v_addc_co_u32_e32 v11, vcc, 0, v9, vcc
	v_add_co_u32_e32 v22, vcc, s2, v8
	global_load_dwordx4 v[4:7], v[0:1], off offset:128
	s_nop 0
	global_load_dwordx4 v[0:3], v[2:3], off offset:128
	v_addc_co_u32_e32 v23, vcc, 0, v9, vcc
	global_load_dwordx4 v[8:11], v[10:11], off offset:128
	s_nop 0
	global_load_dwordx4 v[22:25], v[22:23], off offset:128
	s_setprio 0
	ds_read_b128 v[160:163], v245 offset:0
	ds_read_b128 v[164:167], v245 offset:2048
	ds_read_b128 v[168:171], v245 offset:4096
	ds_read_b128 v[172:175], v245 offset:6144
	ds_read_b128 v[176:179], v247 offset:0
	ds_read_b128 v[180:183], v247 offset:2048
	ds_read_b128 v[184:187], v247 offset:4096
	ds_read_b128 v[188:191], v247 offset:6144
	s_setprio 1
	s_waitcnt lgkmcnt(11)
	v_mfma_f32_16x16x32_bf16 v[94:97], v[126:129], v[110:113], v[94:97]
	s_waitcnt lgkmcnt(10)
	v_mfma_f32_16x16x32_bf16 v[90:93], v[130:133], v[110:113], v[90:93]
	s_waitcnt lgkmcnt(9)
	v_mfma_f32_16x16x32_bf16 v[86:89], v[134:137], v[110:113], v[86:89]
	s_waitcnt lgkmcnt(8)
	v_mfma_f32_16x16x32_bf16 v[82:85], v[138:141], v[110:113], v[82:85]
	v_mfma_f32_16x16x32_bf16 v[78:81], v[126:129], v[114:117], v[78:81]
	v_mfma_f32_16x16x32_bf16 v[74:77], v[130:133], v[114:117], v[74:77]
	v_mfma_f32_16x16x32_bf16 v[70:73], v[134:137], v[114:117], v[70:73]
	v_mfma_f32_16x16x32_bf16 v[66:69], v[138:141], v[114:117], v[66:69]
	v_mfma_f32_16x16x32_bf16 v[62:65], v[126:129], v[118:121], v[62:65]
	v_mfma_f32_16x16x32_bf16 v[58:61], v[130:133], v[118:121], v[58:61]
	v_mfma_f32_16x16x32_bf16 v[54:57], v[134:137], v[118:121], v[54:57]
	v_mfma_f32_16x16x32_bf16 v[50:53], v[138:141], v[118:121], v[50:53]
	v_mfma_f32_16x16x32_bf16 v[46:49], v[126:129], v[122:125], v[46:49]
	v_mfma_f32_16x16x32_bf16 v[42:45], v[130:133], v[122:125], v[42:45]
	v_mfma_f32_16x16x32_bf16 v[38:41], v[134:137], v[122:125], v[38:41]
	v_mfma_f32_16x16x32_bf16 v[30:33], v[138:141], v[122:125], v[30:33]
	s_setprio 0
	s_waitcnt lgkmcnt(0)
	s_setprio 1
	v_mfma_f32_16x16x32_bf16 v[94:97], v[176:179], v[160:163], v[94:97]
	v_mfma_f32_16x16x32_bf16 v[90:93], v[180:183], v[160:163], v[90:93]
	v_mfma_f32_16x16x32_bf16 v[86:89], v[184:187], v[160:163], v[86:89]
	v_mfma_f32_16x16x32_bf16 v[82:85], v[188:191], v[160:163], v[82:85]
	v_mfma_f32_16x16x32_bf16 v[78:81], v[176:179], v[164:167], v[78:81]
	v_mfma_f32_16x16x32_bf16 v[74:77], v[180:183], v[164:167], v[74:77]
	v_mfma_f32_16x16x32_bf16 v[70:73], v[184:187], v[164:167], v[70:73]
	v_mfma_f32_16x16x32_bf16 v[66:69], v[188:191], v[164:167], v[66:69]
	v_mfma_f32_16x16x32_bf16 v[62:65], v[176:179], v[168:171], v[62:65]
	v_mfma_f32_16x16x32_bf16 v[58:61], v[180:183], v[168:171], v[58:61]
	v_mfma_f32_16x16x32_bf16 v[54:57], v[184:187], v[168:171], v[54:57]
	v_mfma_f32_16x16x32_bf16 v[50:53], v[188:191], v[168:171], v[50:53]
	v_mfma_f32_16x16x32_bf16 v[46:49], v[176:179], v[172:175], v[46:49]
	v_mfma_f32_16x16x32_bf16 v[42:45], v[180:183], v[172:175], v[42:45]
	v_mfma_f32_16x16x32_bf16 v[38:41], v[184:187], v[172:175], v[38:41]
	v_mfma_f32_16x16x32_bf16 v[30:33], v[188:191], v[172:175], v[30:33]
	s_setprio 0
	s_waitcnt lgkmcnt(0)
	s_barrier
; template <int NT>
; __device__ __forceinline__ void gemm_tile(f32x4 (&acc)[4][NT], const bf16_t* A, int lda, const bf16_t* B, int ldb, int K, bf16_t* sm) {
;     ...
;         lds_barrier();
; #pragma unroll
;         for (int i = 0; i < 4; ++i) *(u32x4*)(sA + (lrow + 32 * i) * LDT + lkc * 8) = ra0[i];
; #pragma unroll
;         for (int i = 0; i < NT; ++i) *(u32x4*)(sB + sbrow[i] * LDT + lkc * 8) = rb0[i];
;         lds_barrier();
;         if (kt + 1 < nk) {
;             ga += 64; gb += 64;
; #pragma unroll
;             for (int i = 0; i < 4; ++i) ra0[i] = *(const u32x4*)(ga + (size_t)(32 * i) * lda);
; #pragma unroll
;             for (int i = 0; i < NT; ++i) rb0[i] = *(const u32x4*)(gb + (size_t)(32 * i) * ldb);
;         }
;         __builtin_amdgcn_sched_barrier(0);
;         gemm_compute<NT>(acc, sA, sB, wr, wc, fr, fq);
; __device__ __forceinline__ void phase_proj(const bf16_t* xb, const bf16_t* W, bf16_t* P, bf16_t* sm) {
;     ...
; #pragma unroll
;         for (int mt = 0; mt < 4; ++mt) {
;             const int row = tm * 128 + wr * 64 + mt * 16 + fr;
;             const int cbase = tn * 128 + wc * 64 + fq * 16;
;             float v[16]; gather_cols<4>(acc, mt, v);
;             u32x4 o0, o1;
; #pragma unroll
;             for (int q = 0; q < 4; ++q) { o0[q] = pack2(v[2 * q], v[2 * q + 1]); o1[q] = pack2(v[8 + 2 * q], v[8 + 2 * q + 1]); }
;             *(u32x4*)(P + (size_t)row * PW + cbase) = o0;
;             *(u32x4*)(P + (size_t)row * PW + cbase + 8) = o1;
;         }
;     }
	s_waitcnt vmcnt(7)
	ds_write_b128 v105, v[18:21]
	s_waitcnt vmcnt(6)
	ds_write_b128 v105, v[14:17] offset:5120
	s_waitcnt vmcnt(5)
	ds_write_b128 v105, v[26:29] offset:10240
	s_waitcnt vmcnt(4)
	ds_write_b128 v105, v[34:37] offset:15360
	s_waitcnt vmcnt(3)
	ds_write_b128 v106, v[4:7] offset:20480
	s_waitcnt vmcnt(2)
	ds_write_b128 v107, v[0:3] offset:20480
	s_waitcnt vmcnt(1)
	ds_write_b128 v108, v[8:11] offset:20480
	s_waitcnt vmcnt(0)
	ds_write_b128 v109, v[22:25] offset:20480
	s_waitcnt lgkmcnt(0)
	s_barrier
	ds_read_b128 v[0:3], v104
	ds_read_b128 v[4:7], v104 offset:2560
	ds_read_b128 v[8:11], v104 offset:5120
	ds_read_b128 v[14:17], v104 offset:7680
	ds_read_b128 v[18:21], v12 offset:20480
	ds_read_b128 v[22:25], v12 offset:23040
	ds_read_b128 v[26:29], v12 offset:25600
	ds_read_b128 v[34:37], v12 offset:28160
	s_setprio 1
	s_waitcnt lgkmcnt(3)
	v_mfma_f32_16x16x32_bf16 v[94:97], v[18:21], v[0:3], v[94:97]
	s_waitcnt lgkmcnt(2)
	v_mfma_f32_16x16x32_bf16 v[90:93], v[22:25], v[0:3], v[90:93]
	s_waitcnt lgkmcnt(1)
	v_mfma_f32_16x16x32_bf16 v[86:89], v[26:29], v[0:3], v[86:89]
	s_waitcnt lgkmcnt(0)
	v_mfma_f32_16x16x32_bf16 v[0:3], v[34:37], v[0:3], v[82:85]
	v_mfma_f32_16x16x32_bf16 v[78:81], v[18:21], v[4:7], v[78:81]
	v_mfma_f32_16x16x32_bf16 v[74:77], v[22:25], v[4:7], v[74:77]
	v_mfma_f32_16x16x32_bf16 v[70:73], v[26:29], v[4:7], v[70:73]
	v_mfma_f32_16x16x32_bf16 v[4:7], v[34:37], v[4:7], v[66:69]
	v_mfma_f32_16x16x32_bf16 v[62:65], v[18:21], v[8:11], v[62:65]
	v_mfma_f32_16x16x32_bf16 v[58:61], v[22:25], v[8:11], v[58:61]
	v_mfma_f32_16x16x32_bf16 v[54:57], v[26:29], v[8:11], v[54:57]
	v_mfma_f32_16x16x32_bf16 v[8:11], v[34:37], v[8:11], v[50:53]
	v_mfma_f32_16x16x32_bf16 v[18:21], v[18:21], v[14:17], v[46:49]
	v_mfma_f32_16x16x32_bf16 v[22:25], v[22:25], v[14:17], v[42:45]
	v_mfma_f32_16x16x32_bf16 v[26:29], v[26:29], v[14:17], v[38:41]
	v_mfma_f32_16x16x32_bf16 v[14:17], v[34:37], v[14:17], v[30:33]
	s_setprio 0
	s_nop 1
	ds_read_b128 v[30:33], v104 offset:64
	ds_read_b128 v[34:37], v104 offset:2624
	ds_read_b128 v[38:41], v104 offset:5184
	ds_read_b128 v[42:45], v104 offset:7744
	ds_read_b128 v[46:49], v12 offset:20544
	ds_read_b128 v[50:53], v12 offset:23104
	ds_read_b128 v[66:69], v12 offset:25664
	ds_read_b128 v[82:85], v12 offset:28224
	s_setprio 1
	s_waitcnt lgkmcnt(3)
	v_mfma_f32_16x16x32_bf16 v[94:97], v[46:49], v[30:33], v[94:97]
	s_waitcnt lgkmcnt(2)
	v_mfma_f32_16x16x32_bf16 v[90:93], v[50:53], v[30:33], v[90:93]
	s_waitcnt lgkmcnt(1)
	v_mfma_f32_16x16x32_bf16 v[86:89], v[66:69], v[30:33], v[86:89]
	s_waitcnt lgkmcnt(0)
	v_mfma_f32_16x16x32_bf16 v[0:3], v[82:85], v[30:33], v[0:3]
	v_mfma_f32_16x16x32_bf16 v[30:33], v[46:49], v[34:37], v[78:81]
	v_mfma_f32_16x16x32_bf16 v[74:77], v[50:53], v[34:37], v[74:77]
	v_mfma_f32_16x16x32_bf16 v[70:73], v[66:69], v[34:37], v[70:73]
	v_mfma_f32_16x16x32_bf16 v[4:7], v[82:85], v[34:37], v[4:7]
	v_mfma_f32_16x16x32_bf16 v[34:37], v[46:49], v[38:41], v[62:65]
	v_mfma_f32_16x16x32_bf16 v[58:61], v[50:53], v[38:41], v[58:61]
	v_mfma_f32_16x16x32_bf16 v[54:57], v[66:69], v[38:41], v[54:57]
	v_mfma_f32_16x16x32_bf16 v[8:11], v[82:85], v[38:41], v[8:11]
	v_mfma_f32_16x16x32_bf16 v[18:21], v[46:49], v[42:45], v[18:21]
	v_mfma_f32_16x16x32_bf16 v[22:25], v[50:53], v[42:45], v[22:25]
	v_mfma_f32_16x16x32_bf16 v[26:29], v[66:69], v[42:45], v[26:29]
	v_mfma_f32_16x16x32_bf16 v[14:17], v[82:85], v[42:45], v[14:17]
	s_setprio 0
	v_lshl_or_b32 v38, s18, 7, v103
	v_ashrrev_i32_e32 v39, 31, v38
	v_lshl_add_u32 v12, s14, 7, v102
	v_lshl_add_u64 v[46:47], v[38:39], 1, s[8:9]
	v_cvt_pk_bf16_f32 v38, v94, v90
	v_cvt_pk_bf16_f32 v39, v86, v0
	v_cvt_pk_bf16_f32 v40, v95, v91
	v_cvt_pk_bf16_f32 v41, v87, v1
	v_mad_i64_i32 v[0:1], s[14:15], v12, s92, v[46:47]
	v_cvt_pk_bf16_f32 v42, v96, v92
	v_cvt_pk_bf16_f32 v43, v88, v2
	v_cvt_pk_bf16_f32 v44, v97, v93
	v_cvt_pk_bf16_f32 v45, v89, v3
	global_store_dwordx4 v[0:1], v[38:41], off
	global_store_dwordx4 v[0:1], v[42:45], off offset:16
	v_cvt_pk_bf16_f32 v1, v70, v4
	v_or_b32_e32 v4, 16, v12
	v_cvt_pk_bf16_f32 v0, v30, v74
	v_cvt_pk_bf16_f32 v2, v31, v75
	v_cvt_pk_bf16_f32 v3, v71, v5
	v_mad_i64_i32 v[4:5], s[14:15], v4, s92, v[46:47]
	v_cvt_pk_bf16_f32 v38, v32, v76
	v_cvt_pk_bf16_f32 v39, v72, v6
	v_cvt_pk_bf16_f32 v40, v33, v77
	v_cvt_pk_bf16_f32 v41, v73, v7
	global_store_dwordx4 v[4:5], v[0:3], off
	global_store_dwordx4 v[4:5], v[38:41], off offset:16
	v_cvt_pk_bf16_f32 v4, v36, v60
	v_cvt_pk_bf16_f32 v1, v54, v8
	v_or_b32_e32 v8, 32, v12
	v_cvt_pk_bf16_f32 v0, v34, v58
	v_cvt_pk_bf16_f32 v2, v35, v59
	v_cvt_pk_bf16_f32 v3, v55, v9
	v_mad_i64_i32 v[8:9], s[14:15], v8, s92, v[46:47]
	v_cvt_pk_bf16_f32 v5, v56, v10
	v_cvt_pk_bf16_f32 v6, v37, v61
	v_cvt_pk_bf16_f32 v7, v57, v11
	global_store_dwordx4 v[8:9], v[0:3], off
	global_store_dwordx4 v[8:9], v[4:7], off offset:16
	v_or_b32_e32 v8, 48, v12
	s_add_i32 s13, s13, s62
	v_cvt_pk_bf16_f32 v0, v18, v22
	v_cvt_pk_bf16_f32 v4, v20, v24
	v_cvt_pk_bf16_f32 v1, v26, v14
	v_cvt_pk_bf16_f32 v5, v28, v16
	v_cvt_pk_bf16_f32 v2, v19, v23
	v_cvt_pk_bf16_f32 v6, v21, v25
	v_cvt_pk_bf16_f32 v3, v27, v15
	v_cvt_pk_bf16_f32 v7, v29, v17
	v_mad_i64_i32 v[8:9], s[14:15], v8, s92, v[46:47]
	s_cmpk_gt_i32 s13, 0x13a7
	global_store_dwordx4 v[8:9], v[0:3], off
	global_store_dwordx4 v[8:9], v[4:7], off offset:16
	s_cbranch_scc0 .LBB0_464
	v_mov_b32_e32 v66, v208

; __device__ __forceinline__ int tidx() { int t = threadIdx.x; asm volatile("" : "+v"(t)); return t; }
; template <int NT>
; __device__ __forceinline__ void gemm_tile(f32x4 (&acc)[4][NT], const bf16_t* A, int lda, const bf16_t* B, int ldb, int K, bf16_t* sm) {
;     const int tid_ = tidx();
;     bf16_t* sA = sm; bf16_t* sB = sm + 128 * LDT;
;     const int tid = tid_, lane = tid & 63, wid = tid >> 6, wr = wid >> 1, wc = wid & 1;
;     const int fr = lane & 15, fq = lane >> 4;
;     const int lrow = tid >> 3, lkc = tid & 7;
;     const bf16_t* ga = A + (size_t)lrow * lda + lkc * 8;
;     const bf16_t* gb = B + (size_t)lrow * ldb + lkc * 8;
;     int sbrow[NT];
; #pragma unroll
;     for (int i = 0; i < NT; ++i) { const int g = lrow + 32 * i, W_ = 16 * NT, rem = g % W_; sbrow[i] = (g / W_) * W_ + (rem % NT) * 16 + rem / NT; }
;     u32x4 ra0[4], rb0[NT];
; #pragma unroll
;     for (int i = 0; i < 4; ++i) ra0[i] = *(const u32x4*)(ga + (size_t)(32 * i) * lda);
; #pragma unroll
;     for (int i = 0; i < NT; ++i) rb0[i] = *(const u32x4*)(gb + (size_t)(32 * i) * ldb);
; __device__ __forceinline__ void phase_merge(const bf16_t* G, const bf16_t* BO, const bf16_t* Wb, bf16_t* M, bf16_t* sm) {
;     ...
;     for (int t = blockIdx.x; t < 136 * 16; t += gridDim.x) {
;         const int tm = t >> 4, tn = t & 15;
;         const int cbase = tn * 64 + wc * 32 + fq * 8;
;         f32x4 accm[4][2]; zero_acc<2>(accm);
; #pragma unroll 1
;         for (int i = 0; i < 4; ++i) {
;             f32x4 accb[4][2]; zero_acc<2>(accb);
;             const int koff = i * 512, kk = i < 3 ? 512 : 256;
;             gemm_tile<2>(accb, BO + (size_t)tm * 128 * 1792 + koff, 1792, Wb + (size_t)tn * 64 * 1792 + koff, 1792, kk, sm);
.LBB0_475:
	v_mov_b32_e32 v28, v192
	s_lshl_b32 s2, s48, 10
	s_add_u32 s40, s44, s2
	v_ashrrev_i32_e32 v0, 31, v28
	v_ashrrev_i32_e32 v26, 3, v28
	v_lshrrev_b32_e32 v0, 27, v0
	s_addc_u32 s41, s45, 0
	v_add_u32_e32 v0, v26, v0
	s_add_u32 s50, s46, s2
	v_lshrrev_b32_e32 v1, 5, v0
	s_addc_u32 s51, s47, 0
	v_mul_i32_i24_e32 v1, 32, v1
	v_sub_u32_e32 v27, v26, v1
	v_and_b32_e32 v29, 0x7ffffe0, v0
	v_mov_b64_e32 v[0:1], s[50:51]
	v_lshlrev_b32_e32 v2, 4, v28
	v_mad_i64_i32 v[0:1], s[50:51], v26, s36, v[0:1]
	v_and_b32_e32 v12, 0x70, v2
	v_lshl_add_u64 v[0:1], v[0:1], 0, v[12:13]
	v_add_co_u32_e32 v2, vcc, s38, v0
	s_mov_b32 s2, 0x38000
	s_nop 0
	v_addc_co_u32_e32 v3, vcc, 0, v1, vcc
	v_mov_b32_e32 v250, v0
	v_mov_b32_e32 v251, v1
	v_mov_b64_e32 v[0:1], s[40:41]
	v_mad_i64_i32 v[0:1], s[40:41], v26, s36, v[0:1]
	s_waitcnt vmcnt(10)
	v_lshl_add_u64 v[18:19], v[0:1], 0, v[12:13]
	v_add_co_u32_e32 v0, vcc, s38, v18
	s_waitcnt vmcnt(8)
	v_lshrrev_b16_e32 v30, 7, v27
	v_addc_co_u32_e32 v1, vcc, 0, v19, vcc
	v_add_co_u32_e32 v20, vcc, s2, v18
	s_mov_b32 s2, 0x54000
	s_nop 0
	v_addc_co_u32_e32 v21, vcc, 0, v19, vcc
	v_add_co_u32_e32 v22, vcc, s2, v18
	v_mov_b32_e32 v248, v18
	v_mov_b32_e32 v249, v19
	s_nop 0
	v_addc_co_u32_e32 v23, vcc, 0, v19, vcc
	s_nop 0
	v_and_b32_e32 v30, 1, v30
	v_add_u16_e32 v30, v27, v30
	v_ashrrev_i16_sdwa v31, v195, sext(v30) dst_sel:DWORD dst_unused:UNUSED_PAD src0_sel:DWORD src1_sel:BYTE_0
	v_and_b32_e32 v30, 0xfe, v30
	v_sub_u16_e32 v27, v27, v30
	v_lshlrev_b32_sdwa v27, v198, sext(v27) dst_sel:DWORD dst_unused:UNUSED_PAD src0_sel:DWORD src1_sel:BYTE_0
	v_bfe_i32 v30, v31, 0, 16
	v_add3_u32 v27, v29, v30, v27
	v_add_u32_e32 v29, 32, v26
	v_ashrrev_i32_e32 v30, 31, v29
	v_lshrrev_b32_e32 v30, 27, v30
	v_add_u32_e32 v30, v29, v30
	v_and_b32_e32 v30, 0xffffffe0, v30
	v_sub_u32_e32 v29, v29, v30
	v_lshrrev_b16_e32 v31, 7, v29
	v_and_b32_e32 v31, 1, v31
	v_add_u16_e32 v31, v29, v31
	v_ashrrev_i16_sdwa v32, v195, sext(v31) dst_sel:DWORD dst_unused:UNUSED_PAD src0_sel:DWORD src1_sel:BYTE_0
	v_and_b32_e32 v31, 0xfe, v31
	v_sub_u16_e32 v29, v29, v31
	v_lshlrev_b32_sdwa v29, v198, sext(v29) dst_sel:DWORD dst_unused:UNUSED_PAD src0_sel:DWORD src1_sel:BYTE_0
	v_bfe_i32 v31, v32, 0, 16
	v_add3_u32 v29, v30, v31, v29
	v_and_b32_e32 v31, 15, v28
	v_lshrrev_b32_e32 v32, 1, v28
	v_and_or_b32 v33, v32, s3, v31
	v_and_b32_e32 v30, 48, v28
	v_and_or_b32 v31, v32, 32, v31
	v_mul_lo_u32 v32, v33, s89
	v_mul_lo_u32 v33, v26, s89
	v_mul_lo_u32 v34, v27, s89
	v_mad_i64_i32 v[26:27], s[40:41], v26, s36, 0
	v_and_b32_e32 v28, 7, v28
	s_cmp_eq_u32 s48, 3
	v_mul_u32_u24_e32 v31, 0xa0, v31
	v_mul_lo_u32 v29, v29, s89
	s_movk_i32 s2, 0x180
	v_lshl_or_b32 v26, v28, 4, v26
	s_cselect_b32 s2, s2, 0x380
	v_lshl_add_u64 v[110:111], s[24:25], 0, v[26:27]
	v_lshl_add_u64 v[112:113], s[22:23], 0, v[26:27]
	s_mov_b64 s[40:41], 0
	v_add_u32_e32 v117, v12, v33
	v_add_u32_e32 v118, v12, v34
	v_add_u32_e32 v119, v12, v29
	v_add_u32_e32 v116, v30, v32
	v_add_u32_e32 v12, v30, v31
	v_mov_b32_e32 v26, 0
	v_mov_b32_e32 v27, v115
	v_mov_b32_e32 v28, v115
	v_mov_b32_e32 v29, v115
	v_mov_b32_e32 v30, 0
	v_mov_b32_e32 v31, v115
	v_mov_b32_e32 v32, v115
	v_mov_b32_e32 v33, v115
	v_mov_b32_e32 v34, 0
	v_mov_b32_e32 v35, v115
	v_mov_b32_e32 v36, v115
	v_mov_b32_e32 v37, v115
	v_mov_b32_e32 v38, 0
	v_mov_b32_e32 v39, v115
	v_mov_b32_e32 v40, v115
	s_waitcnt lgkmcnt(0)
	v_mov_b32_e32 v41, v115
	v_mov_b32_e32 v42, 0
	v_mov_b32_e32 v43, v115
	v_mov_b32_e32 v44, v115
	v_mov_b32_e32 v45, v115
	v_mov_b32_e32 v46, 0
	v_mov_b32_e32 v47, v115
	v_mov_b32_e32 v48, v115
	v_mov_b32_e32 v49, v115
	v_mov_b32_e32 v50, 0
	v_mov_b32_e32 v51, v115
	v_mov_b32_e32 v52, v115
	v_mov_b32_e32 v53, v115
	v_mov_b32_e32 v54, 0
	v_mov_b32_e32 v55, v115
	v_mov_b32_e32 v56, v115
	v_mov_b32_e32 v57, v115
	v_writelane_b32 v234, s90, 0
	v_writelane_b32 v234, s91, 1
	v_writelane_b32 v234, s92, 2
	v_writelane_b32 v234, s93, 3
	v_writelane_b32 v234, s94, 4
	v_writelane_b32 v234, s95, 5
	v_bfe_u32 v160, v192, 3, 3
	v_and_b32_e32 v161, 7, v192
	v_xor_b32_e32 v161, v160, v161
	v_lshlrev_b32_e32 v161, 4, v161
	v_lshrrev_b32_e32 v162, 6, v192
	v_lshl_add_u32 v163, v162, 5, v160
	v_mul_u32_u24_e32 v163, 0xe00, v163
	v_add_u32_e32 v236, v163, v161
	v_add_u32_e32 v237, 0x6c00, v236
	v_add_u32_e32 v238, 0x6c00, v237
	v_add_u32_e32 v239, 0x6c00, v238
	v_lshrrev_b32_e32 v163, 7, v192
	v_bfe_u32 v162, v192, 6, 1
	v_lshlrev_b32_e32 v163, 5, v163
	v_lshl_add_u32 v163, v160, 1, v163
	v_add_u32_e32 v163, v162, v163
	v_mul_u32_u24_e32 v163, 0xe00, v163
	v_add_u32_e32 v240, v163, v161
	v_add_u32_e32 v241, 0xdc00, v240
	v_and_b32_e32 v160, 15, v192
	v_bfe_u32 v161, v192, 4, 2
	v_and_b32_e32 v162, 7, v160
	v_xor_b32_e32 v161, v161, v162
	v_lshlrev_b32_e32 v161, 4, v161
	v_lshl_add_u32 v161, v160, 7, v161
	v_lshrrev_b32_e32 v162, 7, v192
	v_lshl_add_u32 v244, v162, 13, v161
	v_bfe_u32 v162, v192, 6, 1
	v_lshl_add_u32 v246, v162, 12, v161
	v_add_u32_e32 v246, 0x4000, v246
	v_xor_b32_e32 v245, 64, v244
	v_xor_b32_e32 v247, 64, v246
	v_lshrrev_b32_e32 v160, 6, v192
	s_nop 0
	v_readfirstlane_b32 s94, v160
	v_readfirstlane_b32 s90, v248
	v_readfirstlane_b32 s91, v249
	v_readfirstlane_b32 s92, v250
	v_readfirstlane_b32 s93, v251
	s_mul_i32 s95, s94, 0x7000
	s_sub_u32 s90, s90, s95
	s_subb_u32 s91, s91, 0
	s_mul_i32 s95, s94, 0x7000
	s_sub_u32 s92, s92, s95
	s_subb_u32 s93, s93, 0
	s_lshl_b32 s94, s94, 10
	s_waitcnt lgkmcnt(0)
	s_barrier
	s_lshl_b32 s95, s94, 2
	s_add_u32 m0, s95, 0x0
	s_nop 0
	global_load_lds_dwordx4 v236, s[90:91] sc1
	global_load_lds_dwordx4 v237, s[90:91] offset:1024 sc1
	global_load_lds_dwordx4 v238, s[90:91] offset:2048 sc1
	global_load_lds_dwordx4 v239, s[90:91] offset:3072 sc1
	s_mul_i32 s95, s94, 2
	s_add_u32 m0, s95, 0x4000
	s_nop 0
	global_load_lds_dwordx4 v240, s[92:93]
	global_load_lds_dwordx4 v241, s[92:93] offset:1024
	s_add_u32 s90, s90, 0x80
	s_addc_u32 s91, s91, 0
	s_add_u32 s92, s92, 0x80
	s_addc_u32 s93, s93, 0
	s_waitcnt vmcnt(0)
	s_barrier
	s_lshl_b32 s95, s94, 2
	s_add_u32 m0, s95, 0x8000
	s_nop 0
	global_load_lds_dwordx4 v236, s[90:91] sc1
	global_load_lds_dwordx4 v237, s[90:91] offset:1024 sc1
	global_load_lds_dwordx4 v238, s[90:91] offset:2048 sc1
	global_load_lds_dwordx4 v239, s[90:91] offset:3072 sc1
	s_mul_i32 s95, s94, 2
	s_add_u32 m0, s95, 0xc000
	s_nop 0
	global_load_lds_dwordx4 v240, s[92:93]
	global_load_lds_dwordx4 v241, s[92:93] offset:1024
	s_add_u32 s90, s90, 0x80
	s_addc_u32 s91, s91, 0
	s_add_u32 s92, s92, 0x80
	s_addc_u32 s93, s93, 0
	ds_read_b128 v[120:123], v244 offset:0
	ds_read_b128 v[124:127], v244 offset:2048
	ds_read_b128 v[128:131], v244 offset:4096
	ds_read_b128 v[132:135], v244 offset:6144
	ds_read_b128 v[136:139], v246 offset:0
	ds_read_b128 v[140:143], v246 offset:2048
	s_lshr_b32 s95, s2, 8
	s_add_i32 s95, s95, -1
	s_cmp_eq_u32 s95, 0
	s_cbranch_scc1 .Lgemm_x476
; template <int NT>
; __device__ __forceinline__ void gemm_compute(f32x4 (&acc)[4][NT], const bf16_t* sA, const bf16_t* sB, int wr, int wc, int fr, int fq) {
;     ...
;     for (int ks = 0; ks < 2; ++ks) {
;         bf16x8 a[4], b[NT];
; #pragma unroll
;         for (int mt = 0; mt < 4; ++mt) a[mt] = *(const bf16x8*)(sA + (wr * 64 + mt * 16 + fr) * LDT + ks * 32 + fq * 8);
; #pragma unroll
;         for (int nt = 0; nt < NT; ++nt) b[nt] = *(const bf16x8*)(sB + (wc * 16 * NT + nt * 16 + fr) * LDT + ks * 32 + fq * 8);
;         __builtin_amdgcn_s_setprio(1);
; #pragma unroll
;         for (int mt = 0; mt < 4; ++mt)
; #pragma unroll
;             for (int nt = 0; nt < NT; ++nt)
;                 acc[mt][nt] = __builtin_amdgcn_mfma_f32_16x16x32_bf16(b[nt], a[mt], acc[mt][nt], 0, 0, 0);
;         __builtin_amdgcn_s_setprio(0);
;     }
; template <int NT>
; __device__ __forceinline__ void gemm_tile(f32x4 (&acc)[4][NT], const bf16_t* A, int lda, const bf16_t* B, int ldb, int K, bf16_t* sm) {
;     ...
;     for (int kt = 0; kt < nk; ++kt) {
;         lds_barrier();
; #pragma unroll
;         for (int i = 0; i < 4; ++i) *(u32x4*)(sA + (lrow + 32 * i) * LDT + lkc * 8) = ra0[i];
; #pragma unroll
;         for (int i = 0; i < NT; ++i) *(u32x4*)(sB + sbrow[i] * LDT + lkc * 8) = rb0[i];
;         lds_barrier();
;         if (kt + 1 < nk) {
;             ga += 64; gb += 64;
; #pragma unroll
;             for (int i = 0; i < 4; ++i) ra0[i] = *(const u32x4*)(ga + (size_t)(32 * i) * lda);
; #pragma unroll
;             for (int i = 0; i < NT; ++i) rb0[i] = *(const u32x4*)(gb + (size_t)(32 * i) * ldb);
;         }
;         __builtin_amdgcn_sched_barrier(0);
;         gemm_compute<NT>(acc, sA, sB, wr, wc, fr, fq);
;         __builtin_amdgcn_sched_barrier(0);
;     }
.Lgemm_k476:
	v_writelane_b32 v234, s95, 6
	ds_read_b128 v[160:163], v245 offset:0
	ds_read_b128 v[164:167], v245 offset:2048
	ds_read_b128 v[168:171], v245 offset:4096
	ds_read_b128 v[172:175], v245 offset:6144
	ds_read_b128 v[176:179], v247 offset:0
	ds_read_b128 v[180:183], v247 offset:2048
	s_setprio 1
	s_waitcnt lgkmcnt(7)
	v_mfma_f32_16x16x32_bf16 v[54:57], v[136:139], v[120:123], v[54:57]
	s_waitcnt lgkmcnt(6)
	v_mfma_f32_16x16x32_bf16 v[50:53], v[140:143], v[120:123], v[50:53]
	v_mfma_f32_16x16x32_bf16 v[46:49], v[136:139], v[124:127], v[46:49]
	v_mfma_f32_16x16x32_bf16 v[42:45], v[140:143], v[124:127], v[42:45]
	v_mfma_f32_16x16x32_bf16 v[38:41], v[136:139], v[128:131], v[38:41]
	v_mfma_f32_16x16x32_bf16 v[34:37], v[140:143], v[128:131], v[34:37]
	v_mfma_f32_16x16x32_bf16 v[30:33], v[136:139], v[132:135], v[30:33]
	v_mfma_f32_16x16x32_bf16 v[26:29], v[140:143], v[132:135], v[26:29]
	s_setprio 0
	s_waitcnt vmcnt(0) lgkmcnt(0)
	s_barrier
	ds_read_b128 v[120:123], v244 offset:32768
	ds_read_b128 v[124:127], v244 offset:34816
	ds_read_b128 v[128:131], v244 offset:36864
	ds_read_b128 v[132:135], v244 offset:38912
	ds_read_b128 v[136:139], v246 offset:32768
	ds_read_b128 v[140:143], v246 offset:34816
	s_setprio 1
	v_mfma_f32_16x16x32_bf16 v[54:57], v[176:179], v[160:163], v[54:57]
	s_lshl_b32 s95, s94, 2
	s_add_u32 m0, s95, 0x0
	s_nop 0
	global_load_lds_dwordx4 v236, s[90:91] sc1
	v_mfma_f32_16x16x32_bf16 v[50:53], v[180:183], v[160:163], v[50:53]
	v_mfma_f32_16x16x32_bf16 v[46:49], v[176:179], v[164:167], v[46:49]
	global_load_lds_dwordx4 v237, s[90:91] offset:1024 sc1
	v_mfma_f32_16x16x32_bf16 v[42:45], v[180:183], v[164:167], v[42:45]
	v_mfma_f32_16x16x32_bf16 v[38:41], v[176:179], v[168:171], v[38:41]
	global_load_lds_dwordx4 v238, s[90:91] offset:2048 sc1
	v_mfma_f32_16x16x32_bf16 v[34:37], v[180:183], v[168:171], v[34:37]
	v_mfma_f32_16x16x32_bf16 v[30:33], v[176:179], v[172:175], v[30:33]
	global_load_lds_dwordx4 v239, s[90:91] offset:3072 sc1
	v_mfma_f32_16x16x32_bf16 v[26:29], v[180:183], v[172:175], v[26:29]
	s_mul_i32 s95, s94, 2
	s_add_u32 m0, s95, 0x4000
	s_nop 0
	global_load_lds_dwordx4 v240, s[92:93]
	global_load_lds_dwordx4 v241, s[92:93] offset:1024
	s_add_u32 s90, s90, 0x80
	s_addc_u32 s91, s91, 0
	s_add_u32 s92, s92, 0x80
	s_addc_u32 s93, s93, 0
	s_setprio 0
	ds_read_b128 v[160:163], v245 offset:32768
	ds_read_b128 v[164:167], v245 offset:34816
	ds_read_b128 v[168:171], v245 offset:36864
	ds_read_b128 v[172:175], v245 offset:38912
	ds_read_b128 v[176:179], v247 offset:32768
	ds_read_b128 v[180:183], v247 offset:34816
	s_setprio 1
	s_waitcnt lgkmcnt(7)
	v_mfma_f32_16x16x32_bf16 v[54:57], v[136:139], v[120:123], v[54:57]
	s_waitcnt lgkmcnt(6)
	v_mfma_f32_16x16x32_bf16 v[50:53], v[140:143], v[120:123], v[50:53]
	v_mfma_f32_16x16x32_bf16 v[46:49], v[136:139], v[124:127], v[46:49]
	v_mfma_f32_16x16x32_bf16 v[42:45], v[140:143], v[124:127], v[42:45]
	v_mfma_f32_16x16x32_bf16 v[38:41], v[136:139], v[128:131], v[38:41]
	v_mfma_f32_16x16x32_bf16 v[34:37], v[140:143], v[128:131], v[34:37]
	v_mfma_f32_16x16x32_bf16 v[30:33], v[136:139], v[132:135], v[30:33]
	v_mfma_f32_16x16x32_bf16 v[26:29], v[140:143], v[132:135], v[26:29]
	s_setprio 0
	s_waitcnt vmcnt(0) lgkmcnt(0)
	s_barrier
	ds_read_b128 v[120:123], v244 offset:0
	ds_read_b128 v[124:127], v244 offset:2048
	ds_read_b128 v[128:131], v244 offset:4096
	ds_read_b128 v[132:135], v244 offset:6144
	ds_read_b128 v[136:139], v246 offset:0
	ds_read_b128 v[140:143], v246 offset:2048
	s_setprio 1
	v_mfma_f32_16x16x32_bf16 v[54:57], v[176:179], v[160:163], v[54:57]
	s_lshl_b32 s95, s94, 2
	s_add_u32 m0, s95, 0x8000
	s_nop 0
	global_load_lds_dwordx4 v236, s[90:91] sc1
	v_mfma_f32_16x16x32_bf16 v[50:53], v[180:183], v[160:163], v[50:53]
	v_mfma_f32_16x16x32_bf16 v[46:49], v[176:179], v[164:167], v[46:49]
	global_load_lds_dwordx4 v237, s[90:91] offset:1024 sc1
	v_mfma_f32_16x16x32_bf16 v[42:45], v[180:183], v[164:167], v[42:45]
	v_mfma_f32_16x16x32_bf16 v[38:41], v[176:179], v[168:171], v[38:41]
	global_load_lds_dwordx4 v238, s[90:91] offset:2048 sc1
	v_mfma_f32_16x16x32_bf16 v[34:37], v[180:183], v[168:171], v[34:37]
	v_mfma_f32_16x16x32_bf16 v[30:33], v[176:179], v[172:175], v[30:33]
	global_load_lds_dwordx4 v239, s[90:91] offset:3072 sc1
	v_mfma_f32_16x16x32_bf16 v[26:29], v[180:183], v[172:175], v[26:29]
	s_mul_i32 s95, s94, 2
	s_add_u32 m0, s95, 0xc000
	s_nop 0
	global_load_lds_dwordx4 v240, s[92:93]
	global_load_lds_dwordx4 v241, s[92:93] offset:1024
	s_add_u32 s90, s90, 0x80
	s_addc_u32 s91, s91, 0
	s_add_u32 s92, s92, 0x80
	s_addc_u32 s93, s93, 0
	s_setprio 0
	v_readlane_b32 s95, v234, 6
	s_add_i32 s95, s95, -1
	s_cmp_lg_u32 s95, 0
	s_cbranch_scc1 .Lgemm_k476
; template <int NT>
; __device__ __forceinline__ void gemm_compute(f32x4 (&acc)[4][NT], const bf16_t* sA, const bf16_t* sB, int wr, int wc, int fr, int fq) {
;     ...
;     for (int ks = 0; ks < 2; ++ks) {
;         bf16x8 a[4], b[NT];
; #pragma unroll
;         for (int mt = 0; mt < 4; ++mt) a[mt] = *(const bf16x8*)(sA + (wr * 64 + mt * 16 + fr) * LDT + ks * 32 + fq * 8);
; #pragma unroll
;         for (int nt = 0; nt < NT; ++nt) b[nt] = *(const bf16x8*)(sB + (wc * 16 * NT + nt * 16 + fr) * LDT + ks * 32 + fq * 8);
;         __builtin_amdgcn_s_setprio(1);
; #pragma unroll
;         for (int mt = 0; mt < 4; ++mt)
; #pragma unroll
;             for (int nt = 0; nt < NT; ++nt)
;                 acc[mt][nt] = __builtin_amdgcn_mfma_f32_16x16x32_bf16(b[nt], a[mt], acc[mt][nt], 0, 0, 0);
;         __builtin_amdgcn_s_setprio(0);
;     }
; template <int NT>
; __device__ __forceinline__ void gemm_tile(f32x4 (&acc)[4][NT], const bf16_t* A, int lda, const bf16_t* B, int ldb, int K, bf16_t* sm) {
;     ...
;     for (int kt = 0; kt < nk; ++kt) {
;         lds_barrier();
; #pragma unroll
;         for (int i = 0; i < 4; ++i) *(u32x4*)(sA + (lrow + 32 * i) * LDT + lkc * 8) = ra0[i];
; #pragma unroll
;         for (int i = 0; i < NT; ++i) *(u32x4*)(sB + sbrow[i] * LDT + lkc * 8) = rb0[i];
;         lds_barrier();
;         if (kt + 1 < nk) {
;             ga += 64; gb += 64;
; #pragma unroll
;             for (int i = 0; i < 4; ++i) ra0[i] = *(const u32x4*)(ga + (size_t)(32 * i) * lda);
; #pragma unroll
;             for (int i = 0; i < NT; ++i) rb0[i] = *(const u32x4*)(gb + (size_t)(32 * i) * ldb);
;         }
;         __builtin_amdgcn_sched_barrier(0);
;         gemm_compute<NT>(acc, sA, sB, wr, wc, fr, fq);
;         __builtin_amdgcn_sched_barrier(0);
;     }
.Lgemm_x476:
	ds_read_b128 v[160:163], v245 offset:0
	ds_read_b128 v[164:167], v245 offset:2048
	ds_read_b128 v[168:171], v245 offset:4096
	ds_read_b128 v[172:175], v245 offset:6144
	ds_read_b128 v[176:179], v247 offset:0
	ds_read_b128 v[180:183], v247 offset:2048
	s_setprio 1
	s_waitcnt lgkmcnt(7)
	v_mfma_f32_16x16x32_bf16 v[54:57], v[136:139], v[120:123], v[54:57]
	s_waitcnt lgkmcnt(6)
	v_mfma_f32_16x16x32_bf16 v[50:53], v[140:143], v[120:123], v[50:53]
	v_mfma_f32_16x16x32_bf16 v[46:49], v[136:139], v[124:127], v[46:49]
	v_mfma_f32_16x16x32_bf16 v[42:45], v[140:143], v[124:127], v[42:45]
	v_mfma_f32_16x16x32_bf16 v[38:41], v[136:139], v[128:131], v[38:41]
	v_mfma_f32_16x16x32_bf16 v[34:37], v[140:143], v[128:131], v[34:37]
	v_mfma_f32_16x16x32_bf16 v[30:33], v[136:139], v[132:135], v[30:33]
	v_mfma_f32_16x16x32_bf16 v[26:29], v[140:143], v[132:135], v[26:29]
	s_setprio 0
	s_waitcnt vmcnt(0) lgkmcnt(0)
	s_barrier
	ds_read_b128 v[120:123], v244 offset:32768
	ds_read_b128 v[124:127], v244 offset:34816
	ds_read_b128 v[128:131], v244 offset:36864
	ds_read_b128 v[132:135], v244 offset:38912
	ds_read_b128 v[136:139], v246 offset:32768
	ds_read_b128 v[140:143], v246 offset:34816
	s_setprio 1
	v_mfma_f32_16x16x32_bf16 v[54:57], v[176:179], v[160:163], v[54:57]
	s_lshl_b32 s95, s94, 2
	s_add_u32 m0, s95, 0x0
	s_nop 0
	global_load_lds_dwordx4 v236, s[90:91] sc1
	v_mfma_f32_16x16x32_bf16 v[50:53], v[180:183], v[160:163], v[50:53]
	v_mfma_f32_16x16x32_bf16 v[46:49], v[176:179], v[164:167], v[46:49]
	global_load_lds_dwordx4 v237, s[90:91] offset:1024 sc1
	v_mfma_f32_16x16x32_bf16 v[42:45], v[180:183], v[164:167], v[42:45]
	v_mfma_f32_16x16x32_bf16 v[38:41], v[176:179], v[168:171], v[38:41]
	global_load_lds_dwordx4 v238, s[90:91] offset:2048 sc1
	v_mfma_f32_16x16x32_bf16 v[34:37], v[180:183], v[168:171], v[34:37]
	v_mfma_f32_16x16x32_bf16 v[30:33], v[176:179], v[172:175], v[30:33]
	global_load_lds_dwordx4 v239, s[90:91] offset:3072 sc1
	v_mfma_f32_16x16x32_bf16 v[26:29], v[180:183], v[172:175], v[26:29]
	s_mul_i32 s95, s94, 2
	s_add_u32 m0, s95, 0x4000
	s_nop 0
	global_load_lds_dwordx4 v240, s[92:93]
	global_load_lds_dwordx4 v241, s[92:93] offset:1024
	s_add_u32 s90, s90, 0x80
	s_addc_u32 s91, s91, 0
	s_add_u32 s92, s92, 0x80
	s_addc_u32 s93, s93, 0
	s_setprio 0
	ds_read_b128 v[160:163], v245 offset:32768
	ds_read_b128 v[164:167], v245 offset:34816
	ds_read_b128 v[168:171], v245 offset:36864
	ds_read_b128 v[172:175], v245 offset:38912
	ds_read_b128 v[176:179], v247 offset:32768
	ds_read_b128 v[180:183], v247 offset:34816
	s_setprio 1
	s_waitcnt lgkmcnt(7)
	v_mfma_f32_16x16x32_bf16 v[54:57], v[136:139], v[120:123], v[54:57]
	s_waitcnt lgkmcnt(6)
	v_mfma_f32_16x16x32_bf16 v[50:53], v[140:143], v[120:123], v[50:53]
	v_mfma_f32_16x16x32_bf16 v[46:49], v[136:139], v[124:127], v[46:49]
	v_mfma_f32_16x16x32_bf16 v[42:45], v[140:143], v[124:127], v[42:45]
	v_mfma_f32_16x16x32_bf16 v[38:41], v[136:139], v[128:131], v[38:41]
	v_mfma_f32_16x16x32_bf16 v[34:37], v[140:143], v[128:131], v[34:37]
	v_mfma_f32_16x16x32_bf16 v[30:33], v[136:139], v[132:135], v[30:33]
	v_mfma_f32_16x16x32_bf16 v[26:29], v[140:143], v[132:135], v[26:29]
	s_setprio 0
	s_waitcnt vmcnt(0) lgkmcnt(0)
	s_barrier
	ds_read_b128 v[120:123], v244 offset:0
	ds_read_b128 v[124:127], v244 offset:2048
	ds_read_b128 v[128:131], v244 offset:4096
	ds_read_b128 v[132:135], v244 offset:6144
	ds_read_b128 v[136:139], v246 offset:0
	ds_read_b128 v[140:143], v246 offset:2048
	s_setprio 1
	v_mfma_f32_16x16x32_bf16 v[54:57], v[176:179], v[160:163], v[54:57]
	s_sub_u32 s40, s2, 0x80
	s_mov_b32 s41, 0
	v_readlane_b32 s90, v234, 0
	v_readlane_b32 s91, v234, 1
	v_readlane_b32 s92, v234, 2
	v_readlane_b32 s93, v234, 3
	v_readlane_b32 s94, v234, 4
	v_readlane_b32 s95, v234, 5
	s_nop 3
	v_mfma_f32_16x16x32_bf16 v[50:53], v[180:183], v[160:163], v[50:53]
	v_mfma_f32_16x16x32_bf16 v[46:49], v[176:179], v[164:167], v[46:49]
	v_lshl_add_u64 v[8:9], v[110:111], 0, s[40:41]
	v_mfma_f32_16x16x32_bf16 v[42:45], v[180:183], v[164:167], v[42:45]
	v_mfma_f32_16x16x32_bf16 v[38:41], v[176:179], v[168:171], v[38:41]
	v_add_co_u32_e32 v0, vcc, s93, v8
	v_mfma_f32_16x16x32_bf16 v[34:37], v[180:183], v[168:171], v[34:37]
	v_mfma_f32_16x16x32_bf16 v[30:33], v[176:179], v[172:175], v[30:33]
	s_mov_b32 s49, 0x1627c000
	v_mfma_f32_16x16x32_bf16 v[26:29], v[180:183], v[172:175], v[26:29]
	s_nop 0
	v_addc_co_u32_e32 v1, vcc, 0, v9, vcc
	v_add_co_u32_e32 v2, vcc, s49, v8
	s_mov_b32 s49, 0x16298000
	s_nop 0
	v_addc_co_u32_e32 v3, vcc, 0, v9, vcc
	v_add_co_u32_e32 v10, vcc, s49, v8
	s_mov_b32 s49, 0x162b4000
	s_nop 0
	v_addc_co_u32_e32 v11, vcc, 0, v9, vcc
	v_add_co_u32_e32 v8, vcc, s49, v8
	s_nop 0
	s_nop 0
	v_addc_co_u32_e32 v9, vcc, 0, v9, vcc
	global_load_dwordx4 v[4:7], v[0:1], off offset:128
	s_nop 0
	global_load_dwordx4 v[0:3], v[2:3], off offset:128
	s_nop 0
	global_load_dwordx4 v[18:21], v[10:11], off offset:128
	global_load_dwordx4 v[22:25], v[8:9], off offset:128
	v_lshl_add_u64 v[8:9], v[112:113], 0, s[40:41]
	s_mov_b32 s49, 0x2940000
	v_add_co_u32_e32 v10, vcc, s49, v8
	s_mov_b32 s49, 0x295c000
	s_nop 0
	v_addc_co_u32_e32 v11, vcc, 0, v9, vcc
	v_add_co_u32_e32 v14, vcc, s49, v8
	s_nop 1
	v_addc_co_u32_e32 v15, vcc, 0, v9, vcc
	global_load_dwordx4 v[8:11], v[10:11], off offset:128
	s_nop 0
	global_load_dwordx4 v[14:17], v[14:15], off offset:128
	s_setprio 0
	ds_read_b128 v[160:163], v245 offset:0
	ds_read_b128 v[164:167], v245 offset:2048
	ds_read_b128 v[168:171], v245 offset:4096
	ds_read_b128 v[172:175], v245 offset:6144
	ds_read_b128 v[176:179], v247 offset:0
	ds_read_b128 v[180:183], v247 offset:2048
	s_setprio 1
	s_waitcnt lgkmcnt(7)
	v_mfma_f32_16x16x32_bf16 v[54:57], v[136:139], v[120:123], v[54:57]
	s_waitcnt lgkmcnt(6)
	v_mfma_f32_16x16x32_bf16 v[50:53], v[140:143], v[120:123], v[50:53]
	v_mfma_f32_16x16x32_bf16 v[46:49], v[136:139], v[124:127], v[46:49]
	v_mfma_f32_16x16x32_bf16 v[42:45], v[140:143], v[124:127], v[42:45]
	v_mfma_f32_16x16x32_bf16 v[38:41], v[136:139], v[128:131], v[38:41]
	v_mfma_f32_16x16x32_bf16 v[34:37], v[140:143], v[128:131], v[34:37]
	v_mfma_f32_16x16x32_bf16 v[30:33], v[136:139], v[132:135], v[30:33]
	v_mfma_f32_16x16x32_bf16 v[26:29], v[140:143], v[132:135], v[26:29]
	s_setprio 0
	s_waitcnt lgkmcnt(0)
	s_setprio 1
	v_mfma_f32_16x16x32_bf16 v[54:57], v[176:179], v[160:163], v[54:57]
	v_mfma_f32_16x16x32_bf16 v[50:53], v[180:183], v[160:163], v[50:53]
	v_mfma_f32_16x16x32_bf16 v[46:49], v[176:179], v[164:167], v[46:49]
	v_mfma_f32_16x16x32_bf16 v[42:45], v[180:183], v[164:167], v[42:45]
	v_mfma_f32_16x16x32_bf16 v[38:41], v[176:179], v[168:171], v[38:41]
	v_mfma_f32_16x16x32_bf16 v[34:37], v[180:183], v[168:171], v[34:37]
	v_mfma_f32_16x16x32_bf16 v[30:33], v[176:179], v[172:175], v[30:33]
	v_mfma_f32_16x16x32_bf16 v[26:29], v[180:183], v[172:175], v[26:29]
	s_setprio 0
	s_waitcnt lgkmcnt(0)
	s_barrier
; __device__ __forceinline__ float lo2f(unsigned u) { return __uint_as_float(u << 16); }
; __device__ __forceinline__ float hi2f(unsigned u) { return __uint_as_float(u & 0xffff0000u); }
; __device__ __forceinline__ u32x4 ldntu4(const bf16_t* p) { return __builtin_nontemporal_load((const u32x4*)p); }
; template <int NT>
; __device__ __forceinline__ void gemm_tile(f32x4 (&acc)[4][NT], const bf16_t* A, int lda, const bf16_t* B, int ldb, int K, bf16_t* sm) {
;     ...
;         lds_barrier();
; #pragma unroll
;         for (int i = 0; i < 4; ++i) *(u32x4*)(sA + (lrow + 32 * i) * LDT + lkc * 8) = ra0[i];
; #pragma unroll
;         for (int i = 0; i < NT; ++i) *(u32x4*)(sB + sbrow[i] * LDT + lkc * 8) = rb0[i];
;         lds_barrier();
;         if (kt + 1 < nk) {
;             ga += 64; gb += 64;
; #pragma unroll
;             for (int i = 0; i < 4; ++i) ra0[i] = *(const u32x4*)(ga + (size_t)(32 * i) * lda);
; #pragma unroll
;             for (int i = 0; i < NT; ++i) rb0[i] = *(const u32x4*)(gb + (size_t)(32 * i) * ldb);
;         }
;         __builtin_amdgcn_sched_barrier(0);
;         gemm_compute<NT>(acc, sA, sB, wr, wc, fr, fq);
; __device__ __forceinline__ void phase_merge(const bf16_t* G, const bf16_t* BO, const bf16_t* Wb, bf16_t* M, bf16_t* sm) {
;     ...
; #pragma unroll
;             for (int mt = 0; mt < 4; ++mt) {
;                 const int row = tm * 128 + wr * 64 + mt * 16 + fr;
;                 const u32x4 gu = ldntu4(G + (size_t)row * 4096 + i * 1024 + cbase);
; #pragma unroll
;                 for (int e = 0; e < 8; ++e) {
;                     const float gv = (e & 1) ? hi2f(gu[e >> 1]) : lo2f(gu[e >> 1]);
;                     accm[mt][e % 2][e / 2] += gv * accb[mt][e % 2][e / 2];
;                 }
;             }
;         }
; #pragma unroll
;         for (int mt = 0; mt < 4; ++mt) {
;             const int row = tm * 128 + wr * 64 + mt * 16 + fr;
;             float v[8]; gather_cols<2>(accm, mt, v);
;             u32x4 o;
; #pragma unroll
;             for (int q = 0; q < 4; ++q) o[q] = pack2(v[2 * q], v[2 * q + 1]);
;             *(u32x4*)(M + (size_t)row * 1024 + cbase) = o;
;         }
	s_waitcnt vmcnt(5)
	ds_write_b128 v117, v[4:7]
	s_waitcnt vmcnt(4)
	ds_write_b128 v117, v[0:3] offset:5120
	s_waitcnt vmcnt(3)
	ds_write_b128 v117, v[18:21] offset:10240
	s_waitcnt vmcnt(2)
	ds_write_b128 v117, v[22:25] offset:15360
	s_waitcnt vmcnt(1)
	ds_write_b128 v118, v[8:11] offset:20480
	s_waitcnt vmcnt(0)
	ds_write_b128 v119, v[14:17] offset:20480
	s_waitcnt lgkmcnt(0)
	s_barrier
	ds_read_b128 v[0:3], v116
	ds_read_b128 v[4:7], v116 offset:2560
	ds_read_b128 v[8:11], v116 offset:5120
	ds_read_b128 v[14:17], v116 offset:7680
	ds_read_b128 v[18:21], v12 offset:20480
	ds_read_b128 v[22:25], v12 offset:23040
	s_setprio 1
	s_waitcnt lgkmcnt(1)
	v_mfma_f32_16x16x32_bf16 v[54:57], v[18:21], v[0:3], v[54:57]
	s_waitcnt lgkmcnt(0)
	v_mfma_f32_16x16x32_bf16 v[0:3], v[22:25], v[0:3], v[50:53]
	v_mfma_f32_16x16x32_bf16 v[46:49], v[18:21], v[4:7], v[46:49]
	v_mfma_f32_16x16x32_bf16 v[4:7], v[22:25], v[4:7], v[42:45]
	v_mfma_f32_16x16x32_bf16 v[38:41], v[18:21], v[8:11], v[38:41]
	v_mfma_f32_16x16x32_bf16 v[34:37], v[22:25], v[8:11], v[34:37]
	v_mfma_f32_16x16x32_bf16 v[18:21], v[18:21], v[14:17], v[30:33]
	v_mfma_f32_16x16x32_bf16 v[22:25], v[22:25], v[14:17], v[26:29]
	s_setprio 0
	ds_read_b128 v[8:11], v116 offset:64
	ds_read_b128 v[14:17], v116 offset:2624
	ds_read_b128 v[26:29], v116 offset:5184
	ds_read_b128 v[30:33], v116 offset:7744
	ds_read_b128 v[42:45], v12 offset:20544
	ds_read_b128 v[50:53], v12 offset:23104
	s_setprio 1
	s_waitcnt lgkmcnt(1)
	v_mfma_f32_16x16x32_bf16 v[54:57], v[42:45], v[8:11], v[54:57]
	s_waitcnt lgkmcnt(0)
	v_mfma_f32_16x16x32_bf16 v[110:113], v[50:53], v[8:11], v[0:3]
	v_mfma_f32_16x16x32_bf16 v[46:49], v[42:45], v[14:17], v[46:49]
	v_mfma_f32_16x16x32_bf16 v[116:119], v[50:53], v[14:17], v[4:7]
	v_mfma_f32_16x16x32_bf16 v[8:11], v[42:45], v[26:29], v[38:41]
	v_mfma_f32_16x16x32_bf16 v[14:17], v[50:53], v[26:29], v[34:37]
	v_mfma_f32_16x16x32_bf16 v[0:3], v[42:45], v[30:33], v[18:21]
	v_mfma_f32_16x16x32_bf16 v[4:7], v[50:53], v[30:33], v[22:25]
	s_setprio 0
	s_lshl_b32 s86, s48, 11
	v_lshl_add_u64 v[18:19], v[76:77], 0, s[86:87]
	v_lshl_add_u64 v[20:21], v[18:19], 0, v[78:79]
	global_load_dwordx4 v[20:23], v[20:21], off nt
	v_mov_b32_e32 v26, v54
	v_mov_b32_e32 v27, v110
	v_mov_b32_e32 v110, v55
	s_add_i32 s48, s48, 1
	s_add_u32 s24, s24, 0x400
	s_addc_u32 s25, s25, 0
	s_add_u32 s22, s22, 0x400
	s_addc_u32 s23, s23, 0
	s_cmp_eq_u32 s48, 4
	s_waitcnt vmcnt(0)
	v_lshlrev_b32_e32 v24, 16, v20
	v_and_b32_e32 v25, 0xffff0000, v20
	v_lshlrev_b32_e32 v20, 16, v21
	v_and_b32_e32 v21, 0xffff0000, v21
	v_pk_fma_f32 v[108:109], v[26:27], v[24:25], v[108:109]
	v_pk_fma_f32 v[106:107], v[110:111], v[20:21], v[106:107]
	v_lshlrev_b32_e32 v20, 16, v22
	v_and_b32_e32 v21, 0xffff0000, v22
	v_mov_b32_e32 v24, v56
	v_mov_b32_e32 v25, v112
	v_pk_fma_f32 v[104:105], v[24:25], v[20:21], v[104:105]
	v_lshlrev_b32_e32 v20, 16, v23
	v_and_b32_e32 v21, 0xffff0000, v23
	v_mov_b32_e32 v112, v57
	v_pk_fma_f32 v[102:103], v[112:113], v[20:21], v[102:103]
	v_lshl_add_u64 v[20:21], v[18:19], 0, v[80:81]
	global_load_dwordx4 v[20:23], v[20:21], off nt
	v_mov_b32_e32 v26, v46
	v_mov_b32_e32 v27, v116
	v_mov_b32_e32 v116, v47
	s_waitcnt vmcnt(0)
	v_lshlrev_b32_e32 v24, 16, v20
	v_and_b32_e32 v25, 0xffff0000, v20
	v_lshlrev_b32_e32 v20, 16, v21
	v_and_b32_e32 v21, 0xffff0000, v21
	v_pk_fma_f32 v[100:101], v[26:27], v[24:25], v[100:101]
	v_pk_fma_f32 v[98:99], v[116:117], v[20:21], v[98:99]
	v_lshlrev_b32_e32 v20, 16, v22
	v_and_b32_e32 v21, 0xffff0000, v22
	v_mov_b32_e32 v24, v48
	v_mov_b32_e32 v25, v118
	v_pk_fma_f32 v[96:97], v[24:25], v[20:21], v[96:97]
	v_lshlrev_b32_e32 v20, 16, v23
	v_and_b32_e32 v21, 0xffff0000, v23
	v_mov_b32_e32 v118, v49
	v_pk_fma_f32 v[94:95], v[118:119], v[20:21], v[94:95]
	v_lshl_add_u64 v[20:21], v[18:19], 0, v[90:91]
	global_load_dwordx4 v[20:23], v[20:21], off nt
	v_mov_b32_e32 v27, v14
	v_mov_b32_e32 v14, v9
	v_mov_b32_e32 v26, v8
	s_waitcnt vmcnt(0)
	v_lshlrev_b32_e32 v24, 16, v20
	v_and_b32_e32 v25, 0xffff0000, v20
	v_lshlrev_b32_e32 v20, 16, v21
	v_and_b32_e32 v21, 0xffff0000, v21
	v_pk_fma_f32 v[86:87], v[14:15], v[20:21], v[86:87]
	v_lshlrev_b32_e32 v8, 16, v22
	v_and_b32_e32 v9, 0xffff0000, v22
	v_mov_b32_e32 v14, v10
	v_mov_b32_e32 v15, v16
	v_pk_fma_f32 v[84:85], v[14:15], v[8:9], v[84:85]
	v_lshlrev_b32_e32 v8, 16, v23
	v_and_b32_e32 v9, 0xffff0000, v23
	v_mov_b32_e32 v16, v11
	v_pk_fma_f32 v[82:83], v[16:17], v[8:9], v[82:83]
	v_lshl_add_u64 v[8:9], v[18:19], 0, v[92:93]
	global_load_dwordx4 v[8:11], v[8:9], off nt
	v_mov_b32_e32 v17, v4
	v_mov_b32_e32 v4, v1
	v_mov_b32_e32 v16, v0
	v_pk_fma_f32 v[88:89], v[26:27], v[24:25], v[88:89]
	s_waitcnt vmcnt(0)
	v_lshlrev_b32_e32 v14, 16, v8
	v_and_b32_e32 v15, 0xffff0000, v8
	v_lshlrev_b32_e32 v8, 16, v9
	v_and_b32_e32 v9, 0xffff0000, v9
	v_pk_fma_f32 v[72:73], v[4:5], v[8:9], v[72:73]
	v_lshlrev_b32_e32 v0, 16, v10
	v_and_b32_e32 v1, 0xffff0000, v10
	v_mov_b32_e32 v4, v2
	v_mov_b32_e32 v5, v6
	v_pk_fma_f32 v[70:71], v[4:5], v[0:1], v[70:71]
	v_lshlrev_b32_e32 v0, 16, v11
	v_and_b32_e32 v1, 0xffff0000, v11
	v_mov_b32_e32 v6, v3
	v_pk_fma_f32 v[74:75], v[16:17], v[14:15], v[74:75]
	v_pk_fma_f32 v[68:69], v[6:7], v[0:1], v[68:69]
	s_cbranch_scc0 .LBB0_475
	v_lshlrev_b32_e32 v12, 1, v66
	v_lshl_add_u64 v[4:5], s[18:19], 0, v[12:13]
	v_lshlrev_b64 v[6:7], 11, v[64:65]
	v_cvt_pk_bf16_f32 v0, v108, v109
	v_cvt_pk_bf16_f32 v1, v106, v107
	v_cvt_pk_bf16_f32 v2, v104, v105
	v_cvt_pk_bf16_f32 v3, v102, v103
	v_lshl_add_u64 v[6:7], v[4:5], 0, v[6:7]
	global_store_dwordx4 v[6:7], v[0:3], off
	v_lshlrev_b64 v[6:7], 11, v[62:63]
	v_lshl_add_u64 v[6:7], v[4:5], 0, v[6:7]
	v_cvt_pk_bf16_f32 v0, v100, v101
	v_cvt_pk_bf16_f32 v1, v98, v99
	v_cvt_pk_bf16_f32 v2, v96, v97
	v_cvt_pk_bf16_f32 v3, v94, v95
	global_store_dwordx4 v[6:7], v[0:3], off
	v_lshlrev_b64 v[6:7], 11, v[60:61]
	v_lshl_add_u64 v[6:7], v[4:5], 0, v[6:7]
	v_cvt_pk_bf16_f32 v0, v88, v89
	v_cvt_pk_bf16_f32 v1, v86, v87
	v_cvt_pk_bf16_f32 v2, v84, v85
	v_cvt_pk_bf16_f32 v3, v82, v83
	global_store_dwordx4 v[6:7], v[0:3], off
	v_lshlrev_b64 v[6:7], 11, v[58:59]
	s_add_i32 s43, s43, s62
	s_add_i32 s42, s42, s62
	v_cvt_pk_bf16_f32 v0, v74, v75
	v_cvt_pk_bf16_f32 v1, v72, v73
	v_cvt_pk_bf16_f32 v2, v70, v71
	v_cvt_pk_bf16_f32 v3, v68, v69
	v_lshl_add_u64 v[4:5], v[4:5], 0, v[6:7]
	s_cmpk_gt_i32 s43, 0x87f
	global_store_dwordx4 v[4:5], v[0:3], off
	s_cbranch_scc0 .LBB0_474

; __device__ __forceinline__ int tidx() { int t = threadIdx.x; asm volatile("" : "+v"(t)); return t; }
; template <int NT>
; __device__ __forceinline__ void gemm_tile(f32x4 (&acc)[4][NT], const bf16_t* A, int lda, const bf16_t* B, int ldb, int K, bf16_t* sm) {
;     const int tid_ = tidx();
;     bf16_t* sA = sm; bf16_t* sB = sm + 128 * LDT;
;     const int tid = tid_, lane = tid & 63, wid = tid >> 6, wr = wid >> 1, wc = wid & 1;
;     const int fr = lane & 15, fq = lane >> 4;
;     const int lrow = tid >> 3, lkc = tid & 7;
;     const bf16_t* ga = A + (size_t)lrow * lda + lkc * 8;
;     const bf16_t* gb = B + (size_t)lrow * ldb + lkc * 8;
;     int sbrow[NT];
; #pragma unroll
;     for (int i = 0; i < NT; ++i) { const int g = lrow + 32 * i, W_ = 16 * NT, rem = g % W_; sbrow[i] = (g / W_) * W_ + (rem % NT) * 16 + rem / NT; }
;     u32x4 ra0[4], rb0[NT];
; #pragma unroll
;     for (int i = 0; i < 4; ++i) ra0[i] = *(const u32x4*)(ga + (size_t)(32 * i) * lda);
; #pragma unroll
;     for (int i = 0; i < NT; ++i) rb0[i] = *(const u32x4*)(gb + (size_t)(32 * i) * ldb);
; __device__ __forceinline__ void phase_ffn_in(const bf16_t* xb, const bf16_t* W, bf16_t* H, bf16_t* sm) {
;     ...
;     for (int t = blockIdx.x; t < 136 * 32; t += gridDim.x) {
;         const int tm = t >> 5, tn = t & 31;
;         f32x4 acc[4][4]; zero_acc<4>(acc);
;         gemm_tile<4>(acc, xb + (size_t)tm * 128 * 1024, 1024, W + (size_t)tn * 128 * 1024, 1024, 1024, sm);
.LBB0_1479:
	v_mov_b32_e32 v38, v192
	s_ashr_i32 s18, s11, 5
	v_ashrrev_i32_e32 v0, 31, v38
	v_ashrrev_i32_e32 v30, 3, v38
	v_lshrrev_b32_e32 v0, 26, v0
	v_add_u32_e32 v0, v30, v0
	v_lshrrev_b32_e32 v1, 6, v0
	v_mul_i32_i24_e32 v1, 64, v1
	v_sub_u32_e32 v1, v30, v1
	v_lshrrev_b16_sdwa v2, v196, sext(v1) dst_sel:DWORD dst_unused:UNUSED_PAD src0_sel:DWORD src1_sel:BYTE_0
	v_and_b32_e32 v2, 3, v2
	v_add_u16_e32 v2, v1, v2
	v_ashrrev_i16_sdwa v3, v197, sext(v2) dst_sel:DWORD dst_unused:UNUSED_PAD src0_sel:DWORD src1_sel:BYTE_0
	v_and_b32_e32 v2, 0xfc, v2
	v_sub_u16_e32 v1, v1, v2
	v_and_b32_e32 v0, 0x7ffffc0, v0
	v_lshlrev_b32_sdwa v1, v198, sext(v1) dst_sel:DWORD dst_unused:UNUSED_PAD src0_sel:DWORD src1_sel:BYTE_0
	v_bfe_i32 v2, v3, 0, 16
	v_add3_u32 v39, v0, v2, v1
	v_add_u32_e32 v0, 32, v30
	v_ashrrev_i32_e32 v1, 31, v0
	v_lshrrev_b32_e32 v1, 26, v1
	v_add_u32_e32 v1, v0, v1
	v_lshrrev_b32_e32 v2, 6, v1
	v_mul_i32_i24_e32 v2, 64, v2
	v_sub_u32_e32 v0, v0, v2
	v_lshrrev_b16_sdwa v2, v196, sext(v0) dst_sel:DWORD dst_unused:UNUSED_PAD src0_sel:DWORD src1_sel:BYTE_0
	v_and_b32_e32 v2, 3, v2
	v_add_u16_e32 v2, v0, v2
	v_ashrrev_i16_sdwa v3, v197, sext(v2) dst_sel:DWORD dst_unused:UNUSED_PAD src0_sel:DWORD src1_sel:BYTE_0
	v_and_b32_e32 v2, 0xfc, v2
	v_sub_u16_e32 v0, v0, v2
	v_and_b32_e32 v1, 0x7ffffc0, v1
	v_lshlrev_b32_sdwa v0, v198, sext(v0) dst_sel:DWORD dst_unused:UNUSED_PAD src0_sel:DWORD src1_sel:BYTE_0
	v_bfe_i32 v2, v3, 0, 16
	v_add3_u32 v40, v1, v2, v0
	v_add_u32_e32 v0, 64, v30
	v_ashrrev_i32_e32 v1, 31, v0
	v_lshrrev_b32_e32 v1, 26, v1
	v_add_u32_e32 v1, v0, v1
	v_lshrrev_b32_e32 v2, 6, v1
	v_mul_i32_i24_e32 v2, 64, v2
	v_sub_u32_e32 v0, v0, v2
	v_lshrrev_b16_sdwa v2, v196, sext(v0) dst_sel:DWORD dst_unused:UNUSED_PAD src0_sel:DWORD src1_sel:BYTE_0
	v_and_b32_e32 v2, 3, v2
	v_add_u16_e32 v2, v0, v2
	v_ashrrev_i16_sdwa v3, v197, sext(v2) dst_sel:DWORD dst_unused:UNUSED_PAD src0_sel:DWORD src1_sel:BYTE_0
	v_and_b32_e32 v2, 0xfc, v2
	v_sub_u16_e32 v0, v0, v2
	v_and_b32_e32 v1, 0x7ffffc0, v1
	v_lshlrev_b32_sdwa v0, v198, sext(v0) dst_sel:DWORD dst_unused:UNUSED_PAD src0_sel:DWORD src1_sel:BYTE_0
	v_bfe_i32 v2, v3, 0, 16
	s_waitcnt lgkmcnt(0)
	v_add3_u32 v41, v1, v2, v0
	v_add_u32_e32 v0, 0x60, v30
	v_ashrrev_i32_e32 v1, 31, v0
	v_lshrrev_b32_e32 v1, 26, v1
	v_add_u32_e32 v1, v0, v1
	v_lshrrev_b32_e32 v2, 6, v1
	v_mul_i32_i24_e32 v2, 64, v2
	v_sub_u32_e32 v0, v0, v2
	v_lshrrev_b16_sdwa v2, v196, sext(v0) dst_sel:DWORD dst_unused:UNUSED_PAD src0_sel:DWORD src1_sel:BYTE_0
	s_and_b32 s2, s10, 31
	s_ashr_i32 s19, s18, 31
	v_and_b32_e32 v2, 3, v2
	s_lshl_b32 s86, s2, 18
	s_and_b32 s12, s11, 31
	s_lshl_b64 s[22:23], s[18:19], 18
	v_add_u16_e32 v2, v0, v2
	s_add_u32 s24, s80, s22
	v_ashrrev_i16_sdwa v3, v197, sext(v2) dst_sel:DWORD dst_unused:UNUSED_PAD src0_sel:DWORD src1_sel:BYTE_0
	v_and_b32_e32 v2, 0xfc, v2
	s_addc_u32 s25, s81, s23
	s_lshl_b32 s2, s12, 18
	v_sub_u16_e32 v0, v0, v2
	s_add_u32 s40, s16, s2
	v_and_b32_e32 v1, 0x7ffffc0, v1
	v_lshlrev_b32_sdwa v0, v198, sext(v0) dst_sel:DWORD dst_unused:UNUSED_PAD src0_sel:DWORD src1_sel:BYTE_0
	v_bfe_i32 v2, v3, 0, 16
	v_ashrrev_i32_e32 v31, 31, v30
	s_addc_u32 s41, s17, 0
	v_add3_u32 v42, v1, v2, v0
	v_lshlrev_b64 v[32:33], 11, v[30:31]
	v_lshlrev_b32_e32 v2, 4, v38
	v_lshl_add_u64 v[0:1], s[40:41], 0, v[32:33]
	v_and_b32_e32 v12, 0x70, v2
	v_lshl_add_u64 v[8:9], v[0:1], 0, v[12:13]
	v_add_co_u32_e32 v0, vcc, s7, v8
	v_lshl_add_u64 v[18:19], s[24:25], 0, v[32:33]
	s_nop 0
	v_addc_co_u32_e32 v1, vcc, 0, v9, vcc
	v_add_co_u32_e32 v10, vcc, s37, v8
	v_lshl_add_u64 v[26:27], v[18:19], 0, v[12:13]
	s_nop 0
	v_addc_co_u32_e32 v11, vcc, 0, v9, vcc
	v_add_co_u32_e32 v14, vcc, s73, v8
	v_mov_b32_e32 v250, v8
	v_mov_b32_e32 v251, v9
	s_nop 0
	v_addc_co_u32_e32 v15, vcc, 0, v9, vcc
	v_add_co_u32_e32 v18, vcc, s7, v26
	s_nop 0
	v_addc_co_u32_e32 v19, vcc, 0, v27, vcc
	v_add_co_u32_e32 v28, vcc, s37, v26
	v_mov_b32_e32 v248, v26
	v_mov_b32_e32 v249, v27
	s_nop 0
	v_addc_co_u32_e32 v29, vcc, 0, v27, vcc
	v_add_co_u32_e32 v34, vcc, s73, v26
	v_and_b32_e32 v31, 15, v38
	s_nop 0
	v_addc_co_u32_e32 v35, vcc, 0, v27, vcc
	s_nop 0
	v_lshrrev_b32_e32 v44, 1, v38
	v_and_or_b32 v31, v44, s3, v31
	v_mul_lo_u32 v44, v31, s89
	v_mul_lo_u32 v45, v30, s89
	v_lshl_add_u64 v[30:31], s[22:23], 0, v[32:33]
	v_or_b32_e32 v30, v30, v12
	v_lshl_add_u64 v[98:99], s[58:59], 0, v[30:31]
	v_lshl_add_u64 v[30:31], s[86:87], 0, v[32:33]
	v_and_b32_e32 v43, 48, v38
	v_and_b32_e32 v38, 0x4f, v38
	v_or_b32_e32 v30, v30, v12
	v_mul_u32_u24_e32 v38, 0xa0, v38
	v_mul_lo_u32 v39, v39, s89
	v_mul_lo_u32 v40, v40, s89
	v_mul_lo_u32 v41, v41, s89
	v_mul_lo_u32 v42, v42, s89
	v_lshl_add_u64 v[100:101], s[16:17], 0, v[30:31]
	v_mov_b32_e32 v30, 0
	s_mov_b64 s[22:23], 0
	v_add_u32_e32 v105, v12, v45
	v_add_u32_e32 v106, v12, v39
	v_add_u32_e32 v107, v12, v40
	v_add_u32_e32 v108, v12, v41
	v_add_u32_e32 v109, v12, v42
	v_add_u32_e32 v104, v43, v44
; __device__ __forceinline__ int tidx() { int t = threadIdx.x; asm volatile("" : "+v"(t)); return t; }
; template <int NT>
; __device__ __forceinline__ void gemm_tile(f32x4 (&acc)[4][NT], const bf16_t* A, int lda, const bf16_t* B, int ldb, int K, bf16_t* sm) {
;     const int tid_ = tidx();
;     bf16_t* sA = sm; bf16_t* sB = sm + 128 * LDT;
;     const int tid = tid_, lane = tid & 63, wid = tid >> 6, wr = wid >> 1, wc = wid & 1;
;     const int fr = lane & 15, fq = lane >> 4;
;     const int lrow = tid >> 3, lkc = tid & 7;
;     const bf16_t* ga = A + (size_t)lrow * lda + lkc * 8;
;     const bf16_t* gb = B + (size_t)lrow * ldb + lkc * 8;
;     int sbrow[NT];
; #pragma unroll
;     for (int i = 0; i < NT; ++i) { const int g = lrow + 32 * i, W_ = 16 * NT, rem = g % W_; sbrow[i] = (g / W_) * W_ + (rem % NT) * 16 + rem / NT; }
;     u32x4 ra0[4], rb0[NT];
; #pragma unroll
;     for (int i = 0; i < 4; ++i) ra0[i] = *(const u32x4*)(ga + (size_t)(32 * i) * lda);
; #pragma unroll
;     for (int i = 0; i < NT; ++i) rb0[i] = *(const u32x4*)(gb + (size_t)(32 * i) * ldb);
;     const int nk = K >> 6;
;     for (int kt = 0; kt < nk; ++kt) {
;         lds_barrier();
; #pragma unroll
;         for (int i = 0; i < 4; ++i) *(u32x4*)(sA + (lrow + 32 * i) * LDT + lkc * 8) = ra0[i];
; #pragma unroll
;         for (int i = 0; i < NT; ++i) *(u32x4*)(sB + sbrow[i] * LDT + lkc * 8) = rb0[i];
;         lds_barrier();
;         if (kt + 1 < nk) {
;             ga += 64; gb += 64;
; #pragma unroll
;             for (int i = 0; i < 4; ++i) ra0[i] = *(const u32x4*)(ga + (size_t)(32 * i) * lda);
; #pragma unroll
;             for (int i = 0; i < NT; ++i) rb0[i] = *(const u32x4*)(gb + (size_t)(32 * i) * ldb);
;         }
; template <int NT> __device__ __forceinline__ void zero_acc(f32x4 (&acc)[4][NT]) {
; #pragma unroll
;     for (int mt = 0; mt < 4; ++mt)
; #pragma unroll
;         for (int nt = 0; nt < NT; ++nt) acc[mt][nt] = (f32x4){0.f, 0.f, 0.f, 0.f};
; }
	v_add_u32_e32 v12, v43, v38
	v_mov_b32_e32 v31, v30
	v_mov_b32_e32 v32, v30
	v_mov_b32_e32 v33, v30
	v_mov_b32_e32 v38, v30
	v_mov_b32_e32 v39, v30
	v_mov_b32_e32 v40, v30
	v_mov_b32_e32 v41, v30
	v_mov_b32_e32 v42, v30
	v_mov_b32_e32 v43, v30
	v_mov_b32_e32 v44, v30
	v_mov_b32_e32 v45, v30
	v_mov_b32_e32 v46, v30
	v_mov_b32_e32 v47, v30
	v_mov_b32_e32 v48, v30
	v_mov_b32_e32 v49, v30
	v_mov_b32_e32 v50, v30
	v_mov_b32_e32 v51, v30
	v_mov_b32_e32 v52, v30
	v_mov_b32_e32 v53, v30
	v_mov_b32_e32 v54, v30
	v_mov_b32_e32 v55, v30
	v_mov_b32_e32 v56, v30
	v_mov_b32_e32 v57, v30
	v_mov_b32_e32 v58, v30
	v_mov_b32_e32 v59, v30
	v_mov_b32_e32 v60, v30
	v_mov_b32_e32 v61, v30
	v_mov_b32_e32 v62, v30
	v_mov_b32_e32 v63, v30
	v_mov_b32_e32 v64, v30
	v_mov_b32_e32 v65, v30
	v_mov_b32_e32 v66, v30
	v_mov_b32_e32 v67, v30
	v_mov_b32_e32 v68, v30
	v_mov_b32_e32 v69, v30
	v_mov_b32_e32 v70, v30
	v_mov_b32_e32 v71, v30
	v_mov_b32_e32 v72, v30
	v_mov_b32_e32 v73, v30
	v_mov_b32_e32 v74, v30
	v_mov_b32_e32 v75, v30
	v_mov_b32_e32 v76, v30
	v_mov_b32_e32 v77, v30
	v_mov_b32_e32 v78, v30
	v_mov_b32_e32 v79, v30
	v_mov_b32_e32 v80, v30
	v_mov_b32_e32 v81, v30
	v_mov_b32_e32 v82, v30
	v_mov_b32_e32 v83, v30
	v_mov_b32_e32 v84, v30
	v_mov_b32_e32 v85, v30
	v_mov_b32_e32 v86, v30
	v_mov_b32_e32 v87, v30
	v_mov_b32_e32 v88, v30
	v_mov_b32_e32 v89, v30
	v_mov_b32_e32 v90, v30
	v_mov_b32_e32 v91, v30
	v_mov_b32_e32 v92, v30
	v_mov_b32_e32 v93, v30
	v_mov_b32_e32 v94, v30
	v_mov_b32_e32 v95, v30
	v_mov_b32_e32 v96, v30
	v_mov_b32_e32 v97, v30
	v_writelane_b32 v234, s90, 0
	v_writelane_b32 v234, s91, 1
	v_writelane_b32 v234, s92, 2
	v_writelane_b32 v234, s93, 3
	v_writelane_b32 v234, s94, 4
	v_writelane_b32 v234, s95, 5
	v_bfe_u32 v160, v192, 3, 3
	v_and_b32_e32 v161, 7, v192
	v_xor_b32_e32 v161, v160, v161
	v_lshlrev_b32_e32 v161, 4, v161
	v_lshrrev_b32_e32 v162, 6, v192
	v_lshl_add_u32 v163, v162, 5, v160
	v_mul_u32_u24_e32 v163, 0x800, v163
	v_add_u32_e32 v236, v163, v161
	v_add_u32_e32 v237, 0x3c00, v236
	v_add_u32_e32 v238, 0x3c00, v237
	v_add_u32_e32 v239, 0x3c00, v238
	v_lshrrev_b32_e32 v163, 7, v192
	v_bfe_u32 v162, v192, 6, 1
	v_lshlrev_b32_e32 v163, 6, v163
	v_lshl_add_u32 v163, v160, 2, v163
	v_lshl_add_u32 v163, v162, 1, v163
	v_mul_u32_u24_e32 v163, 0x800, v163
	v_add_u32_e32 v240, v163, v161
	v_add_u32_e32 v241, 0xfc00, v240
	v_subrev_u32_e32 v242, 0xfc00, v241
	v_add_u32_e32 v243, 0xfc00, v242
	v_and_b32_e32 v160, 15, v192
	v_bfe_u32 v161, v192, 4, 2
	v_and_b32_e32 v162, 7, v160
	v_xor_b32_e32 v161, v161, v162
	v_lshlrev_b32_e32 v161, 4, v161
	v_lshl_add_u32 v161, v160, 7, v161
	v_lshrrev_b32_e32 v162, 7, v192
	v_lshl_add_u32 v244, v162, 13, v161
	v_bfe_u32 v162, v192, 6, 1
	v_lshl_add_u32 v246, v162, 13, v161
	v_add_u32_e32 v246, 0x4000, v246
	v_xor_b32_e32 v245, 64, v244
	v_xor_b32_e32 v247, 64, v246
	v_lshrrev_b32_e32 v160, 6, v192
	s_nop 0
	v_readfirstlane_b32 s94, v160
	v_readfirstlane_b32 s90, v248
	v_readfirstlane_b32 s91, v249
	v_readfirstlane_b32 s92, v250
	v_readfirstlane_b32 s93, v251
	s_mul_i32 s95, s94, 0x4000
	s_sub_u32 s90, s90, s95
	s_subb_u32 s91, s91, 0
	s_mul_i32 s95, s94, 0x4000
	s_sub_u32 s92, s92, s95
	s_subb_u32 s93, s93, 0
	s_lshl_b32 s94, s94, 10
	s_waitcnt lgkmcnt(0)
	s_barrier
	s_lshl_b32 s95, s94, 2
	s_add_u32 m0, s95, 0x0
	s_nop 0
	global_load_lds_dwordx4 v236, s[90:91] sc1
	global_load_lds_dwordx4 v237, s[90:91] offset:1024 sc1
	global_load_lds_dwordx4 v238, s[90:91] offset:2048 sc1
	global_load_lds_dwordx4 v239, s[90:91] offset:3072 sc1
	s_mul_i32 s95, s94, 4
	s_add_u32 m0, s95, 0x4000
	s_nop 0
	global_load_lds_dwordx4 v240, s[92:93]
	global_load_lds_dwordx4 v241, s[92:93] offset:1024
	global_load_lds_dwordx4 v242, s[92:93] offset:2048
	global_load_lds_dwordx4 v243, s[92:93] offset:3072
	s_add_u32 s90, s90, 0x80
	s_addc_u32 s91, s91, 0
	s_add_u32 s92, s92, 0x80
	s_addc_u32 s93, s93, 0
	s_waitcnt vmcnt(0)
	s_barrier
	s_lshl_b32 s95, s94, 2
	s_add_u32 m0, s95, 0x8000
	s_nop 0
	global_load_lds_dwordx4 v236, s[90:91] sc1
	global_load_lds_dwordx4 v237, s[90:91] offset:1024 sc1
	global_load_lds_dwordx4 v238, s[90:91] offset:2048 sc1
	global_load_lds_dwordx4 v239, s[90:91] offset:3072 sc1
	s_mul_i32 s95, s94, 4
	s_add_u32 m0, s95, 0xc000
	s_nop 0
	global_load_lds_dwordx4 v240, s[92:93]
	global_load_lds_dwordx4 v241, s[92:93] offset:1024
	global_load_lds_dwordx4 v242, s[92:93] offset:2048
	global_load_lds_dwordx4 v243, s[92:93] offset:3072
	s_add_u32 s90, s90, 0x80
	s_addc_u32 s91, s91, 0
	s_add_u32 s92, s92, 0x80
	s_addc_u32 s93, s93, 0
	ds_read_b128 v[110:113], v244 offset:0
	ds_read_b128 v[114:117], v244 offset:2048
	ds_read_b128 v[118:121], v244 offset:4096
	ds_read_b128 v[122:125], v244 offset:6144
	ds_read_b128 v[126:129], v246 offset:0
	ds_read_b128 v[130:133], v246 offset:2048
	ds_read_b128 v[134:137], v246 offset:4096
	ds_read_b128 v[138:141], v246 offset:6144
	s_movk_i32 s95, 0x6
	s_cmp_eq_u32 s95, 0
	s_cbranch_scc1 .Lgemm_x1480

; template <int NT>
; __device__ __forceinline__ void gemm_compute(f32x4 (&acc)[4][NT], const bf16_t* sA, const bf16_t* sB, int wr, int wc, int fr, int fq) {
;     ...
;     for (int ks = 0; ks < 2; ++ks) {
;         bf16x8 a[4], b[NT];
; #pragma unroll
;         for (int mt = 0; mt < 4; ++mt) a[mt] = *(const bf16x8*)(sA + (wr * 64 + mt * 16 + fr) * LDT + ks * 32 + fq * 8);
; #pragma unroll
;         for (int nt = 0; nt < NT; ++nt) b[nt] = *(const bf16x8*)(sB + (wc * 16 * NT + nt * 16 + fr) * LDT + ks * 32 + fq * 8);
;         __builtin_amdgcn_s_setprio(1);
; #pragma unroll
;         for (int mt = 0; mt < 4; ++mt)
; #pragma unroll
;             for (int nt = 0; nt < NT; ++nt)
;                 acc[mt][nt] = __builtin_amdgcn_mfma_f32_16x16x32_bf16(b[nt], a[mt], acc[mt][nt], 0, 0, 0);
;         __builtin_amdgcn_s_setprio(0);
;     }
; template <int NT>
; __device__ __forceinline__ void gemm_tile(f32x4 (&acc)[4][NT], const bf16_t* A, int lda, const bf16_t* B, int ldb, int K, bf16_t* sm) {
;     ...
;     for (int kt = 0; kt < nk; ++kt) {
;         lds_barrier();
; #pragma unroll
;         for (int i = 0; i < 4; ++i) *(u32x4*)(sA + (lrow + 32 * i) * LDT + lkc * 8) = ra0[i];
; #pragma unroll
;         for (int i = 0; i < NT; ++i) *(u32x4*)(sB + sbrow[i] * LDT + lkc * 8) = rb0[i];
;         lds_barrier();
;         if (kt + 1 < nk) {
;             ga += 64; gb += 64;
; #pragma unroll
;             for (int i = 0; i < 4; ++i) ra0[i] = *(const u32x4*)(ga + (size_t)(32 * i) * lda);
; #pragma unroll
;             for (int i = 0; i < NT; ++i) rb0[i] = *(const u32x4*)(gb + (size_t)(32 * i) * ldb);
;         }
;         __builtin_amdgcn_sched_barrier(0);
;         gemm_compute<NT>(acc, sA, sB, wr, wc, fr, fq);
;         __builtin_amdgcn_sched_barrier(0);
;     }
.Lgemm_x1480:
	ds_read_b128 v[160:163], v245 offset:0
	ds_read_b128 v[164:167], v245 offset:2048
	ds_read_b128 v[168:171], v245 offset:4096
	ds_read_b128 v[172:175], v245 offset:6144
	ds_read_b128 v[176:179], v247 offset:0
	ds_read_b128 v[180:183], v247 offset:2048
	ds_read_b128 v[184:187], v247 offset:4096
	ds_read_b128 v[188:191], v247 offset:6144
	s_setprio 1
	s_waitcnt lgkmcnt(11)
	v_mfma_f32_16x16x32_bf16 v[94:97], v[126:129], v[110:113], v[94:97]
	s_waitcnt lgkmcnt(10)
	v_mfma_f32_16x16x32_bf16 v[90:93], v[130:133], v[110:113], v[90:93]
	s_waitcnt lgkmcnt(9)
	v_mfma_f32_16x16x32_bf16 v[86:89], v[134:137], v[110:113], v[86:89]
	s_waitcnt lgkmcnt(8)
	v_mfma_f32_16x16x32_bf16 v[82:85], v[138:141], v[110:113], v[82:85]
	v_mfma_f32_16x16x32_bf16 v[78:81], v[126:129], v[114:117], v[78:81]
	v_mfma_f32_16x16x32_bf16 v[74:77], v[130:133], v[114:117], v[74:77]
	v_mfma_f32_16x16x32_bf16 v[70:73], v[134:137], v[114:117], v[70:73]
	v_mfma_f32_16x16x32_bf16 v[66:69], v[138:141], v[114:117], v[66:69]
	v_mfma_f32_16x16x32_bf16 v[62:65], v[126:129], v[118:121], v[62:65]
	v_mfma_f32_16x16x32_bf16 v[58:61], v[130:133], v[118:121], v[58:61]
	v_mfma_f32_16x16x32_bf16 v[54:57], v[134:137], v[118:121], v[54:57]
	v_mfma_f32_16x16x32_bf16 v[50:53], v[138:141], v[118:121], v[50:53]
	v_mfma_f32_16x16x32_bf16 v[46:49], v[126:129], v[122:125], v[46:49]
	v_mfma_f32_16x16x32_bf16 v[42:45], v[130:133], v[122:125], v[42:45]
	v_mfma_f32_16x16x32_bf16 v[38:41], v[134:137], v[122:125], v[38:41]
	v_mfma_f32_16x16x32_bf16 v[30:33], v[138:141], v[122:125], v[30:33]
	s_setprio 0
	s_waitcnt vmcnt(0) lgkmcnt(0)
	s_barrier
	ds_read_b128 v[110:113], v244 offset:32768
	ds_read_b128 v[114:117], v244 offset:34816
	ds_read_b128 v[118:121], v244 offset:36864
	ds_read_b128 v[122:125], v244 offset:38912
	ds_read_b128 v[126:129], v246 offset:32768
	ds_read_b128 v[130:133], v246 offset:34816
	ds_read_b128 v[134:137], v246 offset:36864
	ds_read_b128 v[138:141], v246 offset:38912
	s_setprio 1
	v_mfma_f32_16x16x32_bf16 v[94:97], v[176:179], v[160:163], v[94:97]
	s_lshl_b32 s95, s94, 2
	s_add_u32 m0, s95, 0x0
	s_nop 0
	global_load_lds_dwordx4 v236, s[90:91] sc1
	v_mfma_f32_16x16x32_bf16 v[90:93], v[180:183], v[160:163], v[90:93]
	v_mfma_f32_16x16x32_bf16 v[86:89], v[184:187], v[160:163], v[86:89]
	global_load_lds_dwordx4 v237, s[90:91] offset:1024 sc1
	v_mfma_f32_16x16x32_bf16 v[82:85], v[188:191], v[160:163], v[82:85]
	v_mfma_f32_16x16x32_bf16 v[78:81], v[176:179], v[164:167], v[78:81]
	global_load_lds_dwordx4 v238, s[90:91] offset:2048 sc1
	v_mfma_f32_16x16x32_bf16 v[74:77], v[180:183], v[164:167], v[74:77]
	v_mfma_f32_16x16x32_bf16 v[70:73], v[184:187], v[164:167], v[70:73]
	global_load_lds_dwordx4 v239, s[90:91] offset:3072 sc1
	v_mfma_f32_16x16x32_bf16 v[66:69], v[188:191], v[164:167], v[66:69]
	v_mfma_f32_16x16x32_bf16 v[62:65], v[176:179], v[168:171], v[62:65]
	s_mul_i32 s95, s94, 4
	s_add_u32 m0, s95, 0x4000
	s_nop 0
	global_load_lds_dwordx4 v240, s[92:93]
	v_mfma_f32_16x16x32_bf16 v[58:61], v[180:183], v[168:171], v[58:61]
	v_mfma_f32_16x16x32_bf16 v[54:57], v[184:187], v[168:171], v[54:57]
	global_load_lds_dwordx4 v241, s[92:93] offset:1024
	v_mfma_f32_16x16x32_bf16 v[50:53], v[188:191], v[168:171], v[50:53]
	v_mfma_f32_16x16x32_bf16 v[46:49], v[176:179], v[172:175], v[46:49]
	global_load_lds_dwordx4 v242, s[92:93] offset:2048
	v_mfma_f32_16x16x32_bf16 v[42:45], v[180:183], v[172:175], v[42:45]
	v_mfma_f32_16x16x32_bf16 v[38:41], v[184:187], v[172:175], v[38:41]
	global_load_lds_dwordx4 v243, s[92:93] offset:3072
	v_mfma_f32_16x16x32_bf16 v[30:33], v[188:191], v[172:175], v[30:33]
	s_add_u32 s90, s90, 0x80
	s_addc_u32 s91, s91, 0
	s_add_u32 s92, s92, 0x80
	s_addc_u32 s93, s93, 0
	s_setprio 0
	ds_read_b128 v[160:163], v245 offset:32768
	ds_read_b128 v[164:167], v245 offset:34816
	ds_read_b128 v[168:171], v245 offset:36864
	ds_read_b128 v[172:175], v245 offset:38912
	ds_read_b128 v[176:179], v247 offset:32768
	ds_read_b128 v[180:183], v247 offset:34816
	ds_read_b128 v[184:187], v247 offset:36864
	ds_read_b128 v[188:191], v247 offset:38912
	s_setprio 1
	s_waitcnt lgkmcnt(11)
	v_mfma_f32_16x16x32_bf16 v[94:97], v[126:129], v[110:113], v[94:97]
	s_waitcnt lgkmcnt(10)
	v_mfma_f32_16x16x32_bf16 v[90:93], v[130:133], v[110:113], v[90:93]
	s_waitcnt lgkmcnt(9)
	v_mfma_f32_16x16x32_bf16 v[86:89], v[134:137], v[110:113], v[86:89]
	s_waitcnt lgkmcnt(8)
	v_mfma_f32_16x16x32_bf16 v[82:85], v[138:141], v[110:113], v[82:85]
	v_mfma_f32_16x16x32_bf16 v[78:81], v[126:129], v[114:117], v[78:81]
	v_mfma_f32_16x16x32_bf16 v[74:77], v[130:133], v[114:117], v[74:77]
	v_mfma_f32_16x16x32_bf16 v[70:73], v[134:137], v[114:117], v[70:73]
	v_mfma_f32_16x16x32_bf16 v[66:69], v[138:141], v[114:117], v[66:69]
	v_mfma_f32_16x16x32_bf16 v[62:65], v[126:129], v[118:121], v[62:65]
	v_mfma_f32_16x16x32_bf16 v[58:61], v[130:133], v[118:121], v[58:61]
	v_mfma_f32_16x16x32_bf16 v[54:57], v[134:137], v[118:121], v[54:57]
	v_mfma_f32_16x16x32_bf16 v[50:53], v[138:141], v[118:121], v[50:53]
	v_mfma_f32_16x16x32_bf16 v[46:49], v[126:129], v[122:125], v[46:49]
	v_mfma_f32_16x16x32_bf16 v[42:45], v[130:133], v[122:125], v[42:45]
	v_mfma_f32_16x16x32_bf16 v[38:41], v[134:137], v[122:125], v[38:41]
	v_mfma_f32_16x16x32_bf16 v[30:33], v[138:141], v[122:125], v[30:33]
	s_setprio 0
	s_waitcnt vmcnt(0) lgkmcnt(0)
	s_barrier
; template <int NT>
; __device__ __forceinline__ void gemm_compute(f32x4 (&acc)[4][NT], const bf16_t* sA, const bf16_t* sB, int wr, int wc, int fr, int fq) {
;     ...
;     for (int ks = 0; ks < 2; ++ks) {
;         bf16x8 a[4], b[NT];
; #pragma unroll
;         for (int mt = 0; mt < 4; ++mt) a[mt] = *(const bf16x8*)(sA + (wr * 64 + mt * 16 + fr) * LDT + ks * 32 + fq * 8);
; #pragma unroll
;         for (int nt = 0; nt < NT; ++nt) b[nt] = *(const bf16x8*)(sB + (wc * 16 * NT + nt * 16 + fr) * LDT + ks * 32 + fq * 8);
;         __builtin_amdgcn_s_setprio(1);
; #pragma unroll
;         for (int mt = 0; mt < 4; ++mt)
; #pragma unroll
;             for (int nt = 0; nt < NT; ++nt)
;                 acc[mt][nt] = __builtin_amdgcn_mfma_f32_16x16x32_bf16(b[nt], a[mt], acc[mt][nt], 0, 0, 0);
;         __builtin_amdgcn_s_setprio(0);
;     }
; template <int NT>
; __device__ __forceinline__ void gemm_tile(f32x4 (&acc)[4][NT], const bf16_t* A, int lda, const bf16_t* B, int ldb, int K, bf16_t* sm) {
;     ...
;     for (int kt = 0; kt < nk; ++kt) {
;         lds_barrier();
; #pragma unroll
;         for (int i = 0; i < 4; ++i) *(u32x4*)(sA + (lrow + 32 * i) * LDT + lkc * 8) = ra0[i];
; #pragma unroll
;         for (int i = 0; i < NT; ++i) *(u32x4*)(sB + sbrow[i] * LDT + lkc * 8) = rb0[i];
;         lds_barrier();
;         if (kt + 1 < nk) {
;             ga += 64; gb += 64;
; #pragma unroll
;             for (int i = 0; i < 4; ++i) ra0[i] = *(const u32x4*)(ga + (size_t)(32 * i) * lda);
; #pragma unroll
;             for (int i = 0; i < NT; ++i) rb0[i] = *(const u32x4*)(gb + (size_t)(32 * i) * ldb);
;         }
;         __builtin_amdgcn_sched_barrier(0);
;         gemm_compute<NT>(acc, sA, sB, wr, wc, fr, fq);
;         __builtin_amdgcn_sched_barrier(0);
;     }
	ds_read_b128 v[110:113], v244 offset:0
	ds_read_b128 v[114:117], v244 offset:2048
	ds_read_b128 v[118:121], v244 offset:4096
	ds_read_b128 v[122:125], v244 offset:6144
	ds_read_b128 v[126:129], v246 offset:0
	ds_read_b128 v[130:133], v246 offset:2048
	ds_read_b128 v[134:137], v246 offset:4096
	ds_read_b128 v[138:141], v246 offset:6144
	s_setprio 1
	v_mfma_f32_16x16x32_bf16 v[94:97], v[176:179], v[160:163], v[94:97]
	v_readlane_b32 s90, v234, 0
	v_readlane_b32 s91, v234, 1
	v_readlane_b32 s92, v234, 2
	v_readlane_b32 s93, v234, 3
	v_readlane_b32 s94, v234, 4
	v_readlane_b32 s95, v234, 5
	s_mov_b32 s22, 0x700
	s_mov_b32 s23, 0
	s_nop 3
	v_mfma_f32_16x16x32_bf16 v[90:93], v[180:183], v[160:163], v[90:93]
	v_mfma_f32_16x16x32_bf16 v[86:89], v[184:187], v[160:163], v[86:89]
	v_lshl_add_u64 v[0:1], v[98:99], 0, s[22:23]
	v_mfma_f32_16x16x32_bf16 v[82:85], v[188:191], v[160:163], v[82:85]
	v_mfma_f32_16x16x32_bf16 v[78:81], v[176:179], v[164:167], v[78:81]
	v_add_co_u32_e32 v2, vcc, s0, v0
	v_mfma_f32_16x16x32_bf16 v[74:77], v[180:183], v[164:167], v[74:77]
	v_mfma_f32_16x16x32_bf16 v[70:73], v[184:187], v[164:167], v[70:73]
	s_nop 0
	v_mfma_f32_16x16x32_bf16 v[66:69], v[188:191], v[164:167], v[66:69]
	v_mfma_f32_16x16x32_bf16 v[62:65], v[176:179], v[168:171], v[62:65]
	s_nop 0
	v_mfma_f32_16x16x32_bf16 v[58:61], v[180:183], v[168:171], v[58:61]
	v_mfma_f32_16x16x32_bf16 v[54:57], v[184:187], v[168:171], v[54:57]
	v_addc_co_u32_e32 v3, vcc, 0, v1, vcc
	v_mfma_f32_16x16x32_bf16 v[50:53], v[188:191], v[168:171], v[50:53]
	v_mfma_f32_16x16x32_bf16 v[46:49], v[176:179], v[172:175], v[46:49]
	v_add_co_u32_e32 v4, vcc, s64, v0
	v_mfma_f32_16x16x32_bf16 v[42:45], v[180:183], v[172:175], v[42:45]
	v_mfma_f32_16x16x32_bf16 v[38:41], v[184:187], v[172:175], v[38:41]
	v_lshl_add_u64 v[8:9], v[100:101], 0, s[22:23]
	v_mfma_f32_16x16x32_bf16 v[30:33], v[188:191], v[172:175], v[30:33]
	s_nop 0
	v_addc_co_u32_e32 v5, vcc, 0, v1, vcc
	global_load_dwordx4 v[22:25], v[2:3], off offset:128
	global_load_dwordx4 v[18:21], v[4:5], off offset:128
	v_add_co_u32_e32 v2, vcc, s65, v0
	s_nop 1
	v_addc_co_u32_e32 v3, vcc, 0, v1, vcc
	v_add_co_u32_e32 v0, vcc, s33, v0
	s_nop 1
	v_addc_co_u32_e32 v1, vcc, 0, v1, vcc
	global_load_dwordx4 v[26:29], v[2:3], off offset:128
	global_load_dwordx4 v[34:37], v[0:1], off offset:128
	v_add_co_u32_e32 v0, vcc, s7, v8
	s_nop 1
	v_addc_co_u32_e32 v1, vcc, 0, v9, vcc
	v_add_co_u32_e32 v10, vcc, s37, v8
	global_load_dwordx4 v[4:7], v[8:9], off offset:128
	s_nop 0
	global_load_dwordx4 v[0:3], v[0:1], off offset:128
	v_addc_co_u32_e32 v11, vcc, 0, v9, vcc
	v_add_co_u32_e32 v14, vcc, s73, v8
	s_nop 1
	v_addc_co_u32_e32 v15, vcc, 0, v9, vcc
	global_load_dwordx4 v[8:11], v[10:11], off offset:128
	s_nop 0
	global_load_dwordx4 v[14:17], v[14:15], off offset:128
	s_setprio 0
	ds_read_b128 v[160:163], v245 offset:0
	ds_read_b128 v[164:167], v245 offset:2048
	ds_read_b128 v[168:171], v245 offset:4096
	ds_read_b128 v[172:175], v245 offset:6144
	ds_read_b128 v[176:179], v247 offset:0
	ds_read_b128 v[180:183], v247 offset:2048
	ds_read_b128 v[184:187], v247 offset:4096
	ds_read_b128 v[188:191], v247 offset:6144
	s_setprio 1
	s_waitcnt lgkmcnt(11)
	v_mfma_f32_16x16x32_bf16 v[94:97], v[126:129], v[110:113], v[94:97]
	s_waitcnt lgkmcnt(10)
	v_mfma_f32_16x16x32_bf16 v[90:93], v[130:133], v[110:113], v[90:93]
	s_waitcnt lgkmcnt(9)
	v_mfma_f32_16x16x32_bf16 v[86:89], v[134:137], v[110:113], v[86:89]
	s_waitcnt lgkmcnt(8)
	v_mfma_f32_16x16x32_bf16 v[82:85], v[138:141], v[110:113], v[82:85]
	v_mfma_f32_16x16x32_bf16 v[78:81], v[126:129], v[114:117], v[78:81]
	v_mfma_f32_16x16x32_bf16 v[74:77], v[130:133], v[114:117], v[74:77]
	v_mfma_f32_16x16x32_bf16 v[70:73], v[134:137], v[114:117], v[70:73]
	v_mfma_f32_16x16x32_bf16 v[66:69], v[138:141], v[114:117], v[66:69]
	v_mfma_f32_16x16x32_bf16 v[62:65], v[126:129], v[118:121], v[62:65]
	v_mfma_f32_16x16x32_bf16 v[58:61], v[130:133], v[118:121], v[58:61]
	v_mfma_f32_16x16x32_bf16 v[54:57], v[134:137], v[118:121], v[54:57]
	v_mfma_f32_16x16x32_bf16 v[50:53], v[138:141], v[118:121], v[50:53]
	v_mfma_f32_16x16x32_bf16 v[46:49], v[126:129], v[122:125], v[46:49]
	v_mfma_f32_16x16x32_bf16 v[42:45], v[130:133], v[122:125], v[42:45]
	v_mfma_f32_16x16x32_bf16 v[38:41], v[134:137], v[122:125], v[38:41]
	v_mfma_f32_16x16x32_bf16 v[30:33], v[138:141], v[122:125], v[30:33]
	s_setprio 0
	s_waitcnt lgkmcnt(0)
	s_setprio 1
	v_mfma_f32_16x16x32_bf16 v[94:97], v[176:179], v[160:163], v[94:97]
	v_mfma_f32_16x16x32_bf16 v[90:93], v[180:183], v[160:163], v[90:93]
	v_mfma_f32_16x16x32_bf16 v[86:89], v[184:187], v[160:163], v[86:89]
	v_mfma_f32_16x16x32_bf16 v[82:85], v[188:191], v[160:163], v[82:85]
	v_mfma_f32_16x16x32_bf16 v[78:81], v[176:179], v[164:167], v[78:81]
	v_mfma_f32_16x16x32_bf16 v[74:77], v[180:183], v[164:167], v[74:77]
	v_mfma_f32_16x16x32_bf16 v[70:73], v[184:187], v[164:167], v[70:73]
	v_mfma_f32_16x16x32_bf16 v[66:69], v[188:191], v[164:167], v[66:69]
	v_mfma_f32_16x16x32_bf16 v[62:65], v[176:179], v[168:171], v[62:65]
	v_mfma_f32_16x16x32_bf16 v[58:61], v[180:183], v[168:171], v[58:61]
	v_mfma_f32_16x16x32_bf16 v[54:57], v[184:187], v[168:171], v[54:57]
	v_mfma_f32_16x16x32_bf16 v[50:53], v[188:191], v[168:171], v[50:53]
	v_mfma_f32_16x16x32_bf16 v[46:49], v[176:179], v[172:175], v[46:49]
	v_mfma_f32_16x16x32_bf16 v[42:45], v[180:183], v[172:175], v[42:45]
	v_mfma_f32_16x16x32_bf16 v[38:41], v[184:187], v[172:175], v[38:41]
	v_mfma_f32_16x16x32_bf16 v[30:33], v[188:191], v[172:175], v[30:33]
	s_setprio 0
	s_waitcnt lgkmcnt(0)
	s_barrier
; __device__ __forceinline__ float silu_(float x) { return x * __builtin_amdgcn_rcpf(1.f + __expf(-x)); }
; template <int NT>
; __device__ __forceinline__ void gemm_tile(f32x4 (&acc)[4][NT], const bf16_t* A, int lda, const bf16_t* B, int ldb, int K, bf16_t* sm) {
;     ...
;         lds_barrier();
; #pragma unroll
;         for (int i = 0; i < 4; ++i) *(u32x4*)(sA + (lrow + 32 * i) * LDT + lkc * 8) = ra0[i];
; #pragma unroll
;         for (int i = 0; i < NT; ++i) *(u32x4*)(sB + sbrow[i] * LDT + lkc * 8) = rb0[i];
;         lds_barrier();
;         if (kt + 1 < nk) {
;             ga += 64; gb += 64;
; #pragma unroll
;             for (int i = 0; i < 4; ++i) ra0[i] = *(const u32x4*)(ga + (size_t)(32 * i) * lda);
; #pragma unroll
;             for (int i = 0; i < NT; ++i) rb0[i] = *(const u32x4*)(gb + (size_t)(32 * i) * ldb);
;         }
;         __builtin_amdgcn_sched_barrier(0);
;         gemm_compute<NT>(acc, sA, sB, wr, wc, fr, fq);
; __device__ __forceinline__ void phase_ffn_in(const bf16_t* xb, const bf16_t* W, bf16_t* H, bf16_t* sm) {
;     ...
; #pragma unroll
;         for (int mt = 0; mt < 4; ++mt) {
;             const int row = tm * 128 + wr * 64 + mt * 16 + fr;
;             const int hc = tn * 64 + wc * 32 + fq * 8;
;             float v[16]; gather_cols<4>(acc, mt, v);
;             u32x4 o;
; #pragma unroll
;             for (int q = 0; q < 4; ++q) o[q] = pack2(silu_(v[4 * q]) * v[4 * q + 1], silu_(v[4 * q + 2]) * v[4 * q + 3]);
;             *(u32x4*)(H + (size_t)row * 2048 + hc) = o;
;         }
	s_waitcnt vmcnt(7)
	ds_write_b128 v105, v[22:25]
	s_waitcnt vmcnt(6)
	ds_write_b128 v105, v[18:21] offset:5120
	s_waitcnt vmcnt(5)
	ds_write_b128 v105, v[26:29] offset:10240
	s_waitcnt vmcnt(4)
	ds_write_b128 v105, v[34:37] offset:15360
	s_waitcnt vmcnt(3)
	ds_write_b128 v106, v[4:7] offset:20480
	s_waitcnt vmcnt(2)
	ds_write_b128 v107, v[0:3] offset:20480
	s_waitcnt vmcnt(1)
	ds_write_b128 v108, v[8:11] offset:20480
	s_waitcnt vmcnt(0)
	ds_write_b128 v109, v[14:17] offset:20480
	s_waitcnt lgkmcnt(0)
	s_barrier
	ds_read_b128 v[0:3], v104
	ds_read_b128 v[4:7], v104 offset:2560
	ds_read_b128 v[8:11], v104 offset:5120
	ds_read_b128 v[14:17], v104 offset:7680
	ds_read_b128 v[18:21], v12 offset:20480
	ds_read_b128 v[22:25], v12 offset:23040
	ds_read_b128 v[26:29], v12 offset:25600
	ds_read_b128 v[34:37], v12 offset:28160
	s_setprio 1
	s_waitcnt lgkmcnt(3)
	v_mfma_f32_16x16x32_bf16 v[94:97], v[18:21], v[0:3], v[94:97]
	s_waitcnt lgkmcnt(2)
	v_mfma_f32_16x16x32_bf16 v[90:93], v[22:25], v[0:3], v[90:93]
	s_waitcnt lgkmcnt(1)
	v_mfma_f32_16x16x32_bf16 v[86:89], v[26:29], v[0:3], v[86:89]
	s_waitcnt lgkmcnt(0)
	v_mfma_f32_16x16x32_bf16 v[0:3], v[34:37], v[0:3], v[82:85]
	v_mfma_f32_16x16x32_bf16 v[78:81], v[18:21], v[4:7], v[78:81]
	v_mfma_f32_16x16x32_bf16 v[74:77], v[22:25], v[4:7], v[74:77]
	v_mfma_f32_16x16x32_bf16 v[70:73], v[26:29], v[4:7], v[70:73]
	v_mfma_f32_16x16x32_bf16 v[4:7], v[34:37], v[4:7], v[66:69]
	v_mfma_f32_16x16x32_bf16 v[62:65], v[18:21], v[8:11], v[62:65]
	v_mfma_f32_16x16x32_bf16 v[58:61], v[22:25], v[8:11], v[58:61]
	v_mfma_f32_16x16x32_bf16 v[54:57], v[26:29], v[8:11], v[54:57]
	v_mfma_f32_16x16x32_bf16 v[8:11], v[34:37], v[8:11], v[50:53]
	v_mfma_f32_16x16x32_bf16 v[46:49], v[18:21], v[14:17], v[46:49]
	v_mfma_f32_16x16x32_bf16 v[42:45], v[22:25], v[14:17], v[42:45]
	v_mfma_f32_16x16x32_bf16 v[38:41], v[26:29], v[14:17], v[38:41]
	v_mfma_f32_16x16x32_bf16 v[34:37], v[34:37], v[14:17], v[30:33]
	s_setprio 0
	ds_read_b128 v[14:17], v104 offset:64
	ds_read_b128 v[18:21], v104 offset:2624
	ds_read_b128 v[22:25], v104 offset:5184
	ds_read_b128 v[50:53], v104 offset:7744
	ds_read_b128 v[66:69], v12 offset:20544
	ds_read_b128 v[82:85], v12 offset:23104
	ds_read_b128 v[98:101], v12 offset:25664
	ds_read_b128 v[104:107], v12 offset:28224
	s_setprio 1
	s_waitcnt lgkmcnt(3)
	v_mfma_f32_16x16x32_bf16 v[94:97], v[66:69], v[14:17], v[94:97]
	s_waitcnt lgkmcnt(2)
	v_mfma_f32_16x16x32_bf16 v[90:93], v[82:85], v[14:17], v[90:93]
	s_waitcnt lgkmcnt(1)
	v_mfma_f32_16x16x32_bf16 v[86:89], v[98:101], v[14:17], v[86:89]
	s_waitcnt lgkmcnt(0)
	v_mfma_f32_16x16x32_bf16 v[108:111], v[104:107], v[14:17], v[0:3]
	v_mfma_f32_16x16x32_bf16 v[78:81], v[66:69], v[18:21], v[78:81]
	v_mfma_f32_16x16x32_bf16 v[74:77], v[82:85], v[18:21], v[74:77]
	v_mfma_f32_16x16x32_bf16 v[70:73], v[98:101], v[18:21], v[70:73]
	v_mfma_f32_16x16x32_bf16 v[112:115], v[104:107], v[18:21], v[4:7]
	v_mfma_f32_16x16x32_bf16 v[30:33], v[66:69], v[22:25], v[62:65]
	v_mfma_f32_16x16x32_bf16 v[18:21], v[82:85], v[22:25], v[58:61]
	v_mfma_f32_16x16x32_bf16 v[26:29], v[98:101], v[22:25], v[54:57]
	v_mfma_f32_16x16x32_bf16 v[22:25], v[104:107], v[22:25], v[8:11]
	v_mfma_f32_16x16x32_bf16 v[14:17], v[66:69], v[50:53], v[46:49]
	v_mfma_f32_16x16x32_bf16 v[0:3], v[82:85], v[50:53], v[42:45]
	v_mfma_f32_16x16x32_bf16 v[8:11], v[98:101], v[50:53], v[38:41]
	v_mfma_f32_16x16x32_bf16 v[4:7], v[104:107], v[50:53], v[34:37]
	s_setprio 0
	v_mul_f32_e32 v12, 0xbfb8aa3b, v94
	s_nop 0
	v_exp_f32_e32 v35, v12
	v_mul_f32_e32 v12, 0xbfb8aa3b, v86
	v_exp_f32_e32 v36, v12
	v_lshl_or_b32 v12, s12, 7, v103
	v_add_f32_e32 v35, 1.0, v35
	v_rcp_f32_e32 v38, v35
	v_add_f32_e32 v35, 1.0, v36
	v_lshl_add_u64 v[36:37], s[8:9], 0, v[12:13]
	v_mul_f32_e32 v12, 0xbfb8aa3b, v95
	v_rcp_f32_e32 v39, v35
	v_exp_f32_e32 v12, v12
	v_mul_f32_e32 v35, 0xbfb8aa3b, v87
	v_exp_f32_e32 v35, v35
	v_mov_b32_e32 v40, v94
	v_add_f32_e32 v12, 1.0, v12
	v_rcp_f32_e32 v42, v12
	v_add_f32_e32 v12, 1.0, v35
	v_rcp_f32_e32 v43, v12
	v_mul_f32_e32 v12, 0xbfb8aa3b, v96
	v_exp_f32_e32 v12, v12
	v_mul_f32_e32 v35, 0xbfb8aa3b, v88
	v_exp_f32_e32 v35, v35
	v_mov_b32_e32 v41, v86
	v_pk_mul_f32 v[38:39], v[40:41], v[38:39]
	v_mov_b32_e32 v40, v90
	v_mov_b32_e32 v41, v108
	v_mov_b32_e32 v86, v95
	v_add_f32_e32 v12, 1.0, v12
	v_pk_mul_f32 v[38:39], v[40:41], v[38:39]
	v_pk_mul_f32 v[40:41], v[86:87], v[42:43]
	v_rcp_f32_e32 v42, v12
	v_add_f32_e32 v12, 1.0, v35
	v_rcp_f32_e32 v43, v12
	v_mul_f32_e32 v12, 0xbfb8aa3b, v97
	v_exp_f32_e32 v12, v12
	v_mul_f32_e32 v35, 0xbfb8aa3b, v89
	v_exp_f32_e32 v35, v35
	v_mov_b32_e32 v108, v91
	v_add_f32_e32 v12, 1.0, v12
	v_rcp_f32_e32 v44, v12
	v_add_f32_e32 v12, 1.0, v35
	v_rcp_f32_e32 v45, v12
	v_pk_mul_f32 v[40:41], v[108:109], v[40:41]
	v_cvt_pk_bf16_f32 v38, v38, v39
	v_cvt_pk_bf16_f32 v39, v40, v41
	v_mov_b32_e32 v40, v96
	v_mov_b32_e32 v41, v88
	v_pk_mul_f32 v[40:41], v[40:41], v[42:43]
	v_mov_b32_e32 v42, v92
	v_mov_b32_e32 v43, v110
	v_mov_b32_e32 v88, v97
	v_lshl_add_u32 v34, s18, 7, v102
	v_pk_mul_f32 v[40:41], v[42:43], v[40:41]
	v_pk_mul_f32 v[42:43], v[88:89], v[44:45]
	v_mov_b32_e32 v110, v93
	v_pk_mul_f32 v[42:43], v[110:111], v[42:43]
	v_ashrrev_i32_e32 v35, 31, v34
	v_mul_f32_e32 v12, 0xbfb8aa3b, v78
	v_cvt_pk_bf16_f32 v40, v40, v41
	v_cvt_pk_bf16_f32 v41, v42, v43
	v_lshlrev_b64 v[42:43], 12, v[34:35]
	v_exp_f32_e32 v12, v12
	v_mul_f32_e32 v35, 0xbfb8aa3b, v70
	v_exp_f32_e32 v35, v35
	v_lshl_add_u64 v[42:43], v[36:37], 0, v[42:43]
; __device__ __forceinline__ float silu_(float x) { return x * __builtin_amdgcn_rcpf(1.f + __expf(-x)); }
; __device__ __forceinline__ void phase_ffn_in(const bf16_t* xb, const bf16_t* W, bf16_t* H, bf16_t* sm) {
;     ...
; #pragma unroll
;         for (int mt = 0; mt < 4; ++mt) {
;             const int row = tm * 128 + wr * 64 + mt * 16 + fr;
;             const int hc = tn * 64 + wc * 32 + fq * 8;
;             float v[16]; gather_cols<4>(acc, mt, v);
;             u32x4 o;
; #pragma unroll
;             for (int q = 0; q < 4; ++q) o[q] = pack2(silu_(v[4 * q]) * v[4 * q + 1], silu_(v[4 * q + 2]) * v[4 * q + 3]);
;             *(u32x4*)(H + (size_t)row * 2048 + hc) = o;
;         }
;     }
	v_add_f32_e32 v12, 1.0, v12
	v_rcp_f32_e32 v44, v12
	v_add_f32_e32 v12, 1.0, v35
	v_rcp_f32_e32 v45, v12
	v_mul_f32_e32 v12, 0xbfb8aa3b, v79
	v_exp_f32_e32 v12, v12
	v_mul_f32_e32 v35, 0xbfb8aa3b, v71
	v_exp_f32_e32 v35, v35
	global_store_dwordx4 v[42:43], v[38:41], off
	v_add_f32_e32 v12, 1.0, v12
	v_rcp_f32_e32 v42, v12
	v_add_f32_e32 v12, 1.0, v35
	v_rcp_f32_e32 v43, v12
	v_mul_f32_e32 v12, 0xbfb8aa3b, v80
	v_exp_f32_e32 v12, v12
	v_mul_f32_e32 v35, 0xbfb8aa3b, v72
	v_exp_f32_e32 v35, v35
	v_mov_b32_e32 v38, v78
	v_mov_b32_e32 v39, v70
	v_pk_mul_f32 v[38:39], v[38:39], v[44:45]
	v_mov_b32_e32 v40, v74
	v_mov_b32_e32 v41, v112
	v_mov_b32_e32 v70, v79
	v_add_f32_e32 v12, 1.0, v12
	v_pk_mul_f32 v[38:39], v[40:41], v[38:39]
	v_pk_mul_f32 v[40:41], v[70:71], v[42:43]
	v_rcp_f32_e32 v42, v12
	v_add_f32_e32 v12, 1.0, v35
	v_rcp_f32_e32 v43, v12
	v_mul_f32_e32 v12, 0xbfb8aa3b, v81
	v_exp_f32_e32 v12, v12
	v_mul_f32_e32 v35, 0xbfb8aa3b, v73
	v_exp_f32_e32 v35, v35
	v_mov_b32_e32 v112, v75
	v_add_f32_e32 v12, 1.0, v12
	v_rcp_f32_e32 v44, v12
	v_add_f32_e32 v12, 1.0, v35
	v_rcp_f32_e32 v45, v12
	v_pk_mul_f32 v[40:41], v[112:113], v[40:41]
	v_cvt_pk_bf16_f32 v38, v38, v39
	v_cvt_pk_bf16_f32 v39, v40, v41
	v_mov_b32_e32 v40, v80
	v_mov_b32_e32 v41, v72
	v_mul_f32_e32 v12, 0xbfb8aa3b, v30
	v_pk_mul_f32 v[40:41], v[40:41], v[42:43]
	v_mov_b32_e32 v42, v76
	v_mov_b32_e32 v43, v114
	v_mov_b32_e32 v72, v81
	v_exp_f32_e32 v12, v12
	v_mul_f32_e32 v35, 0xbfb8aa3b, v26
	v_pk_mul_f32 v[40:41], v[42:43], v[40:41]
	v_pk_mul_f32 v[42:43], v[72:73], v[44:45]
	v_mov_b32_e32 v114, v77
	v_exp_f32_e32 v35, v35
	v_pk_mul_f32 v[42:43], v[114:115], v[42:43]
	v_cvt_pk_bf16_f32 v40, v40, v41
	v_cvt_pk_bf16_f32 v41, v42, v43
	v_or_b32_e32 v42, 16, v34
	v_ashrrev_i32_e32 v43, 31, v42
	v_add_f32_e32 v12, 1.0, v12
	v_lshlrev_b64 v[42:43], 12, v[42:43]
	v_rcp_f32_e32 v44, v12
	v_add_f32_e32 v12, 1.0, v35
	v_lshl_add_u64 v[42:43], v[36:37], 0, v[42:43]
	v_rcp_f32_e32 v45, v12
	v_mul_f32_e32 v12, 0xbfb8aa3b, v31
	global_store_dwordx4 v[42:43], v[38:41], off
	v_exp_f32_e32 v12, v12
	s_add_i32 s11, s11, s62
	v_mov_b32_e32 v40, v18
	v_mul_f32_e32 v18, 0xbfb8aa3b, v27
	v_exp_f32_e32 v18, v18
	v_add_f32_e32 v12, 1.0, v12
	v_rcp_f32_e32 v42, v12
	v_mov_b32_e32 v41, v22
	v_add_f32_e32 v12, 1.0, v18
	v_rcp_f32_e32 v43, v12
	v_mul_f32_e32 v12, 0xbfb8aa3b, v32
	v_mov_b32_e32 v22, v19
	v_exp_f32_e32 v12, v12
	v_mul_f32_e32 v19, 0xbfb8aa3b, v28
	v_exp_f32_e32 v19, v19
	v_mov_b32_e32 v39, v26
	v_mov_b32_e32 v26, v31
	v_pk_mul_f32 v[26:27], v[26:27], v[42:43]
	v_add_f32_e32 v12, 1.0, v12
	v_pk_mul_f32 v[22:23], v[22:23], v[26:27]
	v_rcp_f32_e32 v26, v12
	v_add_f32_e32 v12, 1.0, v19
	v_rcp_f32_e32 v27, v12
	v_cvt_pk_bf16_f32 v19, v22, v23
	v_mov_b32_e32 v22, v32
	v_mov_b32_e32 v23, v28
	v_mul_f32_e32 v12, 0xbfb8aa3b, v33
	v_pk_mul_f32 v[22:23], v[22:23], v[26:27]
	v_mov_b32_e32 v26, v20
	v_exp_f32_e32 v12, v12
	v_mul_f32_e32 v20, 0xbfb8aa3b, v29
	v_exp_f32_e32 v20, v20
	v_mov_b32_e32 v38, v30
	v_add_f32_e32 v12, 1.0, v12
	v_rcp_f32_e32 v30, v12
	v_add_f32_e32 v12, 1.0, v20
	v_rcp_f32_e32 v31, v12
	v_mov_b32_e32 v27, v24
	v_pk_mul_f32 v[22:23], v[26:27], v[22:23]
	v_mov_b32_e32 v28, v33
	v_cvt_pk_bf16_f32 v20, v22, v23
	v_pk_mul_f32 v[22:23], v[28:29], v[30:31]
	v_mov_b32_e32 v24, v21
	v_pk_mul_f32 v[22:23], v[24:25], v[22:23]
	v_pk_mul_f32 v[38:39], v[38:39], v[44:45]
	v_cvt_pk_bf16_f32 v21, v22, v23
	v_or_b32_e32 v22, 32, v34
	v_ashrrev_i32_e32 v23, 31, v22
	v_pk_mul_f32 v[38:39], v[40:41], v[38:39]
	v_lshlrev_b64 v[22:23], 12, v[22:23]
	v_cvt_pk_bf16_f32 v18, v38, v39
	v_lshl_add_u64 v[22:23], v[36:37], 0, v[22:23]
	v_mul_f32_e32 v12, 0xbfb8aa3b, v14
	global_store_dwordx4 v[22:23], v[18:21], off
	v_exp_f32_e32 v12, v12
	v_mul_f32_e32 v24, 0xbfb8aa3b, v8
	v_mov_b32_e32 v20, v0
	v_mul_f32_e32 v0, 0xbfb8aa3b, v15
	v_mov_b32_e32 v19, v8
	v_exp_f32_e32 v0, v0
	v_mul_f32_e32 v8, 0xbfb8aa3b, v9
	v_exp_f32_e32 v25, v24
	v_exp_f32_e32 v8, v8
	v_add_f32_e32 v12, 1.0, v12
	v_add_f32_e32 v0, 1.0, v0
	v_rcp_f32_e32 v24, v12
	v_add_f32_e32 v12, 1.0, v25
	v_mov_b32_e32 v21, v4
	v_rcp_f32_e32 v22, v0
	v_add_f32_e32 v0, 1.0, v8
	v_mov_b32_e32 v4, v1
	v_mul_f32_e32 v1, 0xbfb8aa3b, v16
	v_rcp_f32_e32 v25, v12
	v_rcp_f32_e32 v23, v0
	v_exp_f32_e32 v1, v1
	v_mul_f32_e32 v12, 0xbfb8aa3b, v10
	v_exp_f32_e32 v12, v12
	v_mov_b32_e32 v8, v15
	v_pk_mul_f32 v[8:9], v[8:9], v[22:23]
	v_add_f32_e32 v1, 1.0, v1
	v_pk_mul_f32 v[4:5], v[4:5], v[8:9]
	v_rcp_f32_e32 v8, v1
	v_add_f32_e32 v1, 1.0, v12
	v_rcp_f32_e32 v9, v1
	v_cvt_pk_bf16_f32 v1, v4, v5
	v_mov_b32_e32 v4, v16
	v_mov_b32_e32 v5, v10
	v_pk_mul_f32 v[4:5], v[4:5], v[8:9]
	v_mov_b32_e32 v8, v2
	v_mul_f32_e32 v2, 0xbfb8aa3b, v17
	v_exp_f32_e32 v2, v2
	v_mul_f32_e32 v9, 0xbfb8aa3b, v11
	v_exp_f32_e32 v10, v9
	v_mov_b32_e32 v18, v14
	v_add_f32_e32 v2, 1.0, v2
	v_rcp_f32_e32 v14, v2
	v_add_f32_e32 v2, 1.0, v10
	v_rcp_f32_e32 v15, v2
	v_mov_b32_e32 v9, v6
	v_pk_mul_f32 v[4:5], v[8:9], v[4:5]
	v_mov_b32_e32 v10, v17
	v_cvt_pk_bf16_f32 v2, v4, v5
	v_pk_mul_f32 v[4:5], v[10:11], v[14:15]
	v_mov_b32_e32 v6, v3
	v_pk_mul_f32 v[4:5], v[6:7], v[4:5]
	v_pk_mul_f32 v[18:19], v[18:19], v[24:25]
	v_cvt_pk_bf16_f32 v3, v4, v5
	v_or_b32_e32 v4, 48, v34
	v_ashrrev_i32_e32 v5, 31, v4
	v_pk_mul_f32 v[18:19], v[20:21], v[18:19]
	v_lshlrev_b64 v[4:5], 12, v[4:5]
	s_add_i32 s10, s10, s62
	v_cvt_pk_bf16_f32 v0, v18, v19
	v_lshl_add_u64 v[4:5], v[36:37], 0, v[4:5]
	s_cmpk_lt_i32 s11, 0x1100
	global_store_dwordx4 v[4:5], v[0:3], off
	s_cbranch_scc1 .LBB0_1479
